# one s_nop in front of each MFMA run of 8 or more that sat at 4 mod 8 bytes (24 pads)
# baseline (speedup 1.0000x reference)
.LBB0_104:
	s_add_u32 s2, s34, 0xfffc2080
	s_addc_u32 s3, s35, -1
	s_add_i32 s12, 0, 0x10000
	v_add_u32_e32 v110, s12, v179
	ds_read_b128 v[98:101], v110
	ds_read_b128 v[102:105], v110 offset:1024
	ds_read_b128 v[106:109], v110 offset:2048
	ds_read_b128 v[110:113], v110 offset:3072
	s_cmp_eq_u32 s53, 12
	s_cselect_b32 s49, s97, s3
	s_cselect_b32 s48, s96, s2
	s_cselect_b32 s3, s1, s52
	s_cselect_b32 s2, s23, s51
	v_lshl_add_u64 v[174:175], s[34:35], 0, v[170:171]
	s_add_i32 m0, s85, 0xc000
	ds_read_b128 v[114:117], v184
	ds_read_b128 v[118:121], v184 offset:1024
	ds_read_b128 v[122:125], v184 offset:2048
	ds_read_b128 v[126:129], v184 offset:3072
	ds_read_b128 v[186:189], v184 offset:4096
	ds_read_b128 v[190:193], v184 offset:5120
	ds_read_b128 v[194:197], v184 offset:6144
	ds_read_b128 v[198:201], v184 offset:7168
	global_load_lds_dwordx4 v[174:175], off
	v_lshl_add_u64 v[174:175], s[34:35], 0, v[172:173]
	s_add_i32 m0, s85, 0xe000
	s_nop 0
	global_load_lds_dwordx4 v[174:175], off
	s_waitcnt lgkmcnt(8)
	s_add_i32 s54, 0, 0x14000
	v_add_u32_e32 v174, s54, v179
	s_add_i32 s12, s12, s78
	ds_read_b128 v[226:229], v174
	ds_read_b128 v[230:233], v174 offset:1024
	ds_read_b128 v[234:237], v174 offset:2048
	ds_read_b128 v[242:245], v174 offset:3072
	s_barrier
	s_waitcnt lgkmcnt(0)
	s_waitcnt lgkmcnt(0)
	s_nop 0
	v_mfma_f32_16x16x32_bf16 v[158:161], v[98:101], v[114:117], v[158:161]
	v_mfma_f32_16x16x32_bf16 v[154:157], v[106:109], v[114:117], v[154:157]
	v_mfma_f32_16x16x32_bf16 v[150:153], v[98:101], v[122:125], v[150:153]
	v_mfma_f32_16x16x32_bf16 v[146:149], v[106:109], v[122:125], v[146:149]
	v_mfma_f32_16x16x32_bf16 v[142:145], v[98:101], v[186:189], v[142:145]
	v_mfma_f32_16x16x32_bf16 v[138:141], v[106:109], v[186:189], v[138:141]
	v_mfma_f32_16x16x32_bf16 v[134:137], v[98:101], v[194:197], v[134:137]
	v_mfma_f32_16x16x32_bf16 v[130:133], v[106:109], v[194:197], v[130:133]
	v_mfma_f32_16x16x32_bf16 v[158:161], v[102:105], v[118:121], v[158:161]
	v_mfma_f32_16x16x32_bf16 v[154:157], v[110:113], v[118:121], v[154:157]
	v_mfma_f32_16x16x32_bf16 v[150:153], v[102:105], v[126:129], v[150:153]
	v_mfma_f32_16x16x32_bf16 v[146:149], v[110:113], v[126:129], v[146:149]
	v_mfma_f32_16x16x32_bf16 v[142:145], v[102:105], v[190:193], v[142:145]
	v_mfma_f32_16x16x32_bf16 v[138:141], v[110:113], v[190:193], v[138:141]
	v_mfma_f32_16x16x32_bf16 v[134:137], v[102:105], v[198:201], v[134:137]
	v_mfma_f32_16x16x32_bf16 v[130:133], v[110:113], v[198:201], v[130:133]
	s_waitcnt lgkmcnt(0)
	s_waitcnt lgkmcnt(0)
	v_mfma_f32_16x16x32_bf16 v[62:65], v[226:229], v[114:117], v[62:65]
	v_mfma_f32_16x16x32_bf16 v[58:61], v[234:237], v[114:117], v[58:61]
	v_mfma_f32_16x16x32_bf16 v[54:57], v[226:229], v[122:125], v[54:57]
	v_mfma_f32_16x16x32_bf16 v[50:53], v[234:237], v[122:125], v[50:53]
	v_mfma_f32_16x16x32_bf16 v[46:49], v[226:229], v[186:189], v[46:49]
	v_mfma_f32_16x16x32_bf16 v[42:45], v[234:237], v[186:189], v[42:45]
	v_mfma_f32_16x16x32_bf16 v[38:41], v[226:229], v[194:197], v[38:41]
	v_mfma_f32_16x16x32_bf16 v[34:37], v[234:237], v[194:197], v[34:37]
	v_mfma_f32_16x16x32_bf16 v[62:65], v[230:233], v[118:121], v[62:65]
	v_mfma_f32_16x16x32_bf16 v[58:61], v[242:245], v[118:121], v[58:61]
	v_mfma_f32_16x16x32_bf16 v[54:57], v[230:233], v[126:129], v[54:57]
	v_mfma_f32_16x16x32_bf16 v[50:53], v[242:245], v[126:129], v[50:53]
	v_mfma_f32_16x16x32_bf16 v[46:49], v[230:233], v[190:193], v[46:49]
	v_mfma_f32_16x16x32_bf16 v[42:45], v[242:245], v[190:193], v[42:45]
	v_mfma_f32_16x16x32_bf16 v[38:41], v[230:233], v[198:201], v[38:41]
	v_mfma_f32_16x16x32_bf16 v[34:37], v[242:245], v[198:201], v[34:37]
	s_mov_b32 m0, s85
	v_lshl_add_u64 v[248:249], s[48:49], 0, v[162:163]
	s_barrier
	ds_read_b128 v[114:117], v184 offset:16384
	ds_read_b128 v[118:121], v184 offset:17408
	ds_read_b128 v[122:125], v184 offset:18432
	ds_read_b128 v[126:129], v184 offset:19456
	ds_read_b128 v[186:189], v184 offset:20480
	ds_read_b128 v[190:193], v184 offset:21504
	ds_read_b128 v[194:197], v184 offset:22528
	ds_read_b128 v[198:201], v184 offset:23552
	global_load_lds_dwordx4 v[248:249], off
	v_lshl_add_u64 v[250:251], s[48:49], 0, v[164:165]
	s_mov_b32 m0, s82
	s_nop 0
	global_load_lds_dwordx4 v[250:251], off
	v_lshl_add_u64 v[174:175], s[2:3], 0, v[0:1]
	s_mov_b32 m0, s12
	v_lshl_add_u64 v[246:247], s[2:3], 0, v[166:167]
	global_load_lds_dwordx4 v[174:175], off
	s_add_i32 m0, s12, 0x2000
	s_nop 0
	global_load_lds_dwordx4 v[246:247], off
	s_add_u32 s12, s2, 0x40000
	s_addc_u32 s13, s3, 0
	s_add_i32 s54, s54, s78
	v_lshl_add_u64 v[174:175], s[12:13], 0, v[0:1]
	s_mov_b32 m0, s54
	s_nop 0
	global_load_lds_dwordx4 v[174:175], off
	v_lshl_add_u64 v[174:175], s[12:13], 0, v[166:167]
	s_add_i32 m0, s54, 0x2000
	s_nop 0
	global_load_lds_dwordx4 v[174:175], off
	s_waitcnt vmcnt(6)
	s_barrier
	s_waitcnt lgkmcnt(0)
	s_waitcnt lgkmcnt(0)
	s_nop 0
	v_mfma_f32_16x16x32_bf16 v[94:97], v[98:101], v[114:117], v[94:97]
	v_mfma_f32_16x16x32_bf16 v[90:93], v[106:109], v[114:117], v[90:93]
	v_mfma_f32_16x16x32_bf16 v[86:89], v[98:101], v[122:125], v[86:89]
	v_mfma_f32_16x16x32_bf16 v[82:85], v[106:109], v[122:125], v[82:85]
	v_mfma_f32_16x16x32_bf16 v[78:81], v[98:101], v[186:189], v[78:81]
	v_mfma_f32_16x16x32_bf16 v[74:77], v[106:109], v[186:189], v[74:77]
	v_mfma_f32_16x16x32_bf16 v[70:73], v[98:101], v[194:197], v[70:73]
	v_mfma_f32_16x16x32_bf16 v[66:69], v[106:109], v[194:197], v[66:69]
	v_mfma_f32_16x16x32_bf16 v[94:97], v[102:105], v[118:121], v[94:97]
	v_mfma_f32_16x16x32_bf16 v[90:93], v[110:113], v[118:121], v[90:93]
	v_mfma_f32_16x16x32_bf16 v[86:89], v[102:105], v[126:129], v[86:89]
	v_mfma_f32_16x16x32_bf16 v[82:85], v[110:113], v[126:129], v[82:85]
	v_mfma_f32_16x16x32_bf16 v[78:81], v[102:105], v[190:193], v[78:81]
	v_mfma_f32_16x16x32_bf16 v[74:77], v[110:113], v[190:193], v[74:77]
	v_mfma_f32_16x16x32_bf16 v[70:73], v[102:105], v[198:201], v[70:73]
	v_mfma_f32_16x16x32_bf16 v[66:69], v[110:113], v[198:201], v[66:69]
	v_mfma_f32_16x16x32_bf16 v[30:33], v[226:229], v[114:117], v[30:33]
	v_mfma_f32_16x16x32_bf16 v[26:29], v[234:237], v[114:117], v[26:29]
	v_mfma_f32_16x16x32_bf16 v[22:25], v[226:229], v[122:125], v[22:25]
	v_mfma_f32_16x16x32_bf16 v[18:21], v[234:237], v[122:125], v[18:21]
	v_mfma_f32_16x16x32_bf16 v[14:17], v[226:229], v[186:189], v[14:17]
	v_mfma_f32_16x16x32_bf16 v[10:13], v[234:237], v[186:189], v[10:13]
	v_mfma_f32_16x16x32_bf16 v[6:9], v[226:229], v[194:197], v[6:9]
	v_mfma_f32_16x16x32_bf16 v[2:5], v[234:237], v[194:197], v[2:5]
	v_mfma_f32_16x16x32_bf16 v[30:33], v[230:233], v[118:121], v[30:33]
	v_mfma_f32_16x16x32_bf16 v[26:29], v[242:245], v[118:121], v[26:29]
	v_mfma_f32_16x16x32_bf16 v[22:25], v[230:233], v[126:129], v[22:25]
	v_mfma_f32_16x16x32_bf16 v[18:21], v[242:245], v[126:129], v[18:21]
	v_mfma_f32_16x16x32_bf16 v[14:17], v[230:233], v[190:193], v[14:17]
	v_mfma_f32_16x16x32_bf16 v[10:13], v[242:245], v[190:193], v[10:13]
	v_mfma_f32_16x16x32_bf16 v[6:9], v[230:233], v[198:201], v[6:9]
	v_mfma_f32_16x16x32_bf16 v[2:5], v[242:245], v[198:201], v[2:5]
	s_add_i32 s54, 0, 0x18000
	v_add_u32_e32 v110, s54, v179
	s_barrier
	ds_read_b128 v[98:101], v110
	ds_read_b128 v[102:105], v110 offset:1024
	ds_read_b128 v[106:109], v110 offset:2048
	ds_read_b128 v[110:113], v110 offset:3072
	s_add_u32 s12, s48, 0x3e000
	s_addc_u32 s13, s49, 0
	s_mov_b32 m0, s89
	v_lshl_add_u64 v[226:227], s[12:13], 0, v[162:163]
	ds_read_b128 v[114:117], v184 offset:32768
	ds_read_b128 v[118:121], v184 offset:33792
	ds_read_b128 v[122:125], v184 offset:34816
	ds_read_b128 v[126:129], v184 offset:35840
	ds_read_b128 v[186:189], v184 offset:36864
	ds_read_b128 v[190:193], v184 offset:37888
	ds_read_b128 v[194:197], v184 offset:38912
	ds_read_b128 v[198:201], v184 offset:39936
	global_load_lds_dwordx4 v[226:227], off
	v_lshl_add_u64 v[226:227], s[12:13], 0, v[164:165]
	s_mov_b32 m0, s91
	s_nop 0
	global_load_lds_dwordx4 v[226:227], off
	s_waitcnt lgkmcnt(8)
	s_add_i32 s12, 0, 0x1c000
	s_add_i32 s13, s54, s78
	v_add_u32_e32 v242, s12, v179
	ds_read_b128 v[226:229], v242
	ds_read_b128 v[230:233], v242 offset:1024
	ds_read_b128 v[234:237], v242 offset:2048
	ds_read_b128 v[242:245], v242 offset:3072
	s_barrier
	s_waitcnt lgkmcnt(0)
	s_waitcnt lgkmcnt(0)
	v_mfma_f32_16x16x32_bf16 v[158:161], v[98:101], v[114:117], v[158:161]
	v_mfma_f32_16x16x32_bf16 v[154:157], v[106:109], v[114:117], v[154:157]
	v_mfma_f32_16x16x32_bf16 v[150:153], v[98:101], v[122:125], v[150:153]
	v_mfma_f32_16x16x32_bf16 v[146:149], v[106:109], v[122:125], v[146:149]
	v_mfma_f32_16x16x32_bf16 v[142:145], v[98:101], v[186:189], v[142:145]
	v_mfma_f32_16x16x32_bf16 v[138:141], v[106:109], v[186:189], v[138:141]
	v_mfma_f32_16x16x32_bf16 v[134:137], v[98:101], v[194:197], v[134:137]
	v_mfma_f32_16x16x32_bf16 v[130:133], v[106:109], v[194:197], v[130:133]
	v_mfma_f32_16x16x32_bf16 v[158:161], v[102:105], v[118:121], v[158:161]
	v_mfma_f32_16x16x32_bf16 v[154:157], v[110:113], v[118:121], v[154:157]
	v_mfma_f32_16x16x32_bf16 v[150:153], v[102:105], v[126:129], v[150:153]
	v_mfma_f32_16x16x32_bf16 v[146:149], v[110:113], v[126:129], v[146:149]
	v_mfma_f32_16x16x32_bf16 v[142:145], v[102:105], v[190:193], v[142:145]
	v_mfma_f32_16x16x32_bf16 v[138:141], v[110:113], v[190:193], v[138:141]
	v_mfma_f32_16x16x32_bf16 v[134:137], v[102:105], v[198:201], v[134:137]
	v_mfma_f32_16x16x32_bf16 v[130:133], v[110:113], v[198:201], v[130:133]
	s_waitcnt lgkmcnt(0)
	s_waitcnt lgkmcnt(0)
	v_mfma_f32_16x16x32_bf16 v[62:65], v[226:229], v[114:117], v[62:65]
	v_mfma_f32_16x16x32_bf16 v[58:61], v[234:237], v[114:117], v[58:61]
	v_mfma_f32_16x16x32_bf16 v[54:57], v[226:229], v[122:125], v[54:57]
	v_mfma_f32_16x16x32_bf16 v[50:53], v[234:237], v[122:125], v[50:53]
	v_mfma_f32_16x16x32_bf16 v[46:49], v[226:229], v[186:189], v[46:49]
	v_mfma_f32_16x16x32_bf16 v[42:45], v[234:237], v[186:189], v[42:45]
	v_mfma_f32_16x16x32_bf16 v[38:41], v[226:229], v[194:197], v[38:41]
	v_mfma_f32_16x16x32_bf16 v[34:37], v[234:237], v[194:197], v[34:37]
	v_mfma_f32_16x16x32_bf16 v[62:65], v[230:233], v[118:121], v[62:65]
	v_mfma_f32_16x16x32_bf16 v[58:61], v[242:245], v[118:121], v[58:61]
	v_mfma_f32_16x16x32_bf16 v[54:57], v[230:233], v[126:129], v[54:57]
	v_mfma_f32_16x16x32_bf16 v[50:53], v[242:245], v[126:129], v[50:53]
	v_mfma_f32_16x16x32_bf16 v[46:49], v[230:233], v[190:193], v[46:49]
	v_mfma_f32_16x16x32_bf16 v[42:45], v[242:245], v[190:193], v[42:45]
	v_mfma_f32_16x16x32_bf16 v[38:41], v[230:233], v[198:201], v[38:41]
	v_mfma_f32_16x16x32_bf16 v[34:37], v[242:245], v[198:201], v[34:37]
	s_mov_b32 m0, s79
	v_lshl_add_u64 v[174:175], v[248:249], 0, s[20:21]
	s_barrier
	ds_read_b128 v[114:117], v184 offset:49152
	ds_read_b128 v[118:121], v184 offset:50176
	ds_read_b128 v[122:125], v184 offset:51200
	ds_read_b128 v[126:129], v184 offset:52224
	ds_read_b128 v[186:189], v184 offset:53248
	ds_read_b128 v[190:193], v184 offset:54272
	ds_read_b128 v[194:197], v184 offset:55296
	ds_read_b128 v[198:201], v184 offset:56320
	global_load_lds_dwordx4 v[174:175], off
	v_lshl_add_u64 v[174:175], v[250:251], 0, s[20:21]
	s_mov_b32 m0, s87
	s_nop 0
	global_load_lds_dwordx4 v[174:175], off
	v_lshl_add_u64 v[174:175], s[2:3], 0, v[0:1]
	v_lshl_add_u64 v[174:175], v[174:175], 0, s[20:21]
	s_mov_b32 m0, s13
	s_nop 0
	global_load_lds_dwordx4 v[174:175], off
	v_lshl_add_u64 v[174:175], v[246:247], 0, s[20:21]
	s_add_i32 m0, s13, 0x2000
	s_nop 0
	global_load_lds_dwordx4 v[174:175], off
	s_add_u32 s2, s2, 0x40080
	s_addc_u32 s3, s3, 0
	s_add_i32 s12, s12, s78
	v_lshl_add_u64 v[174:175], s[2:3], 0, v[0:1]
	s_mov_b32 m0, s12
	s_nop 0
	global_load_lds_dwordx4 v[174:175], off
	v_lshl_add_u64 v[174:175], s[2:3], 0, v[166:167]
	s_add_i32 m0, s12, 0x2000
	s_nop 0
	global_load_lds_dwordx4 v[174:175], off
	s_waitcnt vmcnt(6)
	s_barrier
	s_waitcnt lgkmcnt(0)
	s_waitcnt lgkmcnt(0)
	v_mfma_f32_16x16x32_bf16 v[94:97], v[98:101], v[114:117], v[94:97]
	v_mfma_f32_16x16x32_bf16 v[90:93], v[106:109], v[114:117], v[90:93]
	v_mfma_f32_16x16x32_bf16 v[86:89], v[98:101], v[122:125], v[86:89]
	v_mfma_f32_16x16x32_bf16 v[82:85], v[106:109], v[122:125], v[82:85]
	v_mfma_f32_16x16x32_bf16 v[78:81], v[98:101], v[186:189], v[78:81]
	v_mfma_f32_16x16x32_bf16 v[74:77], v[106:109], v[186:189], v[74:77]
	v_mfma_f32_16x16x32_bf16 v[70:73], v[98:101], v[194:197], v[70:73]
	v_mfma_f32_16x16x32_bf16 v[66:69], v[106:109], v[194:197], v[66:69]
	v_mfma_f32_16x16x32_bf16 v[94:97], v[102:105], v[118:121], v[94:97]
	v_mfma_f32_16x16x32_bf16 v[90:93], v[110:113], v[118:121], v[90:93]
	v_mfma_f32_16x16x32_bf16 v[86:89], v[102:105], v[126:129], v[86:89]
	v_mfma_f32_16x16x32_bf16 v[82:85], v[110:113], v[126:129], v[82:85]
	v_mfma_f32_16x16x32_bf16 v[78:81], v[102:105], v[190:193], v[78:81]
	v_mfma_f32_16x16x32_bf16 v[74:77], v[110:113], v[190:193], v[74:77]
	v_mfma_f32_16x16x32_bf16 v[70:73], v[102:105], v[198:201], v[70:73]
	v_mfma_f32_16x16x32_bf16 v[66:69], v[110:113], v[198:201], v[66:69]
	v_mfma_f32_16x16x32_bf16 v[30:33], v[226:229], v[114:117], v[30:33]
	v_mfma_f32_16x16x32_bf16 v[26:29], v[234:237], v[114:117], v[26:29]
	v_mfma_f32_16x16x32_bf16 v[22:25], v[226:229], v[122:125], v[22:25]
	v_mfma_f32_16x16x32_bf16 v[18:21], v[234:237], v[122:125], v[18:21]
	v_mfma_f32_16x16x32_bf16 v[14:17], v[226:229], v[186:189], v[14:17]
	v_mfma_f32_16x16x32_bf16 v[10:13], v[234:237], v[186:189], v[10:13]
	v_mfma_f32_16x16x32_bf16 v[6:9], v[226:229], v[194:197], v[6:9]
	v_mfma_f32_16x16x32_bf16 v[2:5], v[234:237], v[194:197], v[2:5]
	v_mfma_f32_16x16x32_bf16 v[30:33], v[230:233], v[118:121], v[30:33]
	v_mfma_f32_16x16x32_bf16 v[26:29], v[242:245], v[118:121], v[26:29]
	v_mfma_f32_16x16x32_bf16 v[22:25], v[230:233], v[126:129], v[22:25]
	v_mfma_f32_16x16x32_bf16 v[18:21], v[242:245], v[126:129], v[18:21]
	v_mfma_f32_16x16x32_bf16 v[14:17], v[230:233], v[190:193], v[14:17]
	v_mfma_f32_16x16x32_bf16 v[10:13], v[242:245], v[190:193], v[10:13]
	v_mfma_f32_16x16x32_bf16 v[6:9], v[230:233], v[198:201], v[6:9]
	v_mfma_f32_16x16x32_bf16 v[2:5], v[242:245], v[198:201], v[2:5]
	s_add_i32 s53, s53, 2
	s_add_u32 s34, s34, 0x100
	s_addc_u32 s35, s35, 0
	s_add_u32 s51, s51, 0x100
	s_addc_u32 s52, s52, 0
	s_cmp_gt_u32 s53, 13
	s_barrier
	s_cbranch_scc0 .LBB0_104
	s_add_i32 s1, s50, 0xffffffbd
	s_cmpk_gt_i32 s50, 0x42
	s_cselect_b32 s1, s1, s50
	s_mul_i32 s23, s1, 0xf8
	s_cselect_b32 s2, 0x4000, 0
	s_cselect_b32 s3, 0x100, s37
	s_add_i32 s23, s23, s84
	v_add_u32_e32 v188, s88, v178
	s_mov_b32 s50, 0xbfb8aa3b
	s_mov_b32 s51, 0xbfb8aa3b
	ds_read_b128 v[126:129], v188
	ds_read_b128 v[122:125], v188 offset:128
	ds_read_b128 v[114:117], v188 offset:256
	ds_read_b128 v[118:121], v188 offset:384
	ds_read_b128 v[110:113], v188 offset:512
	ds_read_b128 v[106:109], v188 offset:640
	ds_read_b128 v[98:101], v188 offset:768
	ds_read_b128 v[102:105], v188 offset:896
	v_readlane_b32 s12, v252, 28
	v_readlane_b32 s13, v252, 29
	v_bfe_u32 v231, v202, 5, 1
	v_and_b32_e32 v174, 48, v180
	v_lshl_or_b32 v174, v231, 3, v174
	v_lshl_or_b32 v174, s0, 7, v174
	v_bfe_u32 v230, v202, 4, 1
	v_lshl_add_u32 v186, v177, 2, s23
	v_cmp_eq_u32_e32 vcc, 1, v230
	s_or_b64 s[52:53], s[42:43], vcc
	v_cmp_eq_u32_e32 vcc, 0, v230
	s_or_b64 s[54:55], s[44:45], vcc
	v_add_u32_e32 v186, v186, v230
	v_add_u32_e32 v187, s2, v186
	v_mul_u32_u24_e32 v187, 0x1600, v187
	v_lshl_add_u32 v187, v174, 1, v187
	s_waitcnt lgkmcnt(0)
	v_pk_fma_f32 v[190:191], v[158:159], v[122:123], v[118:119]
	v_pk_fma_f32 v[192:193], v[160:161], v[124:125], v[120:121]
	v_pk_fma_f32 v[194:195], v[154:155], v[106:107], v[102:103]
	v_pk_fma_f32 v[196:197], v[156:157], v[108:109], v[104:105]
	v_add_u32_e32 v230, 0, v186
	v_fmac_f32_dpp v190, v134, v126 row_ror:1 row_mask:0xf bank_mask:0xf
	v_fmac_f32_dpp v191, v135, v127 row_ror:1 row_mask:0xf bank_mask:0xf
	v_fmac_f32_dpp v192, v136, v128 row_ror:1 row_mask:0xf bank_mask:0xf
	v_fmac_f32_dpp v193, v137, v129 row_ror:1 row_mask:0xf bank_mask:0xf
	v_fmac_f32_dpp v194, v130, v110 row_ror:1 row_mask:0xf bank_mask:0xf
	v_fmac_f32_dpp v195, v131, v111 row_ror:1 row_mask:0xf bank_mask:0xf
	v_fmac_f32_dpp v196, v132, v112 row_ror:1 row_mask:0xf bank_mask:0xf
	v_fmac_f32_dpp v197, v133, v113 row_ror:1 row_mask:0xf bank_mask:0xf
	v_pk_fma_f32 v[190:191], v[150:151], v[114:115], v[190:191]
	v_pk_fma_f32 v[192:193], v[152:153], v[116:117], v[192:193]
	v_pk_fma_f32 v[194:195], v[146:147], v[98:99], v[194:195]
	v_pk_fma_f32 v[196:197], v[148:149], v[100:101], v[196:197]
	v_pk_mul_f32 v[198:199], v[190:191], s[50:51]
	v_pk_mul_f32 v[200:201], v[192:193], s[50:51]
	v_exp_f32_e32 v198, v198
	v_exp_f32_e32 v199, v199
	v_exp_f32_e32 v200, v200
	v_exp_f32_e32 v201, v201
	v_add_f32_e32 v198, 1.0, v198
	v_add_f32_e32 v199, 1.0, v199
	v_add_f32_e32 v200, 1.0, v200
	v_add_f32_e32 v201, 1.0, v201
	v_rcp_f32_e32 v198, v198
	v_rcp_f32_e32 v199, v199
	v_rcp_f32_e32 v200, v200
	v_rcp_f32_e32 v201, v201
	v_pk_mul_f32 v[190:191], v[190:191], v[198:199]
	v_pk_mul_f32 v[192:193], v[192:193], v[200:201]
	v_pk_mul_f32 v[190:191], v[190:191], v[194:195]
	v_pk_mul_f32 v[192:193], v[192:193], v[196:197]
	v_cvt_pk_bf16_f32 v232, v190, v191
	v_cvt_pk_bf16_f32 v233, v192, v193
	v_pk_fma_f32 v[190:191], v[150:151], v[122:123], v[118:119]
	v_pk_fma_f32 v[192:193], v[152:153], v[124:125], v[120:121]
	v_pk_fma_f32 v[194:195], v[146:147], v[106:107], v[102:103]
	v_pk_fma_f32 v[196:197], v[148:149], v[108:109], v[104:105]
	v_pk_fma_f32 v[190:191], v[158:159], v[126:127], v[190:191]
	v_pk_fma_f32 v[192:193], v[160:161], v[128:129], v[192:193]
	v_pk_fma_f32 v[194:195], v[154:155], v[110:111], v[194:195]
	v_pk_fma_f32 v[196:197], v[156:157], v[112:113], v[196:197]
	v_pk_fma_f32 v[190:191], v[142:143], v[114:115], v[190:191]
	v_pk_fma_f32 v[192:193], v[144:145], v[116:117], v[192:193]
	v_pk_fma_f32 v[194:195], v[138:139], v[98:99], v[194:195]
	v_pk_fma_f32 v[196:197], v[140:141], v[100:101], v[196:197]
	v_pk_mul_f32 v[198:199], v[190:191], s[50:51]
	v_pk_mul_f32 v[200:201], v[192:193], s[50:51]
	v_exp_f32_e32 v198, v198
	v_exp_f32_e32 v199, v199
	v_exp_f32_e32 v200, v200
	v_exp_f32_e32 v201, v201
	v_add_f32_e32 v198, 1.0, v198
	v_add_f32_e32 v199, 1.0, v199
	v_add_f32_e32 v200, 1.0, v200
	v_add_f32_e32 v201, 1.0, v201
	v_rcp_f32_e32 v198, v198
	v_rcp_f32_e32 v199, v199
	v_rcp_f32_e32 v200, v200
	v_rcp_f32_e32 v201, v201
	v_pk_mul_f32 v[190:191], v[190:191], v[198:199]
	v_pk_mul_f32 v[192:193], v[192:193], v[200:201]
	v_pk_mul_f32 v[190:191], v[190:191], v[194:195]
	v_pk_mul_f32 v[192:193], v[192:193], v[196:197]
	v_cvt_pk_bf16_f32 v234, v190, v191
	v_cvt_pk_bf16_f32 v235, v192, v193
	v_cmp_gt_i32_e32 vcc, s3, v230
	s_and_b64 vcc, vcc, s[52:53]
	s_nop 0
	v_permlane16_swap_b32_e32 v232, v234
	v_permlane16_swap_b32_e32 v233, v235
	s_and_saveexec_b64 s[0:1], vcc
	global_store_dwordx4 v187, v[232:235], s[12:13]
	s_mov_b64 exec, s[0:1]
	v_pk_fma_f32 v[190:191], v[142:143], v[122:123], v[118:119]
	v_pk_fma_f32 v[192:193], v[144:145], v[124:125], v[120:121]
	v_pk_fma_f32 v[194:195], v[138:139], v[106:107], v[102:103]
	v_pk_fma_f32 v[196:197], v[140:141], v[108:109], v[104:105]
	v_add_u32_e32 v230, 2, v186
	v_add_u32_e32 v231, 0x2c00, v187
	v_pk_fma_f32 v[190:191], v[150:151], v[126:127], v[190:191]
	v_pk_fma_f32 v[192:193], v[152:153], v[128:129], v[192:193]
	v_pk_fma_f32 v[194:195], v[146:147], v[110:111], v[194:195]
	v_pk_fma_f32 v[196:197], v[148:149], v[112:113], v[196:197]
	v_pk_fma_f32 v[190:191], v[134:135], v[114:115], v[190:191]
	v_pk_fma_f32 v[192:193], v[136:137], v[116:117], v[192:193]
	v_pk_fma_f32 v[194:195], v[130:131], v[98:99], v[194:195]
	v_pk_fma_f32 v[196:197], v[132:133], v[100:101], v[196:197]
	v_pk_mul_f32 v[198:199], v[190:191], s[50:51]
	v_pk_mul_f32 v[200:201], v[192:193], s[50:51]
	v_exp_f32_e32 v198, v198
	v_exp_f32_e32 v199, v199
	v_exp_f32_e32 v200, v200
	v_exp_f32_e32 v201, v201
	v_add_f32_e32 v198, 1.0, v198
	v_add_f32_e32 v199, 1.0, v199
	v_add_f32_e32 v200, 1.0, v200
	v_add_f32_e32 v201, 1.0, v201
	v_rcp_f32_e32 v198, v198
	v_rcp_f32_e32 v199, v199
	v_rcp_f32_e32 v200, v200
	v_rcp_f32_e32 v201, v201
	v_pk_mul_f32 v[190:191], v[190:191], v[198:199]
	v_pk_mul_f32 v[192:193], v[192:193], v[200:201]
	v_pk_mul_f32 v[190:191], v[190:191], v[194:195]
	v_pk_mul_f32 v[192:193], v[192:193], v[196:197]
	v_cvt_pk_bf16_f32 v232, v190, v191
	v_cvt_pk_bf16_f32 v233, v192, v193
	v_pk_fma_f32 v[190:191], v[134:135], v[122:123], v[118:119]
	v_pk_fma_f32 v[192:193], v[136:137], v[124:125], v[120:121]
	v_pk_fma_f32 v[194:195], v[130:131], v[106:107], v[102:103]
	v_pk_fma_f32 v[196:197], v[132:133], v[108:109], v[104:105]
	v_pk_fma_f32 v[190:191], v[142:143], v[126:127], v[190:191]
	v_pk_fma_f32 v[192:193], v[144:145], v[128:129], v[192:193]
	v_pk_fma_f32 v[194:195], v[138:139], v[110:111], v[194:195]
	v_pk_fma_f32 v[196:197], v[140:141], v[112:113], v[196:197]
	v_fmac_f32_dpp v190, v158, v114 row_ror:15 row_mask:0xf bank_mask:0xf
	v_fmac_f32_dpp v191, v159, v115 row_ror:15 row_mask:0xf bank_mask:0xf
	v_fmac_f32_dpp v192, v160, v116 row_ror:15 row_mask:0xf bank_mask:0xf
	v_fmac_f32_dpp v193, v161, v117 row_ror:15 row_mask:0xf bank_mask:0xf
	v_fmac_f32_dpp v194, v154, v98 row_ror:15 row_mask:0xf bank_mask:0xf
	v_fmac_f32_dpp v195, v155, v99 row_ror:15 row_mask:0xf bank_mask:0xf
	v_fmac_f32_dpp v196, v156, v100 row_ror:15 row_mask:0xf bank_mask:0xf
	v_fmac_f32_dpp v197, v157, v101 row_ror:15 row_mask:0xf bank_mask:0xf
	v_pk_mul_f32 v[198:199], v[190:191], s[50:51]
	v_pk_mul_f32 v[200:201], v[192:193], s[50:51]
	v_exp_f32_e32 v198, v198
	v_exp_f32_e32 v199, v199
	v_exp_f32_e32 v200, v200
	v_exp_f32_e32 v201, v201
	v_add_f32_e32 v198, 1.0, v198
	v_add_f32_e32 v199, 1.0, v199
	v_add_f32_e32 v200, 1.0, v200
	v_add_f32_e32 v201, 1.0, v201
	v_rcp_f32_e32 v198, v198
	v_rcp_f32_e32 v199, v199
	v_rcp_f32_e32 v200, v200
	v_rcp_f32_e32 v201, v201
	v_pk_mul_f32 v[190:191], v[190:191], v[198:199]
	v_pk_mul_f32 v[192:193], v[192:193], v[200:201]
	v_pk_mul_f32 v[190:191], v[190:191], v[194:195]
	v_pk_mul_f32 v[192:193], v[192:193], v[196:197]
	v_cvt_pk_bf16_f32 v234, v190, v191
	v_cvt_pk_bf16_f32 v235, v192, v193
	v_cmp_gt_i32_e32 vcc, s3, v230
	s_and_b64 vcc, vcc, s[54:55]
	s_nop 0
	v_permlane16_swap_b32_e32 v232, v234
	v_permlane16_swap_b32_e32 v233, v235
	s_and_saveexec_b64 s[0:1], vcc
	global_store_dwordx4 v231, v[232:235], s[12:13]
	s_mov_b64 exec, s[0:1]
	ds_read_b128 v[130:133], v188 offset:64
	ds_read_b128 v[134:137], v188 offset:192
	ds_read_b128 v[138:141], v188 offset:320
	ds_read_b128 v[142:145], v188 offset:448
	ds_read_b128 v[146:149], v188 offset:576
	ds_read_b128 v[150:153], v188 offset:704
	ds_read_b128 v[154:157], v188 offset:832
	ds_read_b128 v[158:161], v188 offset:960
	v_pk_fma_f32 v[190:191], v[94:95], v[122:123], v[118:119]
	v_pk_fma_f32 v[192:193], v[96:97], v[124:125], v[120:121]
	v_pk_fma_f32 v[194:195], v[90:91], v[106:107], v[102:103]
	v_pk_fma_f32 v[196:197], v[92:93], v[108:109], v[104:105]
	v_add_u32_e32 v230, 0x7c, v186
	v_add_u32_e32 v231, 0xaa800, v187
	v_fmac_f32_dpp v190, v70, v126 row_ror:1 row_mask:0xf bank_mask:0xf
	v_fmac_f32_dpp v191, v71, v127 row_ror:1 row_mask:0xf bank_mask:0xf
	v_fmac_f32_dpp v192, v72, v128 row_ror:1 row_mask:0xf bank_mask:0xf
	v_fmac_f32_dpp v193, v73, v129 row_ror:1 row_mask:0xf bank_mask:0xf
	v_fmac_f32_dpp v194, v66, v110 row_ror:1 row_mask:0xf bank_mask:0xf
	v_fmac_f32_dpp v195, v67, v111 row_ror:1 row_mask:0xf bank_mask:0xf
	v_fmac_f32_dpp v196, v68, v112 row_ror:1 row_mask:0xf bank_mask:0xf
	v_fmac_f32_dpp v197, v69, v113 row_ror:1 row_mask:0xf bank_mask:0xf
	v_pk_fma_f32 v[190:191], v[86:87], v[114:115], v[190:191]
	v_pk_fma_f32 v[192:193], v[88:89], v[116:117], v[192:193]
	v_pk_fma_f32 v[194:195], v[82:83], v[98:99], v[194:195]
	v_pk_fma_f32 v[196:197], v[84:85], v[100:101], v[196:197]
	v_pk_mul_f32 v[198:199], v[190:191], s[50:51]
	v_pk_mul_f32 v[200:201], v[192:193], s[50:51]
	v_exp_f32_e32 v198, v198
	v_exp_f32_e32 v199, v199
	v_exp_f32_e32 v200, v200
	v_exp_f32_e32 v201, v201
	v_add_f32_e32 v198, 1.0, v198
	v_add_f32_e32 v199, 1.0, v199
	v_add_f32_e32 v200, 1.0, v200
	v_add_f32_e32 v201, 1.0, v201
	v_rcp_f32_e32 v198, v198
	v_rcp_f32_e32 v199, v199
	v_rcp_f32_e32 v200, v200
	v_rcp_f32_e32 v201, v201
	v_pk_mul_f32 v[190:191], v[190:191], v[198:199]
	v_pk_mul_f32 v[192:193], v[192:193], v[200:201]
	v_pk_mul_f32 v[190:191], v[190:191], v[194:195]
	v_pk_mul_f32 v[192:193], v[192:193], v[196:197]
	v_cvt_pk_bf16_f32 v232, v190, v191
	v_cvt_pk_bf16_f32 v233, v192, v193
	v_pk_fma_f32 v[190:191], v[86:87], v[122:123], v[118:119]
	v_pk_fma_f32 v[192:193], v[88:89], v[124:125], v[120:121]
	v_pk_fma_f32 v[194:195], v[82:83], v[106:107], v[102:103]
	v_pk_fma_f32 v[196:197], v[84:85], v[108:109], v[104:105]
	v_pk_fma_f32 v[190:191], v[94:95], v[126:127], v[190:191]
	v_pk_fma_f32 v[192:193], v[96:97], v[128:129], v[192:193]
	v_pk_fma_f32 v[194:195], v[90:91], v[110:111], v[194:195]
	v_pk_fma_f32 v[196:197], v[92:93], v[112:113], v[196:197]
	v_pk_fma_f32 v[190:191], v[78:79], v[114:115], v[190:191]
	v_pk_fma_f32 v[192:193], v[80:81], v[116:117], v[192:193]
	v_pk_fma_f32 v[194:195], v[74:75], v[98:99], v[194:195]
	v_pk_fma_f32 v[196:197], v[76:77], v[100:101], v[196:197]
	v_pk_mul_f32 v[198:199], v[190:191], s[50:51]
	v_pk_mul_f32 v[200:201], v[192:193], s[50:51]
	v_exp_f32_e32 v198, v198
	v_exp_f32_e32 v199, v199
	v_exp_f32_e32 v200, v200
	v_exp_f32_e32 v201, v201
	v_add_f32_e32 v198, 1.0, v198
	v_add_f32_e32 v199, 1.0, v199
	v_add_f32_e32 v200, 1.0, v200
	v_add_f32_e32 v201, 1.0, v201
	v_rcp_f32_e32 v198, v198
	v_rcp_f32_e32 v199, v199
	v_rcp_f32_e32 v200, v200
	v_rcp_f32_e32 v201, v201
	v_pk_mul_f32 v[190:191], v[190:191], v[198:199]
	v_pk_mul_f32 v[192:193], v[192:193], v[200:201]
	v_pk_mul_f32 v[190:191], v[190:191], v[194:195]
	v_pk_mul_f32 v[192:193], v[192:193], v[196:197]
	v_cvt_pk_bf16_f32 v234, v190, v191
	v_cvt_pk_bf16_f32 v235, v192, v193
	v_cmp_gt_i32_e32 vcc, s3, v230
	s_and_b64 vcc, vcc, s[52:53]
	s_nop 0
	v_permlane16_swap_b32_e32 v232, v234
	v_permlane16_swap_b32_e32 v233, v235
	s_and_saveexec_b64 s[0:1], vcc
	global_store_dwordx4 v231, v[232:235], s[12:13]
	s_mov_b64 exec, s[0:1]
	v_pk_fma_f32 v[190:191], v[78:79], v[122:123], v[118:119]
	v_pk_fma_f32 v[192:193], v[80:81], v[124:125], v[120:121]
	v_pk_fma_f32 v[194:195], v[74:75], v[106:107], v[102:103]
	v_pk_fma_f32 v[196:197], v[76:77], v[108:109], v[104:105]
	v_add_u32_e32 v230, 0x7e, v186
	v_add_u32_e32 v231, 0xad400, v187
	v_pk_fma_f32 v[190:191], v[86:87], v[126:127], v[190:191]
	v_pk_fma_f32 v[192:193], v[88:89], v[128:129], v[192:193]
	v_pk_fma_f32 v[194:195], v[82:83], v[110:111], v[194:195]
	v_pk_fma_f32 v[196:197], v[84:85], v[112:113], v[196:197]
	v_pk_fma_f32 v[190:191], v[70:71], v[114:115], v[190:191]
	v_pk_fma_f32 v[192:193], v[72:73], v[116:117], v[192:193]
	v_pk_fma_f32 v[194:195], v[66:67], v[98:99], v[194:195]
	v_pk_fma_f32 v[196:197], v[68:69], v[100:101], v[196:197]
	v_pk_mul_f32 v[198:199], v[190:191], s[50:51]
	v_pk_mul_f32 v[200:201], v[192:193], s[50:51]
	v_exp_f32_e32 v198, v198
	v_exp_f32_e32 v199, v199
	v_exp_f32_e32 v200, v200
	v_exp_f32_e32 v201, v201
	v_add_f32_e32 v198, 1.0, v198
	v_add_f32_e32 v199, 1.0, v199
	v_add_f32_e32 v200, 1.0, v200
	v_add_f32_e32 v201, 1.0, v201
	v_rcp_f32_e32 v198, v198
	v_rcp_f32_e32 v199, v199
	v_rcp_f32_e32 v200, v200
	v_rcp_f32_e32 v201, v201
	v_pk_mul_f32 v[190:191], v[190:191], v[198:199]
	v_pk_mul_f32 v[192:193], v[192:193], v[200:201]
	v_pk_mul_f32 v[190:191], v[190:191], v[194:195]
	v_pk_mul_f32 v[192:193], v[192:193], v[196:197]
	v_cvt_pk_bf16_f32 v232, v190, v191
	v_cvt_pk_bf16_f32 v233, v192, v193
	v_pk_fma_f32 v[190:191], v[70:71], v[122:123], v[118:119]
	v_pk_fma_f32 v[192:193], v[72:73], v[124:125], v[120:121]
	v_pk_fma_f32 v[194:195], v[66:67], v[106:107], v[102:103]
	v_pk_fma_f32 v[196:197], v[68:69], v[108:109], v[104:105]
	v_pk_fma_f32 v[190:191], v[78:79], v[126:127], v[190:191]
	v_pk_fma_f32 v[192:193], v[80:81], v[128:129], v[192:193]
	v_pk_fma_f32 v[194:195], v[74:75], v[110:111], v[194:195]
	v_pk_fma_f32 v[196:197], v[76:77], v[112:113], v[196:197]
	v_fmac_f32_dpp v190, v94, v114 row_ror:15 row_mask:0xf bank_mask:0xf
	v_fmac_f32_dpp v191, v95, v115 row_ror:15 row_mask:0xf bank_mask:0xf
	v_fmac_f32_dpp v192, v96, v116 row_ror:15 row_mask:0xf bank_mask:0xf
	v_fmac_f32_dpp v193, v97, v117 row_ror:15 row_mask:0xf bank_mask:0xf
	v_fmac_f32_dpp v194, v90, v98 row_ror:15 row_mask:0xf bank_mask:0xf
	v_fmac_f32_dpp v195, v91, v99 row_ror:15 row_mask:0xf bank_mask:0xf
	v_fmac_f32_dpp v196, v92, v100 row_ror:15 row_mask:0xf bank_mask:0xf
	v_fmac_f32_dpp v197, v93, v101 row_ror:15 row_mask:0xf bank_mask:0xf
	v_pk_mul_f32 v[198:199], v[190:191], s[50:51]
	v_pk_mul_f32 v[200:201], v[192:193], s[50:51]
	v_exp_f32_e32 v198, v198
	v_exp_f32_e32 v199, v199
	v_exp_f32_e32 v200, v200
	v_exp_f32_e32 v201, v201
	v_add_f32_e32 v198, 1.0, v198
	v_add_f32_e32 v199, 1.0, v199
	v_add_f32_e32 v200, 1.0, v200
	v_add_f32_e32 v201, 1.0, v201
	v_rcp_f32_e32 v198, v198
	v_rcp_f32_e32 v199, v199
	v_rcp_f32_e32 v200, v200
	v_rcp_f32_e32 v201, v201
	v_pk_mul_f32 v[190:191], v[190:191], v[198:199]
	v_pk_mul_f32 v[192:193], v[192:193], v[200:201]
	v_pk_mul_f32 v[190:191], v[190:191], v[194:195]
	v_pk_mul_f32 v[192:193], v[192:193], v[196:197]
	v_cvt_pk_bf16_f32 v234, v190, v191
	v_cvt_pk_bf16_f32 v235, v192, v193
	v_cmp_gt_i32_e32 vcc, s3, v230
	s_and_b64 vcc, vcc, s[54:55]
	s_nop 0
	v_permlane16_swap_b32_e32 v232, v234
	v_permlane16_swap_b32_e32 v233, v235
	s_and_saveexec_b64 s[0:1], vcc
	global_store_dwordx4 v231, v[232:235], s[12:13]
	s_mov_b64 exec, s[0:1]
	s_waitcnt lgkmcnt(0)
	v_pk_fma_f32 v[190:191], v[62:63], v[134:135], v[142:143]
	v_pk_fma_f32 v[192:193], v[64:65], v[136:137], v[144:145]
	v_pk_fma_f32 v[194:195], v[58:59], v[150:151], v[158:159]
	v_pk_fma_f32 v[196:197], v[60:61], v[152:153], v[160:161]
	v_add_u32_e32 v230, 0, v186
	v_fmac_f32_dpp v190, v38, v130 row_ror:1 row_mask:0xf bank_mask:0xf
	v_fmac_f32_dpp v191, v39, v131 row_ror:1 row_mask:0xf bank_mask:0xf
	v_fmac_f32_dpp v192, v40, v132 row_ror:1 row_mask:0xf bank_mask:0xf
	v_fmac_f32_dpp v193, v41, v133 row_ror:1 row_mask:0xf bank_mask:0xf
	v_fmac_f32_dpp v194, v34, v146 row_ror:1 row_mask:0xf bank_mask:0xf
	v_fmac_f32_dpp v195, v35, v147 row_ror:1 row_mask:0xf bank_mask:0xf
	v_fmac_f32_dpp v196, v36, v148 row_ror:1 row_mask:0xf bank_mask:0xf
	v_fmac_f32_dpp v197, v37, v149 row_ror:1 row_mask:0xf bank_mask:0xf
	v_pk_fma_f32 v[190:191], v[54:55], v[138:139], v[190:191]
	v_pk_fma_f32 v[192:193], v[56:57], v[140:141], v[192:193]
	v_pk_fma_f32 v[194:195], v[50:51], v[154:155], v[194:195]
	v_pk_fma_f32 v[196:197], v[52:53], v[156:157], v[196:197]
	v_pk_mul_f32 v[198:199], v[190:191], s[50:51]
	v_pk_mul_f32 v[200:201], v[192:193], s[50:51]
	v_exp_f32_e32 v198, v198
	v_exp_f32_e32 v199, v199
	v_exp_f32_e32 v200, v200
	v_exp_f32_e32 v201, v201
	v_add_f32_e32 v198, 1.0, v198
	v_add_f32_e32 v199, 1.0, v199
	v_add_f32_e32 v200, 1.0, v200
	v_add_f32_e32 v201, 1.0, v201
	v_rcp_f32_e32 v198, v198
	v_rcp_f32_e32 v199, v199
	v_rcp_f32_e32 v200, v200
	v_rcp_f32_e32 v201, v201
	v_pk_mul_f32 v[190:191], v[190:191], v[198:199]
	v_pk_mul_f32 v[192:193], v[192:193], v[200:201]
	v_pk_mul_f32 v[190:191], v[190:191], v[194:195]
	v_pk_mul_f32 v[192:193], v[192:193], v[196:197]
	v_cvt_pk_bf16_f32 v232, v190, v191
	v_cvt_pk_bf16_f32 v233, v192, v193
	v_pk_fma_f32 v[190:191], v[54:55], v[134:135], v[142:143]
	v_pk_fma_f32 v[192:193], v[56:57], v[136:137], v[144:145]
	v_pk_fma_f32 v[194:195], v[50:51], v[150:151], v[158:159]
	v_pk_fma_f32 v[196:197], v[52:53], v[152:153], v[160:161]
	v_pk_fma_f32 v[190:191], v[62:63], v[130:131], v[190:191]
	v_pk_fma_f32 v[192:193], v[64:65], v[132:133], v[192:193]
	v_pk_fma_f32 v[194:195], v[58:59], v[146:147], v[194:195]
	v_pk_fma_f32 v[196:197], v[60:61], v[148:149], v[196:197]
	v_pk_fma_f32 v[190:191], v[46:47], v[138:139], v[190:191]
	v_pk_fma_f32 v[192:193], v[48:49], v[140:141], v[192:193]
	v_pk_fma_f32 v[194:195], v[42:43], v[154:155], v[194:195]
	v_pk_fma_f32 v[196:197], v[44:45], v[156:157], v[196:197]
	v_pk_mul_f32 v[198:199], v[190:191], s[50:51]
	v_pk_mul_f32 v[200:201], v[192:193], s[50:51]
	v_exp_f32_e32 v198, v198
	v_exp_f32_e32 v199, v199
	v_exp_f32_e32 v200, v200
	v_exp_f32_e32 v201, v201
	v_add_f32_e32 v198, 1.0, v198
	v_add_f32_e32 v199, 1.0, v199
	v_add_f32_e32 v200, 1.0, v200
	v_add_f32_e32 v201, 1.0, v201
	v_rcp_f32_e32 v198, v198
	v_rcp_f32_e32 v199, v199
	v_rcp_f32_e32 v200, v200
	v_rcp_f32_e32 v201, v201
	v_pk_mul_f32 v[190:191], v[190:191], v[198:199]
	v_pk_mul_f32 v[192:193], v[192:193], v[200:201]
	v_pk_mul_f32 v[190:191], v[190:191], v[194:195]
	v_pk_mul_f32 v[192:193], v[192:193], v[196:197]
	v_cvt_pk_bf16_f32 v234, v190, v191
	v_cvt_pk_bf16_f32 v235, v192, v193
	v_cmp_gt_i32_e32 vcc, s3, v230
	s_and_b64 vcc, vcc, s[52:53]
	s_nop 0
	v_permlane16_swap_b32_e32 v232, v234
	v_permlane16_swap_b32_e32 v233, v235
	s_and_saveexec_b64 s[0:1], vcc
	global_store_dwordx4 v187, v[232:235], s[12:13] offset:128
	s_mov_b64 exec, s[0:1]
	v_pk_fma_f32 v[190:191], v[46:47], v[134:135], v[142:143]
	v_pk_fma_f32 v[192:193], v[48:49], v[136:137], v[144:145]
	v_pk_fma_f32 v[194:195], v[42:43], v[150:151], v[158:159]
	v_pk_fma_f32 v[196:197], v[44:45], v[152:153], v[160:161]
	v_add_u32_e32 v230, 2, v186
	v_add_u32_e32 v231, 0x2c00, v187
	v_pk_fma_f32 v[190:191], v[54:55], v[130:131], v[190:191]
	v_pk_fma_f32 v[192:193], v[56:57], v[132:133], v[192:193]
	v_pk_fma_f32 v[194:195], v[50:51], v[146:147], v[194:195]
	v_pk_fma_f32 v[196:197], v[52:53], v[148:149], v[196:197]
	v_pk_fma_f32 v[190:191], v[38:39], v[138:139], v[190:191]
	v_pk_fma_f32 v[192:193], v[40:41], v[140:141], v[192:193]
	v_pk_fma_f32 v[194:195], v[34:35], v[154:155], v[194:195]
	v_pk_fma_f32 v[196:197], v[36:37], v[156:157], v[196:197]
	v_pk_mul_f32 v[198:199], v[190:191], s[50:51]
	v_pk_mul_f32 v[200:201], v[192:193], s[50:51]
	v_exp_f32_e32 v198, v198
	v_exp_f32_e32 v199, v199
	v_exp_f32_e32 v200, v200
	v_exp_f32_e32 v201, v201
	v_add_f32_e32 v198, 1.0, v198
	v_add_f32_e32 v199, 1.0, v199
	v_add_f32_e32 v200, 1.0, v200
	v_add_f32_e32 v201, 1.0, v201
	v_rcp_f32_e32 v198, v198
	v_rcp_f32_e32 v199, v199
	v_rcp_f32_e32 v200, v200
	v_rcp_f32_e32 v201, v201
	v_pk_mul_f32 v[190:191], v[190:191], v[198:199]
	v_pk_mul_f32 v[192:193], v[192:193], v[200:201]
	v_pk_mul_f32 v[190:191], v[190:191], v[194:195]
	v_pk_mul_f32 v[192:193], v[192:193], v[196:197]
	v_cvt_pk_bf16_f32 v232, v190, v191
	v_cvt_pk_bf16_f32 v233, v192, v193
	v_pk_fma_f32 v[190:191], v[38:39], v[134:135], v[142:143]
	v_pk_fma_f32 v[192:193], v[40:41], v[136:137], v[144:145]
	v_pk_fma_f32 v[194:195], v[34:35], v[150:151], v[158:159]
	v_pk_fma_f32 v[196:197], v[36:37], v[152:153], v[160:161]
	v_pk_fma_f32 v[190:191], v[46:47], v[130:131], v[190:191]
	v_pk_fma_f32 v[192:193], v[48:49], v[132:133], v[192:193]
	v_pk_fma_f32 v[194:195], v[42:43], v[146:147], v[194:195]
	v_pk_fma_f32 v[196:197], v[44:45], v[148:149], v[196:197]
	v_fmac_f32_dpp v190, v62, v138 row_ror:15 row_mask:0xf bank_mask:0xf
	v_fmac_f32_dpp v191, v63, v139 row_ror:15 row_mask:0xf bank_mask:0xf
	v_fmac_f32_dpp v192, v64, v140 row_ror:15 row_mask:0xf bank_mask:0xf
	v_fmac_f32_dpp v193, v65, v141 row_ror:15 row_mask:0xf bank_mask:0xf
	v_fmac_f32_dpp v194, v58, v154 row_ror:15 row_mask:0xf bank_mask:0xf
	v_fmac_f32_dpp v195, v59, v155 row_ror:15 row_mask:0xf bank_mask:0xf
	v_fmac_f32_dpp v196, v60, v156 row_ror:15 row_mask:0xf bank_mask:0xf
	v_fmac_f32_dpp v197, v61, v157 row_ror:15 row_mask:0xf bank_mask:0xf
	v_pk_mul_f32 v[198:199], v[190:191], s[50:51]
	v_pk_mul_f32 v[200:201], v[192:193], s[50:51]
	v_exp_f32_e32 v198, v198
	v_exp_f32_e32 v199, v199
	v_exp_f32_e32 v200, v200
	v_exp_f32_e32 v201, v201
	v_add_f32_e32 v198, 1.0, v198
	v_add_f32_e32 v199, 1.0, v199
	v_add_f32_e32 v200, 1.0, v200
	v_add_f32_e32 v201, 1.0, v201
	v_rcp_f32_e32 v198, v198
	v_rcp_f32_e32 v199, v199
	v_rcp_f32_e32 v200, v200
	v_rcp_f32_e32 v201, v201
	v_pk_mul_f32 v[190:191], v[190:191], v[198:199]
	v_pk_mul_f32 v[192:193], v[192:193], v[200:201]
	v_pk_mul_f32 v[190:191], v[190:191], v[194:195]
	v_pk_mul_f32 v[192:193], v[192:193], v[196:197]
	v_cvt_pk_bf16_f32 v234, v190, v191
	v_cvt_pk_bf16_f32 v235, v192, v193
	v_cmp_gt_i32_e32 vcc, s3, v230
	s_and_b64 vcc, vcc, s[54:55]
	s_nop 0
	v_permlane16_swap_b32_e32 v232, v234
	v_permlane16_swap_b32_e32 v233, v235
	s_and_saveexec_b64 s[0:1], vcc
	global_store_dwordx4 v231, v[232:235], s[12:13] offset:128
	s_mov_b64 exec, s[0:1]
	v_pk_fma_f32 v[190:191], v[30:31], v[134:135], v[142:143]
	v_pk_fma_f32 v[192:193], v[32:33], v[136:137], v[144:145]
	v_pk_fma_f32 v[194:195], v[26:27], v[150:151], v[158:159]
	v_pk_fma_f32 v[196:197], v[28:29], v[152:153], v[160:161]
	v_add_u32_e32 v230, 0x7c, v186
	v_add_u32_e32 v231, 0xaa800, v187
	v_fmac_f32_dpp v190, v6, v130 row_ror:1 row_mask:0xf bank_mask:0xf
	v_fmac_f32_dpp v191, v7, v131 row_ror:1 row_mask:0xf bank_mask:0xf
	v_fmac_f32_dpp v192, v8, v132 row_ror:1 row_mask:0xf bank_mask:0xf
	v_fmac_f32_dpp v193, v9, v133 row_ror:1 row_mask:0xf bank_mask:0xf
	v_fmac_f32_dpp v194, v2, v146 row_ror:1 row_mask:0xf bank_mask:0xf
	v_fmac_f32_dpp v195, v3, v147 row_ror:1 row_mask:0xf bank_mask:0xf
	v_fmac_f32_dpp v196, v4, v148 row_ror:1 row_mask:0xf bank_mask:0xf
	v_fmac_f32_dpp v197, v5, v149 row_ror:1 row_mask:0xf bank_mask:0xf
	v_pk_fma_f32 v[190:191], v[22:23], v[138:139], v[190:191]
	v_pk_fma_f32 v[192:193], v[24:25], v[140:141], v[192:193]
	v_pk_fma_f32 v[194:195], v[18:19], v[154:155], v[194:195]
	v_pk_fma_f32 v[196:197], v[20:21], v[156:157], v[196:197]
	v_pk_mul_f32 v[198:199], v[190:191], s[50:51]
	v_pk_mul_f32 v[200:201], v[192:193], s[50:51]
	v_exp_f32_e32 v198, v198
	v_exp_f32_e32 v199, v199
	v_exp_f32_e32 v200, v200
	v_exp_f32_e32 v201, v201
	v_add_f32_e32 v198, 1.0, v198
	v_add_f32_e32 v199, 1.0, v199
	v_add_f32_e32 v200, 1.0, v200
	v_add_f32_e32 v201, 1.0, v201
	v_rcp_f32_e32 v198, v198
	v_rcp_f32_e32 v199, v199
	v_rcp_f32_e32 v200, v200
	v_rcp_f32_e32 v201, v201
	v_pk_mul_f32 v[190:191], v[190:191], v[198:199]
	v_pk_mul_f32 v[192:193], v[192:193], v[200:201]
	v_pk_mul_f32 v[190:191], v[190:191], v[194:195]
	v_pk_mul_f32 v[192:193], v[192:193], v[196:197]
	v_cvt_pk_bf16_f32 v232, v190, v191
	v_cvt_pk_bf16_f32 v233, v192, v193
	v_pk_fma_f32 v[190:191], v[22:23], v[134:135], v[142:143]
	v_pk_fma_f32 v[192:193], v[24:25], v[136:137], v[144:145]
	v_pk_fma_f32 v[194:195], v[18:19], v[150:151], v[158:159]
	v_pk_fma_f32 v[196:197], v[20:21], v[152:153], v[160:161]
	v_pk_fma_f32 v[190:191], v[30:31], v[130:131], v[190:191]
	v_pk_fma_f32 v[192:193], v[32:33], v[132:133], v[192:193]
	v_pk_fma_f32 v[194:195], v[26:27], v[146:147], v[194:195]
	v_pk_fma_f32 v[196:197], v[28:29], v[148:149], v[196:197]
	v_pk_fma_f32 v[190:191], v[14:15], v[138:139], v[190:191]
	v_pk_fma_f32 v[192:193], v[16:17], v[140:141], v[192:193]
	v_pk_fma_f32 v[194:195], v[10:11], v[154:155], v[194:195]
	v_pk_fma_f32 v[196:197], v[12:13], v[156:157], v[196:197]
	v_pk_mul_f32 v[198:199], v[190:191], s[50:51]
	v_pk_mul_f32 v[200:201], v[192:193], s[50:51]
	v_exp_f32_e32 v198, v198
	v_exp_f32_e32 v199, v199
	v_exp_f32_e32 v200, v200
	v_exp_f32_e32 v201, v201
	v_add_f32_e32 v198, 1.0, v198
	v_add_f32_e32 v199, 1.0, v199
	v_add_f32_e32 v200, 1.0, v200
	v_add_f32_e32 v201, 1.0, v201
	v_rcp_f32_e32 v198, v198
	v_rcp_f32_e32 v199, v199
	v_rcp_f32_e32 v200, v200
	v_rcp_f32_e32 v201, v201
	v_pk_mul_f32 v[190:191], v[190:191], v[198:199]
	v_pk_mul_f32 v[192:193], v[192:193], v[200:201]
	v_pk_mul_f32 v[190:191], v[190:191], v[194:195]
	v_pk_mul_f32 v[192:193], v[192:193], v[196:197]
	v_cvt_pk_bf16_f32 v234, v190, v191
	v_cvt_pk_bf16_f32 v235, v192, v193
	v_cmp_gt_i32_e32 vcc, s3, v230
	s_and_b64 vcc, vcc, s[52:53]
	s_nop 0
	v_permlane16_swap_b32_e32 v232, v234
	v_permlane16_swap_b32_e32 v233, v235
	s_and_saveexec_b64 s[0:1], vcc
	global_store_dwordx4 v231, v[232:235], s[12:13] offset:128
	s_mov_b64 exec, s[0:1]
	v_pk_fma_f32 v[190:191], v[14:15], v[134:135], v[142:143]
	v_pk_fma_f32 v[192:193], v[16:17], v[136:137], v[144:145]
	v_pk_fma_f32 v[194:195], v[10:11], v[150:151], v[158:159]
	v_pk_fma_f32 v[196:197], v[12:13], v[152:153], v[160:161]
	v_add_u32_e32 v230, 0x7e, v186
	v_add_u32_e32 v231, 0xad400, v187
	v_pk_fma_f32 v[190:191], v[22:23], v[130:131], v[190:191]
	v_pk_fma_f32 v[192:193], v[24:25], v[132:133], v[192:193]
	v_pk_fma_f32 v[194:195], v[18:19], v[146:147], v[194:195]
	v_pk_fma_f32 v[196:197], v[20:21], v[148:149], v[196:197]
	v_pk_fma_f32 v[190:191], v[6:7], v[138:139], v[190:191]
	v_pk_fma_f32 v[192:193], v[8:9], v[140:141], v[192:193]
	v_pk_fma_f32 v[194:195], v[2:3], v[154:155], v[194:195]
	v_pk_fma_f32 v[196:197], v[4:5], v[156:157], v[196:197]
	v_pk_mul_f32 v[198:199], v[190:191], s[50:51]
	v_pk_mul_f32 v[200:201], v[192:193], s[50:51]
	v_exp_f32_e32 v198, v198
	v_exp_f32_e32 v199, v199
	v_exp_f32_e32 v200, v200
	v_exp_f32_e32 v201, v201
	v_add_f32_e32 v198, 1.0, v198
	v_add_f32_e32 v199, 1.0, v199
	v_add_f32_e32 v200, 1.0, v200
	v_add_f32_e32 v201, 1.0, v201
	v_rcp_f32_e32 v198, v198
	v_rcp_f32_e32 v199, v199
	v_rcp_f32_e32 v200, v200
	v_rcp_f32_e32 v201, v201
	v_pk_mul_f32 v[190:191], v[190:191], v[198:199]
	v_pk_mul_f32 v[192:193], v[192:193], v[200:201]
	v_pk_mul_f32 v[190:191], v[190:191], v[194:195]
	v_pk_mul_f32 v[192:193], v[192:193], v[196:197]
	v_cvt_pk_bf16_f32 v232, v190, v191
	v_cvt_pk_bf16_f32 v233, v192, v193
	v_pk_fma_f32 v[190:191], v[6:7], v[134:135], v[142:143]
	v_pk_fma_f32 v[192:193], v[8:9], v[136:137], v[144:145]
	v_pk_fma_f32 v[194:195], v[2:3], v[150:151], v[158:159]
	v_pk_fma_f32 v[196:197], v[4:5], v[152:153], v[160:161]
	v_pk_fma_f32 v[190:191], v[14:15], v[130:131], v[190:191]
	v_pk_fma_f32 v[192:193], v[16:17], v[132:133], v[192:193]
	v_pk_fma_f32 v[194:195], v[10:11], v[146:147], v[194:195]
	v_pk_fma_f32 v[196:197], v[12:13], v[148:149], v[196:197]
	v_fmac_f32_dpp v190, v30, v138 row_ror:15 row_mask:0xf bank_mask:0xf
	v_fmac_f32_dpp v191, v31, v139 row_ror:15 row_mask:0xf bank_mask:0xf
	v_fmac_f32_dpp v192, v32, v140 row_ror:15 row_mask:0xf bank_mask:0xf
	v_fmac_f32_dpp v193, v33, v141 row_ror:15 row_mask:0xf bank_mask:0xf
	v_fmac_f32_dpp v194, v26, v154 row_ror:15 row_mask:0xf bank_mask:0xf
	v_fmac_f32_dpp v195, v27, v155 row_ror:15 row_mask:0xf bank_mask:0xf
	v_fmac_f32_dpp v196, v28, v156 row_ror:15 row_mask:0xf bank_mask:0xf
	v_fmac_f32_dpp v197, v29, v157 row_ror:15 row_mask:0xf bank_mask:0xf
	v_pk_mul_f32 v[198:199], v[190:191], s[50:51]
	v_pk_mul_f32 v[200:201], v[192:193], s[50:51]
	v_exp_f32_e32 v198, v198
	v_exp_f32_e32 v199, v199
	v_exp_f32_e32 v200, v200
	v_exp_f32_e32 v201, v201
	v_add_f32_e32 v198, 1.0, v198
	v_add_f32_e32 v199, 1.0, v199
	v_add_f32_e32 v200, 1.0, v200
	v_add_f32_e32 v201, 1.0, v201
	v_rcp_f32_e32 v198, v198
	v_rcp_f32_e32 v199, v199
	v_rcp_f32_e32 v200, v200
	v_rcp_f32_e32 v201, v201
	v_pk_mul_f32 v[190:191], v[190:191], v[198:199]
	v_pk_mul_f32 v[192:193], v[192:193], v[200:201]
	v_pk_mul_f32 v[190:191], v[190:191], v[194:195]
	v_pk_mul_f32 v[192:193], v[192:193], v[196:197]
	v_cvt_pk_bf16_f32 v234, v190, v191
	v_cvt_pk_bf16_f32 v235, v192, v193
	v_cmp_gt_i32_e32 vcc, s3, v230
	s_and_b64 vcc, vcc, s[54:55]
	s_nop 0
	v_permlane16_swap_b32_e32 v232, v234
	v_permlane16_swap_b32_e32 v233, v235
	s_and_saveexec_b64 s[0:1], vcc
	global_store_dwordx4 v231, v[232:235], s[12:13] offset:128
	s_mov_b64 exec, s[0:1]

.LBB0_149:
	v_ashrrev_i32_e32 v0, 2, v164
	v_mul_hi_i32 v2, v0, s22
	v_lshrrev_b32_e32 v4, 31, v2
	v_add_u32_e32 v159, v2, v4
	v_mul_lo_u32 v2, v159, 6
	s_waitcnt vmcnt(0)
	v_sub_u32_e32 v130, v0, v2
	s_mul_i32 s3, s62, 6
	v_add_u32_e32 v4, s3, v130
	v_ashrrev_i32_e32 v5, 31, v4
	v_lshlrev_b64 v[4:5], 2, v[4:5]
	v_mov_b32_e32 v3, v202
	v_lshl_add_u64 v[6:7], s[66:67], 0, v[4:5]
	global_load_dword v178, v[6:7], off
	v_and_b32_e32 v158, 15, v3
	v_bfe_u32 v8, v3, 4, 2
	v_lshlrev_b32_e32 v2, 7, v159
	v_lshl_add_u64 v[4:5], s[68:69], 0, v[4:5]
	v_lshlrev_b32_e32 v98, 6, v130
	global_load_dword v179, v[4:5], off
	v_ashrrev_i32_e32 v99, 31, v98
	v_mov_b64_e32 v[4:5], s[16:17]
	v_lshlrev_b64 v[134:135], 1, v[98:99]
	v_lshlrev_b32_e32 v102, 4, v8
	v_mov_b32_e32 v103, v1
	v_and_or_b32 v168, v165, s23, v158
	v_or_b32_e32 v167, v168, v2
	v_or_b32_e32 v166, 16, v167
	v_lshlrev_b32_e32 v0, 3, v8
	v_mad_i64_i32 v[6:7], s[14:15], v167, s57, v[4:5]
	v_mad_i64_i32 v[8:9], s[14:15], v166, s57, v[4:5]
	v_lshl_add_u64 v[100:101], v[6:7], 0, v[134:135]
	v_lshl_add_u64 v[104:105], v[8:9], 0, v[134:135]
	v_lshl_add_u64 v[6:7], v[100:101], 0, v[102:103]
	v_lshl_add_u64 v[8:9], v[104:105], 0, v[102:103]
	v_lshl_add_u64 v[100:101], v[100:101], 0, v[0:1]
	v_lshl_add_u64 v[106:107], v[100:101], 0, s[52:53]
	v_lshl_add_u64 v[132:133], s[24:25], 0, v[102:103]
	v_or_b32_e32 v171, 16, v168
	v_ashrrev_i32_e32 v131, 31, v130
	v_mov_b32_e32 v173, v1
	v_mov_b32_e32 v175, v1
	v_mov_b32_e32 v164, v180
	v_add_u32_e32 v180, v181, v180
	v_lshlrev_b32_e32 v165, 5, v164
	v_lshlrev_b32_e32 v10, 1, v3
	v_and_b32_e32 v10, 24, v10
	v_and_b32_e32 v3, 3, v3
	v_or3_b32 v3, v3, v10, v2
	v_or_b32_e32 v18, 64, v3
	v_mad_i64_i32 v[18:19], s[14:15], v18, s57, v[4:5]
	v_lshl_add_u64 v[18:19], v[18:19], 0, v[134:135]
	v_lshl_add_u64 v[34:35], v[18:19], 0, v[102:103]
	v_or_b32_e32 v18, 0x44, v3
	v_mad_i64_i32 v[18:19], s[14:15], v18, s57, v[4:5]
	v_lshl_add_u64 v[18:19], v[18:19], 0, v[134:135]
	v_lshl_add_u64 v[36:37], v[18:19], 0, v[102:103]
	v_or_b32_e32 v18, 0x60, v3
	v_mad_i64_i32 v[18:19], s[14:15], v18, s57, v[4:5]
	v_mad_i64_i32 v[10:11], s[14:15], v3, s57, v[4:5]
	v_or_b32_e32 v12, 4, v3
	v_or_b32_e32 v14, 32, v3
	v_or_b32_e32 v16, 36, v3
	v_lshl_add_u64 v[18:19], v[18:19], 0, v[134:135]
	v_or_b32_e32 v3, 0x64, v3
	v_mad_i64_i32 v[12:13], s[14:15], v12, s57, v[4:5]
	v_mad_i64_i32 v[14:15], s[14:15], v14, s57, v[4:5]
	v_mad_i64_i32 v[16:17], s[14:15], v16, s57, v[4:5]
	v_lshl_add_u64 v[94:95], v[18:19], 0, v[102:103]
	v_mad_i64_i32 v[4:5], s[14:15], v3, s57, v[4:5]
	v_or_b32_e32 v18, v98, v158
	v_ashrrev_i32_e32 v3, 31, v2
	v_lshl_add_u64 v[2:3], v[2:3], 1, s[18:19]
	v_mul_lo_u32 v18, v18, s35
	v_lshl_add_u64 v[2:3], v[2:3], 0, v[102:103]
	v_ashrrev_i32_e32 v19, 31, v18
	v_lshl_add_u64 v[110:111], v[18:19], 1, v[2:3]
	v_add_co_u32_e32 v112, vcc, s42, v110
	v_lshl_add_u64 v[12:13], v[12:13], 0, v[134:135]
	s_nop 0
	v_addc_co_u32_e32 v113, vcc, 0, v111, vcc
	v_add_co_u32_e32 v152, vcc, s43, v110
	v_lshl_add_u64 v[10:11], v[10:11], 0, v[134:135]
	v_lshl_add_u64 v[12:13], v[12:13], 0, v[102:103]
	v_lshl_add_u64 v[14:15], v[14:15], 0, v[134:135]
	v_lshl_add_u64 v[16:17], v[16:17], 0, v[134:135]
	v_addc_co_u32_e32 v153, vcc, 0, v111, vcc
	v_lshl_add_u64 v[10:11], v[10:11], 0, v[102:103]
	v_lshl_add_u64 v[14:15], v[14:15], 0, v[102:103]
	v_lshl_add_u64 v[16:17], v[16:17], 0, v[102:103]
	v_lshl_add_u64 v[4:5], v[4:5], 0, v[134:135]
	global_load_dwordx4 v[66:69], v[12:13], off offset:3648
	global_load_dwordx4 v[70:73], v[12:13], off offset:3584
	global_load_dwordx4 v[74:77], v[10:11], off offset:3648
	global_load_dwordx4 v[78:81], v[10:11], off offset:3584
	global_load_dwordx4 v[18:21], v[8:9], off offset:2880
	global_load_dwordx4 v[26:29], v[8:9], off offset:2816
	global_load_dwordx4 v[22:25], v[6:7], off offset:2880
	global_load_dwordx4 v[30:33], v[6:7], off offset:2816
	global_load_dwordx4 v[114:117], v[36:37], off offset:3648
	global_load_dwordx4 v[118:121], v[36:37], off offset:3584
	global_load_dwordx4 v[122:125], v[34:35], off offset:3648
	global_load_dwordx4 v[126:129], v[34:35], off offset:3584
	s_nop 0
	global_load_dwordx4 v[34:37], v[16:17], off offset:3648
	global_load_dwordx4 v[38:41], v[16:17], off offset:3584
	global_load_dwordx4 v[42:45], v[14:15], off offset:3648
	global_load_dwordx4 v[46:49], v[14:15], off offset:3584
	v_add_co_u32_e32 v154, vcc, s50, v110
	v_lshl_add_u64 v[4:5], v[4:5], 0, v[102:103]
	s_nop 0
	v_addc_co_u32_e32 v155, vcc, 0, v111, vcc
	global_load_dwordx4 v[50:53], v[112:113], off
	global_load_dwordx4 v[54:57], v[152:153], off
	global_load_dwordx4 v[58:61], v[154:155], off
	global_load_dwordx4 v[62:65], v[110:111], off
	global_load_dwordx4 v[82:85], v[4:5], off offset:3648
	global_load_dwordx4 v[86:89], v[4:5], off offset:3584
	global_load_dwordx4 v[90:93], v[94:95], off offset:3648
	s_nop 0
	global_load_dwordx4 v[94:97], v[94:95], off offset:3584
	s_nop 0
	global_load_dwordx4 v[2:5], v[112:113], off offset:64
	global_load_dwordx4 v[6:9], v[152:153], off offset:64
	global_load_dwordx4 v[10:13], v[154:155], off offset:64
	global_load_dwordx4 v[14:17], v[110:111], off offset:64
	v_add_co_u32_e32 v100, vcc, s51, v100
	v_lshl_add_u64 v[98:99], v[98:99], 2, s[38:39]
	s_nop 0
	v_addc_co_u32_e32 v101, vcc, 0, v101, vcc
	v_lshl_add_u64 v[156:157], v[98:99], 0, v[102:103]
	v_or_b32_e32 v108, 7, v0
	s_waitcnt vmcnt(0)
	v_mul_f32_e32 v169, 0x3fb8aa3b, v178
	v_mul_f32_e32 v170, 0x3fb8aa3b, v179
	global_load_dwordx2 v[150:151], v[100:101], off offset:1024
	global_load_dwordx2 v[148:149], v[106:107], off offset:32
	global_load_dwordx2 v[146:147], v[106:107], off offset:64
	global_load_dwordx2 v[144:145], v[106:107], off offset:96
	v_lshl_add_u64 v[100:101], v[104:105], 0, v[0:1]
	v_lshl_add_u64 v[104:105], v[100:101], 0, s[52:53]
	v_add_co_u32_e32 v100, vcc, s51, v100
	v_or_b32_e32 v106, 5, v0
	s_nop 0
	v_addc_co_u32_e32 v101, vcc, 0, v101, vcc
	global_load_dwordx2 v[142:143], v[100:101], off offset:1024
	global_load_dwordx2 v[140:141], v[104:105], off offset:32
	global_load_dwordx2 v[138:139], v[104:105], off offset:64
	global_load_dwordx2 v[136:137], v[104:105], off offset:96
	v_mfma_f32_16x16x32_bf16 v[98:101], v[78:81], v[30:33], 0
	v_or_b32_e32 v107, 6, v0
	v_mfma_f32_16x16x32_bf16 v[78:81], v[78:81], v[26:29], 0
	v_mfma_f32_16x16x32_bf16 v[98:101], v[74:77], v[22:25], v[98:101]
	v_mfma_f32_16x16x32_bf16 v[74:77], v[74:77], v[18:21], v[78:81]
	v_mfma_f32_16x16x32_bf16 v[78:81], v[70:73], v[30:33], 0
	v_mfma_f32_16x16x32_bf16 v[70:73], v[70:73], v[26:29], 0
	v_mfma_f32_16x16x32_bf16 v[78:81], v[66:69], v[22:25], v[78:81]
	v_mfma_f32_16x16x32_bf16 v[66:69], v[66:69], v[18:21], v[70:73]
	s_nop 5
	v_sub_u32_e32 v71, v168, v0
	v_cvt_f32_u32_e32 v72, v71
	v_cmp_lt_i32_e32 vcc, -1, v71
	v_or_b32_e32 v70, 4, v0
	v_mul_f32_e32 v72, v169, v72
	v_exp_f32_e32 v72, v72
	s_nop 0
	v_cndmask_b32_e32 v72, 0, v72, vcc
	v_cmp_gt_i32_e32 vcc, 1, v71
	v_sub_u32_e32 v71, 0, v71
	v_cvt_f32_u32_e32 v71, v71
	v_mul_f32_e32 v71, v170, v71
	v_exp_f32_e32 v71, v71
	s_nop 0
	v_cndmask_b32_e32 v71, 0, v71, vcc
	v_add_f32_e32 v71, v72, v71
	v_or_b32_e32 v72, 1, v0
	v_sub_u32_e32 v73, v168, v72
	v_mul_f32_e32 v71, v71, v98
	v_cvt_f32_u32_e32 v98, v73
	v_cmp_lt_i32_e32 vcc, -1, v73
	v_sub_u32_e32 v72, v171, v72
	v_mul_f32_e32 v98, v169, v98
	v_exp_f32_e32 v98, v98
	s_nop 0
	v_cndmask_b32_e32 v98, 0, v98, vcc
	v_cmp_gt_i32_e32 vcc, 1, v73
	v_sub_u32_e32 v73, 0, v73
	v_cvt_f32_u32_e32 v73, v73
	v_mul_f32_e32 v73, v170, v73
	v_exp_f32_e32 v73, v73
	s_nop 0
	v_cndmask_b32_e32 v73, 0, v73, vcc
	v_add_f32_e32 v73, v98, v73
	v_or_b32_e32 v98, 2, v0
	v_mul_f32_e32 v73, v73, v99
	v_sub_u32_e32 v99, v168, v98
	v_cvt_f32_u32_e32 v102, v99
	v_cmp_lt_i32_e32 vcc, -1, v99
	v_mul_f32_e32 v102, v169, v102
	v_exp_f32_e32 v102, v102
	s_nop 0
	v_cndmask_b32_e32 v102, 0, v102, vcc
	v_cmp_gt_i32_e32 vcc, 1, v99
	v_sub_u32_e32 v99, 0, v99
	v_cvt_f32_u32_e32 v99, v99
	v_mul_f32_e32 v99, v170, v99
	v_exp_f32_e32 v99, v99
	s_nop 0
	v_cndmask_b32_e32 v99, 0, v99, vcc
	v_add_f32_e32 v99, v102, v99
	v_mul_f32_e32 v99, v99, v100
	v_or_b32_e32 v100, 3, v0
	v_sub_u32_e32 v102, v168, v100
	v_cvt_f32_u32_e32 v103, v102
	v_cmp_lt_i32_e32 vcc, -1, v102
	v_mul_f32_e32 v103, v169, v103
	v_exp_f32_e32 v103, v103
	s_nop 0
	v_cndmask_b32_e32 v103, 0, v103, vcc
	v_cmp_gt_i32_e32 vcc, 1, v102
	v_sub_u32_e32 v102, 0, v102
	v_cvt_f32_u32_e32 v102, v102
	v_mul_f32_e32 v102, v170, v102
	v_exp_f32_e32 v102, v102
	s_nop 0
	v_cndmask_b32_e32 v102, 0, v102, vcc
	v_add_f32_e32 v102, v103, v102
	v_mul_f32_e32 v101, v102, v101
	v_sub_u32_e32 v102, v168, v70
	v_cvt_f32_u32_e32 v103, v102
	v_cmp_lt_i32_e32 vcc, -1, v102
	v_sub_u32_e32 v70, v171, v70
	v_mul_f32_e32 v103, v169, v103
	v_exp_f32_e32 v103, v103
	s_nop 0
	v_cndmask_b32_e32 v103, 0, v103, vcc
	v_cmp_gt_i32_e32 vcc, 1, v102
	v_sub_u32_e32 v102, 0, v102
	v_cvt_f32_u32_e32 v102, v102
	v_mul_f32_e32 v102, v170, v102
	v_exp_f32_e32 v102, v102
	s_nop 0
	v_cndmask_b32_e32 v102, 0, v102, vcc
	v_add_f32_e32 v102, v103, v102
	v_mul_f32_e32 v78, v102, v78
	v_sub_u32_e32 v102, v168, v106
	v_cvt_f32_u32_e32 v103, v102
	v_cmp_lt_i32_e32 vcc, -1, v102
	v_mul_f32_e32 v103, v169, v103
	v_exp_f32_e32 v103, v103
	s_nop 0
	v_cndmask_b32_e32 v103, 0, v103, vcc
	v_cmp_gt_i32_e32 vcc, 1, v102
	v_sub_u32_e32 v102, 0, v102
	v_cvt_f32_u32_e32 v102, v102
	v_mul_f32_e32 v102, v170, v102
	v_exp_f32_e32 v102, v102
	s_nop 0
	v_cndmask_b32_e32 v102, 0, v102, vcc
	v_add_f32_e32 v102, v103, v102
	v_mul_f32_e32 v79, v102, v79
	v_sub_u32_e32 v102, v168, v107
	v_cvt_f32_u32_e32 v103, v102
	v_cmp_lt_i32_e32 vcc, -1, v102
	v_cvt_pk_bf16_f32 v104, v78, v79
	v_mul_f32_e32 v103, v169, v103
	v_exp_f32_e32 v103, v103
	s_nop 0
	v_cndmask_b32_e32 v103, 0, v103, vcc
	v_cmp_gt_i32_e32 vcc, 1, v102
	v_sub_u32_e32 v102, 0, v102
	v_cvt_f32_u32_e32 v102, v102
	v_mul_f32_e32 v102, v170, v102
	v_exp_f32_e32 v102, v102
	s_nop 0
	v_cndmask_b32_e32 v102, 0, v102, vcc
	v_add_f32_e32 v102, v103, v102
	v_mul_f32_e32 v80, v102, v80
	v_sub_u32_e32 v102, v168, v108
	v_cvt_f32_u32_e32 v103, v102
	v_cmp_lt_i32_e32 vcc, -1, v102
	v_mul_f32_e32 v103, v169, v103
	v_exp_f32_e32 v103, v103
	s_nop 0
	v_cndmask_b32_e32 v103, 0, v103, vcc
	v_cmp_gt_i32_e32 vcc, 1, v102
	v_sub_u32_e32 v102, 0, v102
	v_cvt_f32_u32_e32 v102, v102
	v_mul_f32_e32 v102, v170, v102
	v_exp_f32_e32 v102, v102
	s_nop 0
	v_cndmask_b32_e32 v102, 0, v102, vcc
	v_add_f32_e32 v102, v103, v102
	v_mul_f32_e32 v81, v102, v81
	v_cvt_pk_bf16_f32 v102, v71, v73
	v_sub_u32_e32 v71, v171, v0
	v_cvt_f32_u32_e32 v73, v71
	v_cmp_lt_i32_e32 vcc, -1, v71
	v_cvt_pk_bf16_f32 v103, v99, v101
	v_cvt_pk_bf16_f32 v105, v80, v81
	v_mul_f32_e32 v73, v169, v73
	v_exp_f32_e32 v73, v73
	v_mfma_f32_16x16x32_bf16 v[78:81], v[54:57], v[102:105], 0
	v_cndmask_b32_e32 v73, 0, v73, vcc
	v_cmp_gt_i32_e32 vcc, 1, v71
	v_sub_u32_e32 v71, 0, v71
	v_cvt_f32_u32_e32 v71, v71
	v_mul_f32_e32 v71, v170, v71
	v_exp_f32_e32 v71, v71
	s_nop 0
	v_cndmask_b32_e32 v71, 0, v71, vcc
	v_add_f32_e32 v71, v73, v71
	v_cvt_f32_u32_e32 v73, v72
	v_cmp_lt_i32_e32 vcc, -1, v72
	v_mul_f32_e32 v71, v71, v74
	v_mul_f32_e32 v73, v169, v73
	v_exp_f32_e32 v73, v73
	s_nop 0
	v_cndmask_b32_e32 v73, 0, v73, vcc
	v_cmp_gt_i32_e32 vcc, 1, v72
	v_sub_u32_e32 v72, 0, v72
	v_cvt_f32_u32_e32 v72, v72
	v_mul_f32_e32 v72, v170, v72
	v_exp_f32_e32 v72, v72
	s_nop 0
	v_cndmask_b32_e32 v72, 0, v72, vcc
	v_add_f32_e32 v72, v73, v72
	v_sub_u32_e32 v73, v171, v98
	v_cvt_f32_u32_e32 v74, v73
	v_cmp_lt_i32_e32 vcc, -1, v73
	v_mul_f32_e32 v72, v72, v75
	v_mul_f32_e32 v74, v169, v74
	v_exp_f32_e32 v74, v74
	s_nop 0
	v_cndmask_b32_e32 v74, 0, v74, vcc
	v_cmp_gt_i32_e32 vcc, 1, v73
	v_sub_u32_e32 v73, 0, v73
	v_cvt_f32_u32_e32 v73, v73
	v_mul_f32_e32 v73, v170, v73
	v_exp_f32_e32 v73, v73
	s_nop 0
	v_cndmask_b32_e32 v73, 0, v73, vcc
	v_add_f32_e32 v73, v74, v73
	v_sub_u32_e32 v74, v171, v100
	v_cvt_f32_u32_e32 v75, v74
	v_cmp_lt_i32_e32 vcc, -1, v74
	v_mul_f32_e32 v73, v73, v76
	v_mul_f32_e32 v75, v169, v75
	v_exp_f32_e32 v75, v75
	s_nop 0
	v_cndmask_b32_e32 v75, 0, v75, vcc
	v_cmp_gt_i32_e32 vcc, 1, v74
	v_sub_u32_e32 v74, 0, v74
	v_cvt_f32_u32_e32 v74, v74
	v_mul_f32_e32 v74, v170, v74
	v_exp_f32_e32 v74, v74
	s_nop 0
	v_cndmask_b32_e32 v74, 0, v74, vcc
	v_add_f32_e32 v74, v75, v74
	v_cvt_f32_u32_e32 v75, v70
	v_cmp_lt_i32_e32 vcc, -1, v70
	v_mul_f32_e32 v74, v74, v77
	v_mul_f32_e32 v75, v169, v75
	v_exp_f32_e32 v75, v75
	s_nop 0
	v_cndmask_b32_e32 v75, 0, v75, vcc
	v_cmp_gt_i32_e32 vcc, 1, v70
	v_sub_u32_e32 v70, 0, v70
	v_cvt_f32_u32_e32 v70, v70
	v_mul_f32_e32 v70, v170, v70
	v_exp_f32_e32 v70, v70
	s_nop 0
	v_cndmask_b32_e32 v70, 0, v70, vcc
	v_add_f32_e32 v70, v75, v70
	v_mul_f32_e32 v66, v70, v66
	v_sub_u32_e32 v70, v171, v106
	v_cvt_f32_u32_e32 v75, v70
	v_cmp_lt_i32_e32 vcc, -1, v70
	v_cvt_pk_bf16_f32 v106, v71, v72
	v_mul_f32_e32 v75, v169, v75
	v_exp_f32_e32 v75, v75
	s_nop 0
	v_cndmask_b32_e32 v75, 0, v75, vcc
	v_cmp_gt_i32_e32 vcc, 1, v70
	v_sub_u32_e32 v70, 0, v70
	v_cvt_f32_u32_e32 v70, v70
	v_mul_f32_e32 v70, v170, v70
	v_exp_f32_e32 v70, v70
	s_nop 0
	v_cndmask_b32_e32 v70, 0, v70, vcc
	v_add_f32_e32 v70, v75, v70
	v_mul_f32_e32 v67, v70, v67
	v_sub_u32_e32 v70, v171, v107
	v_cvt_f32_u32_e32 v75, v70
	v_cmp_lt_i32_e32 vcc, -1, v70
	v_cvt_pk_bf16_f32 v107, v73, v74
	v_mul_f32_e32 v75, v169, v75
	v_exp_f32_e32 v75, v75
	s_nop 0
	v_cndmask_b32_e32 v75, 0, v75, vcc
	v_cmp_gt_i32_e32 vcc, 1, v70
	v_sub_u32_e32 v70, 0, v70
	v_cvt_f32_u32_e32 v70, v70
	v_mul_f32_e32 v70, v170, v70
	v_exp_f32_e32 v70, v70
	s_nop 0
	v_cndmask_b32_e32 v70, 0, v70, vcc
	v_add_f32_e32 v70, v75, v70
	v_mul_f32_e32 v68, v70, v68
	v_sub_u32_e32 v70, v171, v108
	v_cvt_f32_u32_e32 v75, v70
	v_cmp_lt_i32_e32 vcc, -1, v70
	v_cvt_pk_bf16_f32 v108, v66, v67
	v_mul_f32_e32 v75, v169, v75
	v_exp_f32_e32 v75, v75
	s_nop 0
	v_cndmask_b32_e32 v75, 0, v75, vcc
	v_cmp_gt_i32_e32 vcc, 1, v70
	v_sub_u32_e32 v70, 0, v70
	v_cvt_f32_u32_e32 v70, v70
	v_mul_f32_e32 v70, v170, v70
	v_exp_f32_e32 v70, v70
	s_nop 0
	v_cndmask_b32_e32 v70, 0, v70, vcc
	v_add_f32_e32 v70, v75, v70
	v_mul_f32_e32 v69, v70, v69
	v_cvt_pk_bf16_f32 v109, v68, v69
	v_mfma_f32_16x16x32_bf16 v[66:69], v[62:65], v[102:105], 0
	v_mfma_f32_16x16x32_bf16 v[62:65], v[62:65], v[106:109], 0
	v_mfma_f32_16x16x32_bf16 v[70:73], v[58:61], v[102:105], 0
	v_mfma_f32_16x16x32_bf16 v[74:77], v[58:61], v[106:109], 0
	v_mfma_f32_16x16x32_bf16 v[98:101], v[54:57], v[106:109], 0
	v_or_b32_e32 v55, 32, v0
	v_or_b32_e32 v54, 36, v0
	v_mfma_f32_16x16x32_bf16 v[102:105], v[50:53], v[102:105], 0
	v_mfma_f32_16x16x32_bf16 v[106:109], v[50:53], v[106:109], 0
	v_mfma_f32_16x16x32_bf16 v[50:53], v[46:49], v[30:33], 0
	v_mfma_f32_16x16x32_bf16 v[46:49], v[46:49], v[26:29], 0
	v_mfma_f32_16x16x32_bf16 v[50:53], v[42:45], v[22:25], v[50:53]
	v_mfma_f32_16x16x32_bf16 v[42:45], v[42:45], v[18:21], v[46:49]
	v_mfma_f32_16x16x32_bf16 v[46:49], v[38:41], v[30:33], 0
	v_mfma_f32_16x16x32_bf16 v[38:41], v[38:41], v[26:29], 0
	v_mfma_f32_16x16x32_bf16 v[46:49], v[34:37], v[22:25], v[46:49]
	v_mfma_f32_16x16x32_bf16 v[34:37], v[34:37], v[18:21], v[38:41]
	s_nop 5
	v_sub_u32_e32 v38, v168, v55
	v_cvt_f32_u32_e32 v39, v38
	v_cmp_lt_i32_e32 vcc, -1, v38
	v_mul_f32_e32 v39, v169, v39
	v_exp_f32_e32 v39, v39
	s_nop 0
	v_cndmask_b32_e32 v39, 0, v39, vcc
	v_cmp_gt_i32_e32 vcc, 1, v38
	v_sub_u32_e32 v38, 0, v38
	v_cvt_f32_u32_e32 v38, v38
	v_mul_f32_e32 v38, v170, v38
	v_exp_f32_e32 v38, v38
	s_nop 0
	v_cndmask_b32_e32 v38, 0, v38, vcc
	v_add_f32_e32 v38, v39, v38
	v_mul_f32_e32 v38, v38, v50
	v_or_b32_e32 v50, 33, v0
	v_sub_u32_e32 v39, v168, v50
	v_cvt_f32_u32_e32 v40, v39
	v_cmp_lt_i32_e32 vcc, -1, v39
	v_mul_f32_e32 v40, v169, v40
	v_exp_f32_e32 v40, v40
	s_nop 0
	v_cndmask_b32_e32 v40, 0, v40, vcc
	v_cmp_gt_i32_e32 vcc, 1, v39
	v_sub_u32_e32 v39, 0, v39
	v_cvt_f32_u32_e32 v39, v39
	v_mul_f32_e32 v39, v170, v39
	v_exp_f32_e32 v39, v39
	s_nop 0
	v_cndmask_b32_e32 v39, 0, v39, vcc
	v_add_f32_e32 v39, v40, v39
	v_mul_f32_e32 v39, v39, v51
	v_or_b32_e32 v51, 34, v0
	v_sub_u32_e32 v40, v168, v51
	v_cvt_f32_u32_e32 v41, v40
	v_cmp_lt_i32_e32 vcc, -1, v40
	v_cvt_pk_bf16_f32 v38, v38, v39
	v_mul_f32_e32 v41, v169, v41
	v_exp_f32_e32 v41, v41
	s_nop 0
	v_cndmask_b32_e32 v41, 0, v41, vcc
	v_cmp_gt_i32_e32 vcc, 1, v40
	v_sub_u32_e32 v40, 0, v40
	v_cvt_f32_u32_e32 v40, v40
	v_mul_f32_e32 v40, v170, v40
	v_exp_f32_e32 v40, v40
	s_nop 0
	v_cndmask_b32_e32 v40, 0, v40, vcc
	v_add_f32_e32 v40, v41, v40
	v_mul_f32_e32 v40, v40, v52
	v_or_b32_e32 v52, 35, v0
	v_sub_u32_e32 v41, v168, v52
	v_cvt_f32_u32_e32 v56, v41
	v_cmp_lt_i32_e32 vcc, -1, v41
	v_mul_f32_e32 v56, v169, v56
	v_exp_f32_e32 v56, v56
	s_nop 0
	v_cndmask_b32_e32 v56, 0, v56, vcc
	v_cmp_gt_i32_e32 vcc, 1, v41
	v_sub_u32_e32 v41, 0, v41
	v_cvt_f32_u32_e32 v41, v41
	v_mul_f32_e32 v41, v170, v41
	v_exp_f32_e32 v41, v41
	s_nop 0
	v_cndmask_b32_e32 v41, 0, v41, vcc
	v_add_f32_e32 v41, v56, v41
	v_mul_f32_e32 v41, v41, v53
	v_sub_u32_e32 v53, v168, v54
	v_cvt_f32_u32_e32 v56, v53
	v_cmp_lt_i32_e32 vcc, -1, v53
	v_cvt_pk_bf16_f32 v39, v40, v41
	v_mul_f32_e32 v56, v169, v56
	v_exp_f32_e32 v56, v56
	s_nop 0
	v_cndmask_b32_e32 v56, 0, v56, vcc
	v_cmp_gt_i32_e32 vcc, 1, v53
	v_sub_u32_e32 v53, 0, v53
	v_cvt_f32_u32_e32 v53, v53
	v_mul_f32_e32 v53, v170, v53
	v_exp_f32_e32 v53, v53
	s_nop 0
	v_cndmask_b32_e32 v53, 0, v53, vcc
	v_add_f32_e32 v53, v56, v53
	v_mul_f32_e32 v46, v53, v46
	v_or_b32_e32 v53, 37, v0
	v_sub_u32_e32 v56, v168, v53
	v_cvt_f32_u32_e32 v57, v56
	v_cmp_lt_i32_e32 vcc, -1, v56
	v_mul_f32_e32 v57, v169, v57
	v_exp_f32_e32 v57, v57
	s_nop 0
	v_cndmask_b32_e32 v57, 0, v57, vcc
	v_cmp_gt_i32_e32 vcc, 1, v56
	v_sub_u32_e32 v56, 0, v56
	v_cvt_f32_u32_e32 v56, v56
	v_mul_f32_e32 v56, v170, v56
	v_exp_f32_e32 v56, v56
	s_nop 0
	v_cndmask_b32_e32 v56, 0, v56, vcc
	v_add_f32_e32 v56, v57, v56
	v_mul_f32_e32 v47, v56, v47
	v_or_b32_e32 v56, 38, v0
	v_sub_u32_e32 v57, v168, v56
	v_cvt_f32_u32_e32 v58, v57
	v_cmp_lt_i32_e32 vcc, -1, v57
	v_cvt_pk_bf16_f32 v40, v46, v47
	v_sub_u32_e32 v46, v171, v55
	v_mul_f32_e32 v58, v169, v58
	v_exp_f32_e32 v58, v58
	v_cvt_f32_u32_e32 v47, v46
	v_cndmask_b32_e32 v58, 0, v58, vcc
	v_cmp_gt_i32_e32 vcc, 1, v57
	v_sub_u32_e32 v57, 0, v57
	v_cvt_f32_u32_e32 v57, v57
	v_mul_f32_e32 v47, v169, v47
	v_exp_f32_e32 v47, v47
	v_mul_f32_e32 v57, v170, v57
	v_exp_f32_e32 v57, v57
	s_nop 0
	v_cndmask_b32_e32 v57, 0, v57, vcc
	v_add_f32_e32 v57, v58, v57
	v_mul_f32_e32 v48, v57, v48
	v_or_b32_e32 v57, 39, v0
	v_sub_u32_e32 v58, v168, v57
	v_cvt_f32_u32_e32 v59, v58
	v_cmp_lt_i32_e32 vcc, -1, v58
	v_mul_f32_e32 v59, v169, v59
	v_exp_f32_e32 v59, v59
	s_nop 0
	v_cndmask_b32_e32 v59, 0, v59, vcc
	v_cmp_gt_i32_e32 vcc, 1, v58
	v_sub_u32_e32 v58, 0, v58
	v_cvt_f32_u32_e32 v58, v58
	v_mul_f32_e32 v58, v170, v58
	v_exp_f32_e32 v58, v58
	s_nop 0
	v_cndmask_b32_e32 v58, 0, v58, vcc
	v_cmp_lt_i32_e32 vcc, -1, v46
	v_add_f32_e32 v58, v59, v58
	v_mul_f32_e32 v49, v58, v49
	v_cndmask_b32_e32 v47, 0, v47, vcc
	v_cmp_gt_i32_e32 vcc, 1, v46
	v_sub_u32_e32 v46, 0, v46
	v_cvt_f32_u32_e32 v46, v46
	v_cvt_pk_bf16_f32 v41, v48, v49
	v_mul_f32_e32 v46, v170, v46
	v_exp_f32_e32 v46, v46
	v_mfma_f32_16x16x32_bf16 v[58:61], v[10:13], v[38:41], v[70:73]
	v_cndmask_b32_e32 v46, 0, v46, vcc
	v_add_f32_e32 v46, v47, v46
	v_mul_f32_e32 v42, v46, v42
	v_sub_u32_e32 v46, v171, v50
	v_cvt_f32_u32_e32 v47, v46
	v_cmp_lt_i32_e32 vcc, -1, v46
	v_mul_f32_e32 v47, v169, v47
	v_exp_f32_e32 v47, v47
	s_nop 0
	v_cndmask_b32_e32 v47, 0, v47, vcc
	v_cmp_gt_i32_e32 vcc, 1, v46
	v_sub_u32_e32 v46, 0, v46
	v_cvt_f32_u32_e32 v46, v46
	v_mul_f32_e32 v46, v170, v46
	v_exp_f32_e32 v46, v46
	s_nop 0
	v_cndmask_b32_e32 v46, 0, v46, vcc
	v_add_f32_e32 v46, v47, v46
	v_mul_f32_e32 v43, v46, v43
	v_sub_u32_e32 v46, v171, v51
	v_cvt_f32_u32_e32 v47, v46
	v_cmp_lt_i32_e32 vcc, -1, v46
	v_mul_f32_e32 v47, v169, v47
	v_exp_f32_e32 v47, v47
	s_nop 0
	v_cndmask_b32_e32 v47, 0, v47, vcc
	v_cmp_gt_i32_e32 vcc, 1, v46
	v_sub_u32_e32 v46, 0, v46
	v_cvt_f32_u32_e32 v46, v46
	v_mul_f32_e32 v46, v170, v46
	v_exp_f32_e32 v46, v46
	s_nop 0
	v_cndmask_b32_e32 v46, 0, v46, vcc
	v_add_f32_e32 v46, v47, v46
	v_mul_f32_e32 v44, v46, v44
	v_sub_u32_e32 v46, v171, v52
	v_cvt_f32_u32_e32 v47, v46
	v_cmp_lt_i32_e32 vcc, -1, v46
	v_mul_f32_e32 v47, v169, v47
	v_exp_f32_e32 v47, v47
	s_nop 0
	v_cndmask_b32_e32 v47, 0, v47, vcc
	v_cmp_gt_i32_e32 vcc, 1, v46
	v_sub_u32_e32 v46, 0, v46
	v_cvt_f32_u32_e32 v46, v46
	v_mul_f32_e32 v46, v170, v46
	v_exp_f32_e32 v46, v46
	s_nop 0
	v_cndmask_b32_e32 v46, 0, v46, vcc
	v_add_f32_e32 v46, v47, v46
	v_mul_f32_e32 v45, v46, v45
	v_sub_u32_e32 v46, v171, v54
	v_cvt_f32_u32_e32 v47, v46
	v_cmp_lt_i32_e32 vcc, -1, v46
	v_mul_f32_e32 v47, v169, v47
	v_exp_f32_e32 v47, v47
	s_nop 0
	v_cndmask_b32_e32 v47, 0, v47, vcc
	v_cmp_gt_i32_e32 vcc, 1, v46
	v_sub_u32_e32 v46, 0, v46
	v_cvt_f32_u32_e32 v46, v46
	v_mul_f32_e32 v46, v170, v46
	v_exp_f32_e32 v46, v46
	s_nop 0
	v_cndmask_b32_e32 v46, 0, v46, vcc
	v_add_f32_e32 v46, v47, v46
	v_mul_f32_e32 v46, v46, v34
	v_sub_u32_e32 v34, v171, v53
	v_cvt_f32_u32_e32 v47, v34
	v_cmp_lt_i32_e32 vcc, -1, v34
	v_mfma_f32_16x16x32_bf16 v[50:53], v[14:17], v[38:41], v[66:69]
	v_mul_f32_e32 v47, v169, v47
	v_exp_f32_e32 v47, v47
	v_mfma_f32_16x16x32_bf16 v[66:69], v[6:9], v[38:41], v[78:81]
	v_cndmask_b32_e32 v47, 0, v47, vcc
	v_cmp_gt_i32_e32 vcc, 1, v34
	v_sub_u32_e32 v34, 0, v34
	v_cvt_f32_u32_e32 v34, v34
	v_mul_f32_e32 v34, v170, v34
	v_exp_f32_e32 v34, v34
	s_nop 0
	v_cndmask_b32_e32 v34, 0, v34, vcc
	v_add_f32_e32 v34, v47, v34
	v_mul_f32_e32 v47, v34, v35
	v_sub_u32_e32 v34, v171, v56
	v_cvt_f32_u32_e32 v35, v34
	v_cmp_lt_i32_e32 vcc, -1, v34
	v_mul_f32_e32 v35, v169, v35
	v_exp_f32_e32 v35, v35
	s_nop 0
	v_cndmask_b32_e32 v35, 0, v35, vcc
	v_cmp_gt_i32_e32 vcc, 1, v34
	v_sub_u32_e32 v34, 0, v34
	v_cvt_f32_u32_e32 v34, v34
	v_mul_f32_e32 v34, v170, v34
	v_exp_f32_e32 v34, v34
	s_nop 0
	v_cndmask_b32_e32 v34, 0, v34, vcc
	v_add_f32_e32 v34, v35, v34
	v_mul_f32_e32 v48, v34, v36
	v_sub_u32_e32 v34, v171, v57
	v_cvt_f32_u32_e32 v35, v34
	v_cmp_lt_i32_e32 vcc, -1, v34
	v_cvt_pk_bf16_f32 v36, v46, v47
	v_mul_f32_e32 v35, v169, v35
	v_exp_f32_e32 v35, v35
	s_nop 0
	v_cndmask_b32_e32 v35, 0, v35, vcc
	v_cmp_gt_i32_e32 vcc, 1, v34
	v_sub_u32_e32 v34, 0, v34
	v_cvt_f32_u32_e32 v34, v34
	v_mul_f32_e32 v34, v170, v34
	v_exp_f32_e32 v34, v34
	s_nop 0
	v_cndmask_b32_e32 v34, 0, v34, vcc
	v_add_f32_e32 v34, v35, v34
	v_mul_f32_e32 v37, v34, v37
	v_cvt_pk_bf16_f32 v34, v42, v43
	v_cvt_pk_bf16_f32 v35, v44, v45
	v_cvt_pk_bf16_f32 v37, v48, v37
	s_nop 1
	v_mfma_f32_16x16x32_bf16 v[54:57], v[14:17], v[34:37], v[62:65]
	v_mfma_f32_16x16x32_bf16 v[62:65], v[10:13], v[34:37], v[74:77]
	v_mfma_f32_16x16x32_bf16 v[70:73], v[6:9], v[34:37], v[98:101]
	v_mfma_f32_16x16x32_bf16 v[74:77], v[2:5], v[38:41], v[102:105]
	v_mfma_f32_16x16x32_bf16 v[78:81], v[2:5], v[34:37], v[106:109]
	global_load_dwordx4 v[34:37], v[112:113], off offset:192
	global_load_dwordx4 v[38:41], v[152:153], off offset:192
	global_load_dwordx4 v[42:45], v[154:155], off offset:192
	global_load_dwordx4 v[98:101], v[112:113], off offset:128
	global_load_dwordx4 v[102:105], v[152:153], off offset:128
	global_load_dwordx4 v[106:109], v[154:155], off offset:128
	global_load_dwordx4 v[46:49], v[110:111], off offset:192
	s_nop 0
	global_load_dwordx4 v[110:113], v[110:111], off offset:128
	s_nop 0
	global_load_dwordx4 v[2:5], v[156:157], off offset:192
	global_load_dwordx4 v[6:9], v[156:157], off offset:128
	global_load_dwordx4 v[10:13], v[156:157], off offset:64
	global_load_dwordx4 v[14:17], v[156:157], off
	v_mul_lo_u32 v154, v159, 12
	v_ashrrev_i32_e32 v155, 31, v154
	v_lshl_add_u64 v[152:153], v[154:155], 0, v[130:131]
	v_add_u32_e32 v154, 6, v154
	v_ashrrev_i32_e32 v155, 31, v154
	v_lshl_add_u64 v[130:131], v[154:155], 0, v[130:131]
	v_lshlrev_b64 v[152:153], 13, v[152:153]
	v_lshlrev_b32_e32 v156, 7, v158
	v_lshlrev_b64 v[130:131], 13, v[130:131]
	v_lshl_add_u64 v[160:161], v[132:133], 0, v[152:153]
	v_mov_b32_e32 v157, v1
	v_or_b32_e32 v172, 0x1000, v156
	v_or_b32_e32 v174, 0x1800, v156
	v_lshl_add_u64 v[130:131], v[132:133], 0, v[130:131]
	v_lshl_add_u64 v[152:153], v[160:161], 0, v[156:157]
	v_lshl_add_u64 v[158:159], v[160:161], 0, v[172:173]
	v_lshl_add_u64 v[162:163], v[160:161], 0, v[174:175]
	v_lshl_add_u64 v[154:155], v[130:131], 0, v[156:157]
	v_lshl_add_u64 v[156:157], v[130:131], 0, v[172:173]
	v_lshl_add_u64 v[160:161], v[130:131], 0, v[174:175]
	v_mfma_f32_16x16x32_bf16 v[130:133], v[126:129], v[30:33], 0
	v_or_b32_e32 v173, 64, v0
	v_or_b32_e32 v172, 0x44, v0
	s_waitcnt vmcnt(0)
	v_mfma_f32_16x16x32_bf16 v[126:129], v[126:129], v[26:29], 0
	v_mfma_f32_16x16x32_bf16 v[130:133], v[122:125], v[22:25], v[130:133]
	v_mfma_f32_16x16x32_bf16 v[122:125], v[122:125], v[18:21], v[126:129]
	v_mfma_f32_16x16x32_bf16 v[126:129], v[118:121], v[30:33], 0
	v_mfma_f32_16x16x32_bf16 v[118:121], v[118:121], v[26:29], 0
	v_mfma_f32_16x16x32_bf16 v[126:129], v[114:117], v[22:25], v[126:129]
	v_mfma_f32_16x16x32_bf16 v[114:117], v[114:117], v[18:21], v[118:121]
	s_nop 5
	v_sub_u32_e32 v118, v168, v173
	v_cvt_f32_u32_e32 v119, v118
	v_cmp_lt_i32_e32 vcc, -1, v118
	v_mul_f32_e32 v119, v169, v119
	v_exp_f32_e32 v119, v119
	s_nop 0
	v_cndmask_b32_e32 v119, 0, v119, vcc
	v_cmp_gt_i32_e32 vcc, 1, v118
	v_sub_u32_e32 v118, 0, v118
	v_cvt_f32_u32_e32 v118, v118
	v_mul_f32_e32 v118, v170, v118
	v_exp_f32_e32 v118, v118
	s_nop 0
	v_cndmask_b32_e32 v118, 0, v118, vcc
	v_add_f32_e32 v118, v119, v118
	v_mul_f32_e32 v118, v118, v130
	v_or_b32_e32 v130, 0x41, v0
	v_sub_u32_e32 v119, v168, v130
	v_cvt_f32_u32_e32 v120, v119
	v_cmp_lt_i32_e32 vcc, -1, v119
	v_mul_f32_e32 v120, v169, v120
	v_exp_f32_e32 v120, v120
	s_nop 0
	v_cndmask_b32_e32 v120, 0, v120, vcc
	v_cmp_gt_i32_e32 vcc, 1, v119
	v_sub_u32_e32 v119, 0, v119
	v_cvt_f32_u32_e32 v119, v119
	v_mul_f32_e32 v119, v170, v119
	v_exp_f32_e32 v119, v119
	s_nop 0
	v_cndmask_b32_e32 v119, 0, v119, vcc
	v_add_f32_e32 v119, v120, v119
	v_mul_f32_e32 v119, v119, v131
	v_or_b32_e32 v131, 0x42, v0
	v_sub_u32_e32 v120, v168, v131
	v_cvt_f32_u32_e32 v121, v120
	v_cmp_lt_i32_e32 vcc, -1, v120
	v_cvt_pk_bf16_f32 v118, v118, v119
	v_mul_f32_e32 v121, v169, v121
	v_exp_f32_e32 v121, v121
	s_nop 0
	v_cndmask_b32_e32 v121, 0, v121, vcc
	v_cmp_gt_i32_e32 vcc, 1, v120
	v_sub_u32_e32 v120, 0, v120
	v_cvt_f32_u32_e32 v120, v120
	v_mul_f32_e32 v120, v170, v120
	v_exp_f32_e32 v120, v120
	s_nop 0
	v_cndmask_b32_e32 v120, 0, v120, vcc
	v_add_f32_e32 v120, v121, v120
	v_mul_f32_e32 v120, v120, v132
	v_or_b32_e32 v132, 0x43, v0
	v_sub_u32_e32 v121, v168, v132
	v_cvt_f32_u32_e32 v174, v121
	v_cmp_lt_i32_e32 vcc, -1, v121
	v_mul_f32_e32 v174, v169, v174
	v_exp_f32_e32 v174, v174
	s_nop 0
	v_cndmask_b32_e32 v174, 0, v174, vcc
	v_cmp_gt_i32_e32 vcc, 1, v121
	v_sub_u32_e32 v121, 0, v121
	v_cvt_f32_u32_e32 v121, v121
	v_mul_f32_e32 v121, v170, v121
	v_exp_f32_e32 v121, v121
	s_nop 0
	v_cndmask_b32_e32 v121, 0, v121, vcc
	v_add_f32_e32 v121, v174, v121
	v_mul_f32_e32 v121, v121, v133
	v_sub_u32_e32 v133, v168, v172
	v_cvt_f32_u32_e32 v174, v133
	v_cmp_lt_i32_e32 vcc, -1, v133
	v_cvt_pk_bf16_f32 v119, v120, v121
	v_mul_f32_e32 v174, v169, v174
	v_exp_f32_e32 v174, v174
	s_nop 0
	v_cndmask_b32_e32 v174, 0, v174, vcc
	v_cmp_gt_i32_e32 vcc, 1, v133
	v_sub_u32_e32 v133, 0, v133
	v_cvt_f32_u32_e32 v133, v133
	v_mul_f32_e32 v133, v170, v133
	v_exp_f32_e32 v133, v133
	s_nop 0
	v_cndmask_b32_e32 v133, 0, v133, vcc
	v_add_f32_e32 v133, v174, v133
	v_mul_f32_e32 v133, v133, v126
	v_or_b32_e32 v126, 0x45, v0
	v_sub_u32_e32 v174, v168, v126
	v_cvt_f32_u32_e32 v175, v174
	v_cmp_lt_i32_e32 vcc, -1, v174
	v_mul_f32_e32 v175, v169, v175
	v_exp_f32_e32 v175, v175
	s_nop 0
	v_cndmask_b32_e32 v175, 0, v175, vcc
	v_cmp_gt_i32_e32 vcc, 1, v174
	v_sub_u32_e32 v174, 0, v174
	v_cvt_f32_u32_e32 v174, v174
	v_mul_f32_e32 v174, v170, v174
	v_exp_f32_e32 v174, v174
	s_nop 0
	v_cndmask_b32_e32 v174, 0, v174, vcc
	v_add_f32_e32 v174, v175, v174
	v_mul_f32_e32 v174, v174, v127
	v_or_b32_e32 v127, 0x46, v0
	v_sub_u32_e32 v175, v168, v127
	v_cvt_f32_u32_e32 v176, v175
	v_cmp_lt_i32_e32 vcc, -1, v175
	v_cvt_pk_bf16_f32 v120, v133, v174
	v_mul_f32_e32 v176, v169, v176
	v_exp_f32_e32 v176, v176
	s_nop 0
	v_cndmask_b32_e32 v176, 0, v176, vcc
	v_cmp_gt_i32_e32 vcc, 1, v175
	v_sub_u32_e32 v175, 0, v175
	v_cvt_f32_u32_e32 v175, v175
	v_mul_f32_e32 v175, v170, v175
	v_exp_f32_e32 v175, v175
	s_nop 0
	v_cndmask_b32_e32 v175, 0, v175, vcc
	v_add_f32_e32 v175, v176, v175
	v_mul_f32_e32 v175, v175, v128
	v_or_b32_e32 v128, 0x47, v0
	v_sub_u32_e32 v176, v168, v128
	v_cvt_f32_u32_e32 v177, v176
	v_cmp_lt_i32_e32 vcc, -1, v176
	v_mul_f32_e32 v177, v169, v177
	v_exp_f32_e32 v177, v177
	s_nop 0
	v_cndmask_b32_e32 v177, 0, v177, vcc
	v_cmp_gt_i32_e32 vcc, 1, v176
	v_sub_u32_e32 v176, 0, v176
	v_cvt_f32_u32_e32 v176, v176
	v_mul_f32_e32 v176, v170, v176
	v_exp_f32_e32 v176, v176
	s_nop 0
	v_cndmask_b32_e32 v176, 0, v176, vcc
	v_add_f32_e32 v176, v177, v176
	v_mul_f32_e32 v129, v176, v129
	v_cvt_pk_bf16_f32 v121, v175, v129
	v_sub_u32_e32 v129, v171, v173
	v_cvt_f32_u32_e32 v133, v129
	v_cmp_lt_i32_e32 vcc, -1, v129
	v_mfma_f32_16x16x32_bf16 v[74:77], v[98:101], v[118:121], v[74:77]
	v_mul_f32_e32 v133, v169, v133
	v_exp_f32_e32 v133, v133
	v_mfma_f32_16x16x32_bf16 v[66:69], v[102:105], v[118:121], v[66:69]
	v_cndmask_b32_e32 v133, 0, v133, vcc
	v_cmp_gt_i32_e32 vcc, 1, v129
	v_sub_u32_e32 v129, 0, v129
	v_cvt_f32_u32_e32 v129, v129
	v_mfma_f32_16x16x32_bf16 v[58:61], v[106:109], v[118:121], v[58:61]
	v_mul_f32_e32 v129, v170, v129
	v_exp_f32_e32 v129, v129
	v_mfma_f32_16x16x32_bf16 v[50:53], v[110:113], v[118:121], v[50:53]
	v_cndmask_b32_e32 v129, 0, v129, vcc
	v_add_f32_e32 v129, v133, v129
	v_mul_f32_e32 v122, v129, v122
	v_sub_u32_e32 v129, v171, v130
	v_cvt_f32_u32_e32 v130, v129
	v_cmp_lt_i32_e32 vcc, -1, v129
	v_mul_f32_e32 v130, v169, v130
	v_exp_f32_e32 v130, v130
	s_nop 0
	v_cndmask_b32_e32 v130, 0, v130, vcc
	v_cmp_gt_i32_e32 vcc, 1, v129
	v_sub_u32_e32 v129, 0, v129
	v_cvt_f32_u32_e32 v129, v129
	v_mul_f32_e32 v129, v170, v129
	v_exp_f32_e32 v129, v129
	s_nop 0
	v_cndmask_b32_e32 v129, 0, v129, vcc
	v_add_f32_e32 v129, v130, v129
	v_mul_f32_e32 v123, v129, v123
	v_sub_u32_e32 v129, v171, v131
	v_cvt_f32_u32_e32 v130, v129
	v_cmp_lt_i32_e32 vcc, -1, v129
	v_mul_f32_e32 v130, v169, v130
	v_exp_f32_e32 v130, v130
	s_nop 0
	v_cndmask_b32_e32 v130, 0, v130, vcc
	v_cmp_gt_i32_e32 vcc, 1, v129
	v_sub_u32_e32 v129, 0, v129
	v_cvt_f32_u32_e32 v129, v129
	v_mul_f32_e32 v129, v170, v129
	v_exp_f32_e32 v129, v129
	s_nop 0
	v_cndmask_b32_e32 v129, 0, v129, vcc
	v_add_f32_e32 v129, v130, v129
	v_mul_f32_e32 v124, v129, v124
	v_sub_u32_e32 v129, v171, v132
	v_cvt_f32_u32_e32 v130, v129
	v_cmp_lt_i32_e32 vcc, -1, v129
	v_mul_f32_e32 v130, v169, v130
	v_exp_f32_e32 v130, v130
	s_nop 0
	v_cndmask_b32_e32 v130, 0, v130, vcc
	v_cmp_gt_i32_e32 vcc, 1, v129
	v_sub_u32_e32 v129, 0, v129
	v_cvt_f32_u32_e32 v129, v129
	v_mul_f32_e32 v129, v170, v129
	v_exp_f32_e32 v129, v129
	s_nop 0
	v_cndmask_b32_e32 v129, 0, v129, vcc
	v_add_f32_e32 v129, v130, v129
	v_mul_f32_e32 v125, v129, v125
	v_sub_u32_e32 v129, v171, v172
	v_cvt_f32_u32_e32 v130, v129
	v_cmp_lt_i32_e32 vcc, -1, v129
	v_mul_f32_e32 v130, v169, v130
	v_exp_f32_e32 v130, v130
	s_nop 0
	v_cndmask_b32_e32 v130, 0, v130, vcc
	v_cmp_gt_i32_e32 vcc, 1, v129
	v_sub_u32_e32 v129, 0, v129
	v_cvt_f32_u32_e32 v129, v129
	v_mul_f32_e32 v129, v170, v129
	v_exp_f32_e32 v129, v129
	s_nop 0
	v_cndmask_b32_e32 v129, 0, v129, vcc
	v_add_f32_e32 v129, v130, v129
	v_mul_f32_e32 v129, v129, v114
	v_sub_u32_e32 v114, v171, v126
	v_cvt_f32_u32_e32 v126, v114
	v_cmp_lt_i32_e32 vcc, -1, v114
	v_mul_f32_e32 v126, v169, v126
	v_exp_f32_e32 v126, v126
	s_nop 0
	v_cndmask_b32_e32 v126, 0, v126, vcc
	v_cmp_gt_i32_e32 vcc, 1, v114
	v_sub_u32_e32 v114, 0, v114
	v_cvt_f32_u32_e32 v114, v114
	v_mul_f32_e32 v114, v170, v114
	v_exp_f32_e32 v114, v114
	s_nop 0
	v_cndmask_b32_e32 v114, 0, v114, vcc
	v_add_f32_e32 v114, v126, v114
	v_mul_f32_e32 v126, v114, v115
	v_sub_u32_e32 v114, v171, v127
	v_cvt_f32_u32_e32 v115, v114
	v_cmp_lt_i32_e32 vcc, -1, v114
	v_mul_f32_e32 v115, v169, v115
	v_exp_f32_e32 v115, v115
	s_nop 0
	v_cndmask_b32_e32 v115, 0, v115, vcc
	v_cmp_gt_i32_e32 vcc, 1, v114
	v_sub_u32_e32 v114, 0, v114
	v_cvt_f32_u32_e32 v114, v114
	v_mul_f32_e32 v114, v170, v114
	v_exp_f32_e32 v114, v114
	s_nop 0
	v_cndmask_b32_e32 v114, 0, v114, vcc
	v_add_f32_e32 v114, v115, v114
	v_mul_f32_e32 v127, v114, v116
	v_sub_u32_e32 v114, v171, v128
	v_cvt_f32_u32_e32 v115, v114
	v_cmp_lt_i32_e32 vcc, -1, v114
	v_cvt_pk_bf16_f32 v116, v129, v126
	v_mul_f32_e32 v115, v169, v115
	v_exp_f32_e32 v115, v115
	s_nop 0
	v_cndmask_b32_e32 v115, 0, v115, vcc
	v_cmp_gt_i32_e32 vcc, 1, v114
	v_sub_u32_e32 v114, 0, v114
	v_cvt_f32_u32_e32 v114, v114
	v_mul_f32_e32 v114, v170, v114
	v_exp_f32_e32 v114, v114
	s_nop 0
	v_cndmask_b32_e32 v114, 0, v114, vcc
	v_add_f32_e32 v114, v115, v114
	v_mul_f32_e32 v117, v114, v117
	v_cvt_pk_bf16_f32 v114, v122, v123
	v_cvt_pk_bf16_f32 v115, v124, v125
	v_cvt_pk_bf16_f32 v117, v127, v117
	s_nop 1
	s_nop 0
	v_mfma_f32_16x16x32_bf16 v[78:81], v[98:101], v[114:117], v[78:81]
	v_mfma_f32_16x16x32_bf16 v[98:101], v[94:97], v[30:33], 0
	v_mfma_f32_16x16x32_bf16 v[94:97], v[94:97], v[26:29], 0
	v_mfma_f32_16x16x32_bf16 v[98:101], v[90:93], v[22:25], v[98:101]
	v_mfma_f32_16x16x32_bf16 v[90:93], v[90:93], v[18:21], v[94:97]
	v_mfma_f32_16x16x32_bf16 v[94:97], v[86:89], v[30:33], 0
	v_mfma_f32_16x16x32_bf16 v[86:89], v[86:89], v[26:29], 0
	v_mfma_f32_16x16x32_bf16 v[70:73], v[102:105], v[114:117], v[70:73]
	v_or_b32_e32 v103, 0x60, v0
	v_or_b32_e32 v102, 0x64, v0
	v_mfma_f32_16x16x32_bf16 v[94:97], v[82:85], v[22:25], v[94:97]
	v_mfma_f32_16x16x32_bf16 v[82:85], v[82:85], v[18:21], v[86:89]
	s_nop 2
	v_sub_u32_e32 v86, v168, v103
	v_cvt_f32_u32_e32 v87, v86
	v_cmp_lt_i32_e32 vcc, -1, v86
	v_mfma_f32_16x16x32_bf16 v[62:65], v[106:109], v[114:117], v[62:65]
	v_mul_f32_e32 v87, v169, v87
	v_exp_f32_e32 v87, v87
	v_mfma_f32_16x16x32_bf16 v[54:57], v[110:113], v[114:117], v[54:57]
	v_cndmask_b32_e32 v87, 0, v87, vcc
	v_cmp_gt_i32_e32 vcc, 1, v86
	v_sub_u32_e32 v86, 0, v86
	v_cvt_f32_u32_e32 v86, v86
	v_mul_f32_e32 v86, v170, v86
	v_exp_f32_e32 v86, v86
	s_nop 0
	v_cndmask_b32_e32 v86, 0, v86, vcc
	v_add_f32_e32 v86, v87, v86
	v_mul_f32_e32 v86, v86, v98
	v_or_b32_e32 v98, 0x61, v0
	v_sub_u32_e32 v87, v168, v98
	v_cvt_f32_u32_e32 v88, v87
	v_cmp_lt_i32_e32 vcc, -1, v87
	v_mul_f32_e32 v88, v169, v88
	v_exp_f32_e32 v88, v88
	s_nop 0
	v_cndmask_b32_e32 v88, 0, v88, vcc
	v_cmp_gt_i32_e32 vcc, 1, v87
	v_sub_u32_e32 v87, 0, v87
	v_cvt_f32_u32_e32 v87, v87
	v_mul_f32_e32 v87, v170, v87
	v_exp_f32_e32 v87, v87
	s_nop 0
	v_cndmask_b32_e32 v87, 0, v87, vcc
	v_add_f32_e32 v87, v88, v87
	v_mul_f32_e32 v87, v87, v99
	v_or_b32_e32 v99, 0x62, v0
	v_sub_u32_e32 v88, v168, v99
	v_cvt_f32_u32_e32 v89, v88
	v_cmp_lt_i32_e32 vcc, -1, v88
	v_cvt_pk_bf16_f32 v86, v86, v87
	v_mul_f32_e32 v89, v169, v89
	v_exp_f32_e32 v89, v89
	s_nop 0
	v_cndmask_b32_e32 v89, 0, v89, vcc
	v_cmp_gt_i32_e32 vcc, 1, v88
	v_sub_u32_e32 v88, 0, v88
	v_cvt_f32_u32_e32 v88, v88
	v_mul_f32_e32 v88, v170, v88
	v_exp_f32_e32 v88, v88
	s_nop 0
	v_cndmask_b32_e32 v88, 0, v88, vcc
	v_add_f32_e32 v88, v89, v88
	v_mul_f32_e32 v88, v88, v100
	v_or_b32_e32 v100, 0x63, v0
	v_sub_u32_e32 v89, v168, v100
	v_cvt_f32_u32_e32 v104, v89
	v_cmp_lt_i32_e32 vcc, -1, v89
	v_mul_f32_e32 v104, v169, v104
	v_exp_f32_e32 v104, v104
	s_nop 0
	v_cndmask_b32_e32 v104, 0, v104, vcc
	v_cmp_gt_i32_e32 vcc, 1, v89
	v_sub_u32_e32 v89, 0, v89
	v_cvt_f32_u32_e32 v89, v89
	v_mul_f32_e32 v89, v170, v89
	v_exp_f32_e32 v89, v89
	s_nop 0
	v_cndmask_b32_e32 v89, 0, v89, vcc
	v_add_f32_e32 v89, v104, v89
	v_mul_f32_e32 v89, v89, v101
	v_sub_u32_e32 v101, v168, v102
	v_cvt_f32_u32_e32 v104, v101
	v_cmp_lt_i32_e32 vcc, -1, v101
	v_cvt_pk_bf16_f32 v87, v88, v89
	v_mul_f32_e32 v104, v169, v104
	v_exp_f32_e32 v104, v104
	s_nop 0
	v_cndmask_b32_e32 v104, 0, v104, vcc
	v_cmp_gt_i32_e32 vcc, 1, v101
	v_sub_u32_e32 v101, 0, v101
	v_cvt_f32_u32_e32 v101, v101
	v_mul_f32_e32 v101, v170, v101
	v_exp_f32_e32 v101, v101
	s_nop 0
	v_cndmask_b32_e32 v101, 0, v101, vcc
	v_add_f32_e32 v101, v104, v101
	v_mul_f32_e32 v101, v101, v94
	v_or_b32_e32 v94, 0x65, v0
	v_sub_u32_e32 v104, v168, v94
	v_cvt_f32_u32_e32 v105, v104
	v_cmp_lt_i32_e32 vcc, -1, v104
	v_sub_u32_e32 v94, v171, v94
	v_mul_f32_e32 v105, v169, v105
	v_exp_f32_e32 v105, v105
	s_nop 0
	v_cndmask_b32_e32 v105, 0, v105, vcc
	v_cmp_gt_i32_e32 vcc, 1, v104
	v_sub_u32_e32 v104, 0, v104
	v_cvt_f32_u32_e32 v104, v104
	v_mul_f32_e32 v104, v170, v104
	v_exp_f32_e32 v104, v104
	s_nop 0
	v_cndmask_b32_e32 v104, 0, v104, vcc
	v_add_f32_e32 v104, v105, v104
	v_mul_f32_e32 v104, v104, v95
	v_or_b32_e32 v95, 0x66, v0
	v_sub_u32_e32 v105, v168, v95
	v_cvt_f32_u32_e32 v106, v105
	v_cmp_lt_i32_e32 vcc, -1, v105
	v_cvt_pk_bf16_f32 v88, v101, v104
	v_mul_f32_e32 v106, v169, v106
	v_exp_f32_e32 v106, v106
	s_nop 0
	v_cndmask_b32_e32 v106, 0, v106, vcc
	v_cmp_gt_i32_e32 vcc, 1, v105
	v_sub_u32_e32 v105, 0, v105
	v_cvt_f32_u32_e32 v105, v105
	v_mul_f32_e32 v105, v170, v105
	v_exp_f32_e32 v105, v105
	s_nop 0
	v_cndmask_b32_e32 v105, 0, v105, vcc
	v_add_f32_e32 v105, v106, v105
	v_mul_f32_e32 v105, v105, v96
	v_or_b32_e32 v96, 0x67, v0
	v_sub_u32_e32 v106, v168, v96
	v_cvt_f32_u32_e32 v107, v106
	v_cmp_lt_i32_e32 vcc, -1, v106
	v_mul_f32_e32 v107, v169, v107
	v_exp_f32_e32 v107, v107
	s_nop 0
	v_cndmask_b32_e32 v107, 0, v107, vcc
	v_cmp_gt_i32_e32 vcc, 1, v106
	v_sub_u32_e32 v106, 0, v106
	v_cvt_f32_u32_e32 v106, v106
	v_mul_f32_e32 v106, v170, v106
	v_exp_f32_e32 v106, v106
	s_nop 0
	v_cndmask_b32_e32 v106, 0, v106, vcc
	v_add_f32_e32 v106, v107, v106
	v_mul_f32_e32 v97, v106, v97
	v_cvt_pk_bf16_f32 v89, v105, v97
	v_sub_u32_e32 v97, v171, v103
	v_cvt_f32_u32_e32 v101, v97
	v_cmp_lt_i32_e32 vcc, -1, v97
	v_mfma_f32_16x16x32_bf16 v[50:53], v[46:49], v[86:89], v[50:53]
	v_mul_f32_e32 v101, v169, v101
	v_exp_f32_e32 v101, v101
	v_mfma_f32_16x16x32_bf16 v[58:61], v[42:45], v[86:89], v[58:61]
	v_cndmask_b32_e32 v101, 0, v101, vcc
	v_cmp_gt_i32_e32 vcc, 1, v97
	v_sub_u32_e32 v97, 0, v97
	v_cvt_f32_u32_e32 v97, v97
	v_mul_f32_e32 v97, v170, v97
	v_exp_f32_e32 v97, v97
	s_nop 0
	v_cndmask_b32_e32 v97, 0, v97, vcc
	v_add_f32_e32 v97, v101, v97
	v_mul_f32_e32 v90, v97, v90
	v_sub_u32_e32 v97, v171, v98
	v_cvt_f32_u32_e32 v98, v97
	v_cmp_lt_i32_e32 vcc, -1, v97
	v_mul_f32_e32 v98, v169, v98
	v_exp_f32_e32 v98, v98
	s_nop 0
	v_cndmask_b32_e32 v98, 0, v98, vcc
	v_cmp_gt_i32_e32 vcc, 1, v97
	v_sub_u32_e32 v97, 0, v97
	v_cvt_f32_u32_e32 v97, v97
	v_mul_f32_e32 v97, v170, v97
	v_exp_f32_e32 v97, v97
	s_nop 0
	v_cndmask_b32_e32 v97, 0, v97, vcc
	v_add_f32_e32 v97, v98, v97
	v_mul_f32_e32 v91, v97, v91
	v_sub_u32_e32 v97, v171, v99
	v_cvt_f32_u32_e32 v98, v97
	v_cmp_lt_i32_e32 vcc, -1, v97
	v_cvt_pk_bf16_f32 v90, v90, v91
	v_mul_f32_e32 v98, v169, v98
	v_exp_f32_e32 v98, v98
	s_nop 0
	v_cndmask_b32_e32 v98, 0, v98, vcc
	v_cmp_gt_i32_e32 vcc, 1, v97
	v_sub_u32_e32 v97, 0, v97
	v_cvt_f32_u32_e32 v97, v97
	v_mul_f32_e32 v97, v170, v97
	v_exp_f32_e32 v97, v97
	s_nop 0
	v_cndmask_b32_e32 v97, 0, v97, vcc
	v_add_f32_e32 v97, v98, v97
	v_mul_f32_e32 v92, v97, v92
	v_sub_u32_e32 v97, v171, v100
	v_cvt_f32_u32_e32 v98, v97
	v_cmp_lt_i32_e32 vcc, -1, v97
	v_mul_f32_e32 v98, v169, v98
	v_exp_f32_e32 v98, v98
	s_nop 0
	v_cndmask_b32_e32 v98, 0, v98, vcc
	v_cmp_gt_i32_e32 vcc, 1, v97
	v_sub_u32_e32 v97, 0, v97
	v_cvt_f32_u32_e32 v97, v97
	v_mul_f32_e32 v97, v170, v97
	v_exp_f32_e32 v97, v97
	s_nop 0
	v_cndmask_b32_e32 v97, 0, v97, vcc
	v_add_f32_e32 v97, v98, v97
	v_mul_f32_e32 v93, v97, v93
	v_sub_u32_e32 v97, v171, v102
	v_cvt_f32_u32_e32 v98, v97
	v_cmp_lt_i32_e32 vcc, -1, v97
	v_cvt_pk_bf16_f32 v91, v92, v93
	v_mul_f32_e32 v98, v169, v98
	v_exp_f32_e32 v98, v98
	s_nop 0
	v_cndmask_b32_e32 v98, 0, v98, vcc
	v_cmp_gt_i32_e32 vcc, 1, v97
	v_sub_u32_e32 v97, 0, v97
	v_cvt_f32_u32_e32 v97, v97
	v_mul_f32_e32 v97, v170, v97
	v_exp_f32_e32 v97, v97
	s_nop 0
	v_cndmask_b32_e32 v97, 0, v97, vcc
	v_add_f32_e32 v97, v98, v97
	v_mul_f32_e32 v82, v97, v82
	v_cvt_f32_u32_e32 v97, v94
	v_cmp_lt_i32_e32 vcc, -1, v94
	v_mul_f32_e32 v97, v169, v97
	v_exp_f32_e32 v97, v97
	s_nop 0
	v_cndmask_b32_e32 v97, 0, v97, vcc
	v_cmp_gt_i32_e32 vcc, 1, v94
	v_sub_u32_e32 v94, 0, v94
	v_cvt_f32_u32_e32 v94, v94
	v_mul_f32_e32 v94, v170, v94
	v_exp_f32_e32 v94, v94
	s_nop 0
	v_cndmask_b32_e32 v94, 0, v94, vcc
	v_add_f32_e32 v94, v97, v94
	v_mul_f32_e32 v83, v94, v83
	v_sub_u32_e32 v94, v171, v95
	v_cvt_f32_u32_e32 v95, v94
	v_cmp_lt_i32_e32 vcc, -1, v94
	v_cvt_pk_bf16_f32 v92, v82, v83
	v_mul_f32_e32 v95, v169, v95
	v_exp_f32_e32 v95, v95
	s_nop 0
	v_cndmask_b32_e32 v95, 0, v95, vcc
	v_cmp_gt_i32_e32 vcc, 1, v94
	v_sub_u32_e32 v94, 0, v94
	v_cvt_f32_u32_e32 v94, v94
	v_mul_f32_e32 v94, v170, v94
	v_exp_f32_e32 v94, v94
	s_nop 0
	v_cndmask_b32_e32 v94, 0, v94, vcc
	v_add_f32_e32 v94, v95, v94
	v_mul_f32_e32 v84, v94, v84
	v_sub_u32_e32 v94, v171, v96
	v_cvt_f32_u32_e32 v95, v94
	v_cmp_lt_i32_e32 vcc, -1, v94
	v_mul_f32_e32 v95, v169, v95
	v_exp_f32_e32 v95, v95
	s_nop 0
	v_cndmask_b32_e32 v95, 0, v95, vcc
	v_cmp_gt_i32_e32 vcc, 1, v94
	v_sub_u32_e32 v94, 0, v94
	v_cvt_f32_u32_e32 v94, v94
	v_mul_f32_e32 v94, v170, v94
	v_exp_f32_e32 v94, v94
	s_nop 0
	v_cndmask_b32_e32 v94, 0, v94, vcc
	v_add_f32_e32 v94, v95, v94
	v_mul_f32_e32 v85, v94, v85
	v_cvt_pk_bf16_f32 v93, v84, v85
	v_cmp_lt_i32_e32 vcc, v210, v208
	v_mfma_f32_16x16x32_bf16 v[54:57], v[46:49], v[90:93], v[54:57]
	v_mfma_f32_16x16x32_bf16 v[62:65], v[42:45], v[90:93], v[62:65]
	v_mfma_f32_16x16x32_bf16 v[46:49], v[38:41], v[86:89], v[66:69]
	v_mfma_f32_16x16x32_bf16 v[66:69], v[38:41], v[90:93], v[70:73]
	v_mfma_f32_16x16x32_bf16 v[38:41], v[34:37], v[86:89], v[74:77]
	v_mfma_f32_16x16x32_bf16 v[70:73], v[34:37], v[90:93], v[78:81]
	global_load_dwordx4 v[34:37], v[162:163], off offset:64
	global_load_dwordx4 v[42:45], v[162:163], off
	global_load_dwordx4 v[74:77], v[158:159], off offset:64
	global_load_dwordx4 v[78:81], v[158:159], off
	global_load_dwordx4 v[82:85], v[152:153], off offset:2112
	global_load_dwordx4 v[86:89], v[152:153], off offset:2048
	global_load_dwordx4 v[90:93], v[152:153], off offset:64
	global_load_dwordx4 v[94:97], v[152:153], off
	global_load_dwordx4 v[98:101], v[160:161], off offset:64
	global_load_dwordx4 v[102:105], v[160:161], off
	global_load_dwordx4 v[106:109], v[156:157], off offset:64
	global_load_dwordx4 v[110:113], v[156:157], off
	global_load_dwordx4 v[114:117], v[154:155], off offset:2112
	global_load_dwordx4 v[118:121], v[154:155], off offset:2048
	global_load_dwordx4 v[122:125], v[154:155], off offset:64
	global_load_dwordx4 v[126:129], v[154:155], off
	s_waitcnt vmcnt(0)
	s_nop 0
	v_mfma_f32_16x16x32_bf16 v[130:133], v[94:97], v[30:33], 0
	v_mfma_f32_16x16x32_bf16 v[94:97], v[94:97], v[26:29], 0
	v_mfma_f32_16x16x32_bf16 v[130:133], v[90:93], v[22:25], v[130:133]
	v_mfma_f32_16x16x32_bf16 v[90:93], v[90:93], v[18:21], v[94:97]
	v_mfma_f32_16x16x32_bf16 v[94:97], v[86:89], v[30:33], 0
	v_mfma_f32_16x16x32_bf16 v[86:89], v[86:89], v[26:29], 0
	v_mfma_f32_16x16x32_bf16 v[94:97], v[82:85], v[22:25], v[94:97]
	v_mfma_f32_16x16x32_bf16 v[82:85], v[82:85], v[18:21], v[86:89]
	v_mfma_f32_16x16x32_bf16 v[86:89], v[78:81], v[30:33], 0
	v_mfma_f32_16x16x32_bf16 v[78:81], v[78:81], v[26:29], 0
	v_mfma_f32_16x16x32_bf16 v[86:89], v[74:77], v[22:25], v[86:89]
	v_mfma_f32_16x16x32_bf16 v[74:77], v[74:77], v[18:21], v[78:81]
	v_mfma_f32_16x16x32_bf16 v[78:81], v[42:45], v[30:33], 0
	v_mfma_f32_16x16x32_bf16 v[42:45], v[42:45], v[26:29], 0
	v_mfma_f32_16x16x32_bf16 v[78:81], v[34:37], v[22:25], v[78:81]
	v_mfma_f32_16x16x32_bf16 v[152:155], v[34:37], v[18:21], v[42:45]
	v_mfma_f32_16x16x32_bf16 v[34:37], v[126:129], v[30:33], 0
	v_mfma_f32_16x16x32_bf16 v[42:45], v[126:129], v[26:29], 0
	v_mfma_f32_16x16x32_bf16 v[126:129], v[122:125], v[22:25], v[34:37]
	v_mfma_f32_16x16x32_bf16 v[122:125], v[122:125], v[18:21], v[42:45]
	v_mfma_f32_16x16x32_bf16 v[34:37], v[118:121], v[30:33], 0
	v_mfma_f32_16x16x32_bf16 v[42:45], v[118:121], v[26:29], 0
	v_mfma_f32_16x16x32_bf16 v[118:121], v[114:117], v[22:25], v[34:37]
	v_mfma_f32_16x16x32_bf16 v[114:117], v[114:117], v[18:21], v[42:45]
	v_mfma_f32_16x16x32_bf16 v[34:37], v[110:113], v[30:33], 0
	v_mfma_f32_16x16x32_bf16 v[42:45], v[110:113], v[26:29], 0
	v_mfma_f32_16x16x32_bf16 v[30:33], v[102:105], v[30:33], 0
	v_mfma_f32_16x16x32_bf16 v[26:29], v[102:105], v[26:29], 0
	v_mfma_f32_16x16x32_bf16 v[34:37], v[106:109], v[22:25], v[34:37]
	v_mfma_f32_16x16x32_bf16 v[106:109], v[106:109], v[18:21], v[42:45]
	v_mfma_f32_16x16x32_bf16 v[22:25], v[98:101], v[22:25], v[30:33]
	v_mfma_f32_16x16x32_bf16 v[98:101], v[98:101], v[18:21], v[26:29]
	v_sub_u32_e32 v18, 0x80, v171
	v_cvt_f32_ubyte0_e32 v18, v18
	v_mul_f32_e32 v18, v170, v18
	s_nop 0
	v_exp_f32_e32 v28, v18
	v_add_u32_e32 v18, 1, v168
	v_cvt_f32_ubyte0_e32 v18, v18
	v_mul_f32_e32 v18, v169, v18
	v_exp_f32_e32 v18, v18
	s_nop 0
	v_pk_fma_f32 v[20:21], v[18:19], v[80:81], v[40:41] op_sel_hi:[0,1,1]
	v_pk_fma_f32 v[26:27], v[18:19], v[78:79], v[38:39] op_sel_hi:[0,1,1]
	v_sub_u32_e32 v19, 0x80, v168
	v_cvt_f32_ubyte0_e32 v19, v19
	v_mul_f32_e32 v19, v170, v19
	v_exp_f32_e32 v30, v19
	s_nop 0
	v_pk_fma_f32 v[42:43], v[30:31], v[24:25], v[20:21] op_sel_hi:[0,1,1]
	v_pk_fma_f32 v[20:21], v[18:19], v[88:89], v[48:49] op_sel_hi:[0,1,1]
	v_pk_fma_f32 v[44:45], v[30:31], v[22:23], v[26:27] op_sel_hi:[0,1,1]
	v_pk_fma_f32 v[22:23], v[18:19], v[86:87], v[46:47] op_sel_hi:[0,1,1]
	v_pk_fma_f32 v[46:47], v[30:31], v[36:37], v[20:21] op_sel_hi:[0,1,1]
	v_pk_fma_f32 v[20:21], v[18:19], v[96:97], v[60:61] op_sel_hi:[0,1,1]
	v_pk_fma_f32 v[48:49], v[30:31], v[34:35], v[22:23] op_sel_hi:[0,1,1]
	v_pk_fma_f32 v[22:23], v[18:19], v[94:95], v[58:59] op_sel_hi:[0,1,1]
	v_pk_fma_f32 v[34:35], v[30:31], v[120:121], v[20:21] op_sel_hi:[0,1,1]
	v_pk_fma_f32 v[20:21], v[18:19], v[132:133], v[52:53] op_sel_hi:[0,1,1]
	v_pk_fma_f32 v[18:19], v[18:19], v[130:131], v[50:51] op_sel_hi:[0,1,1]
	v_pk_fma_f32 v[40:41], v[30:31], v[126:127], v[18:19] op_sel_hi:[0,1,1]
	v_add_u32_e32 v18, 17, v168
	v_cvt_f32_ubyte0_e32 v18, v18
	v_mul_f32_e32 v18, v169, v18
	v_exp_f32_e32 v18, v18
	v_pk_fma_f32 v[36:37], v[30:31], v[118:119], v[22:23] op_sel_hi:[0,1,1]
	v_pk_fma_f32 v[38:39], v[30:31], v[128:129], v[20:21] op_sel_hi:[0,1,1]
	v_and_b32_e32 v58, 0xffff0000, v151
	v_pk_fma_f32 v[26:27], v[18:19], v[154:155], v[72:73] op_sel_hi:[0,1,1]
	v_pk_fma_f32 v[50:51], v[18:19], v[152:153], v[70:71] op_sel_hi:[0,1,1]
	v_pk_fma_f32 v[30:31], v[18:19], v[76:77], v[68:69] op_sel_hi:[0,1,1]
	v_pk_fma_f32 v[32:33], v[18:19], v[74:75], v[66:67] op_sel_hi:[0,1,1]
	v_pk_fma_f32 v[20:21], v[18:19], v[84:85], v[64:65] op_sel_hi:[0,1,1]
	v_pk_fma_f32 v[52:53], v[18:19], v[82:83], v[62:63] op_sel_hi:[0,1,1]
	v_pk_fma_f32 v[22:23], v[18:19], v[92:93], v[56:57] op_sel_hi:[0,1,1]
	v_pk_fma_f32 v[18:19], v[18:19], v[90:91], v[54:55] op_sel_hi:[0,1,1]
	v_pk_fma_f32 v[22:23], v[28:29], v[124:125], v[22:23] op_sel_hi:[0,1,1]
	v_pk_fma_f32 v[24:25], v[28:29], v[122:123], v[18:19] op_sel_hi:[0,1,1]
	v_pk_fma_f32 v[18:19], v[28:29], v[116:117], v[20:21] op_sel_hi:[0,1,1]
	v_pk_fma_f32 v[20:21], v[28:29], v[114:115], v[52:53] op_sel_hi:[0,1,1]
	v_pk_fma_f32 v[30:31], v[28:29], v[108:109], v[30:31] op_sel_hi:[0,1,1]
	v_pk_fma_f32 v[32:33], v[28:29], v[106:107], v[32:33] op_sel_hi:[0,1,1]
	v_pk_fma_f32 v[26:27], v[28:29], v[100:101], v[26:27] op_sel_hi:[0,1,1]
	v_pk_fma_f32 v[28:29], v[28:29], v[98:99], v[50:51] op_sel_hi:[0,1,1]
	v_cndmask_b32_e32 v50, v207, v210, vcc
	v_cmp_lt_i32_e32 vcc, v209, v208
	v_lshlrev_b32_e32 v54, 2, v50
	v_mov_b32_e32 v51, v36
	v_cndmask_b32_e32 v50, v207, v209, vcc
	v_lshlrev_b32_e32 v55, 2, v50
	v_mov_b32_e32 v50, v40
	v_mov_b32_e32 v52, v41
	v_mov_b32_e32 v53, v37
	v_pk_add_f32 v[50:51], v[50:51], v[52:53]
	v_mov_b32_e32 v52, v38
	v_mov_b32_e32 v53, v34
	v_pk_add_f32 v[50:51], v[52:53], v[50:51]
	v_mov_b32_e32 v52, v39
	v_mov_b32_e32 v53, v35
	v_pk_add_f32 v[50:51], v[52:53], v[50:51]
	v_mov_b32_e32 v52, v49
	v_add_f32_e32 v50, 0, v50
	v_add_f32_e32 v56, v50, v51
	v_mov_b32_e32 v50, v48
	v_mov_b32_e32 v51, v44
	v_mov_b32_e32 v53, v45
	v_pk_add_f32 v[50:51], v[50:51], v[52:53]
	v_mov_b32_e32 v52, v46
	v_mov_b32_e32 v53, v42
	v_pk_add_f32 v[50:51], v[52:53], v[50:51]
	v_mov_b32_e32 v52, v47
	v_mov_b32_e32 v53, v43
	v_pk_add_f32 v[50:51], v[52:53], v[50:51]
	v_lshlrev_b32_e32 v57, 16, v151
	v_add_f32_e32 v50, v56, v50
	v_add_f32_e32 v50, v50, v51
	ds_bpermute_b32 v51, v54, v50
	s_waitcnt lgkmcnt(0)
	v_add_f32_e32 v50, v50, v51
	ds_bpermute_b32 v51, v55, v50
	s_waitcnt lgkmcnt(0)
	v_add_f32_e32 v51, v50, v51
	v_fmac_f32_e32 v41, 0xbc800000, v51
	v_fmamk_f32 v40, v51, 0xbc800000, v40
	v_mul_f32_e32 v56, v41, v41
	v_fmac_f32_e32 v56, v40, v40
	v_fmamk_f32 v38, v51, 0xbc800000, v38
	v_fmac_f32_e32 v56, v38, v38
	v_fmac_f32_e32 v39, 0xbc800000, v51
	v_fmac_f32_e32 v56, v39, v39
	v_fmamk_f32 v36, v51, 0xbc800000, v36
	v_fmac_f32_e32 v56, v36, v36
	v_fmac_f32_e32 v37, 0xbc800000, v51
	v_mul_f32_e32 v50, 0x3c800000, v51
	v_fmac_f32_e32 v56, v37, v37
	v_fmamk_f32 v34, v51, 0xbc800000, v34
	v_fmac_f32_e32 v56, v34, v34
	v_fmac_f32_e32 v35, 0xbc800000, v51
	v_pk_add_f32 v[48:49], v[48:49], v[50:51] op_sel_hi:[1,0] neg_lo:[0,1] neg_hi:[0,1]
	v_fmac_f32_e32 v56, v35, v35
	v_pk_mul_f32 v[52:53], v[48:49], v[48:49]
	s_nop 0
	v_add_f32_e32 v51, v52, v56
	v_add_f32_e32 v51, v53, v51
	v_pk_add_f32 v[46:47], v[46:47], v[50:51] op_sel_hi:[1,0] neg_lo:[0,1] neg_hi:[0,1]
	v_and_b32_e32 v56, 0xffff0000, v150
	v_pk_mul_f32 v[52:53], v[46:47], v[46:47]
	s_nop 0
	v_add_f32_e32 v51, v52, v51
	v_add_f32_e32 v51, v53, v51
	v_pk_add_f32 v[44:45], v[44:45], v[50:51] op_sel_hi:[1,0] neg_lo:[0,1] neg_hi:[0,1]
	s_nop 0
	v_pk_mul_f32 v[52:53], v[44:45], v[44:45]
	s_nop 0
	v_add_f32_e32 v51, v52, v51
	v_pk_add_f32 v[42:43], v[42:43], v[50:51] op_sel_hi:[1,0] neg_lo:[0,1] neg_hi:[0,1]
	v_add_f32_e32 v52, v53, v51
	v_pk_mul_f32 v[50:51], v[42:43], v[42:43]
	v_lshlrev_b32_e32 v53, 16, v150
	v_add_f32_e32 v50, v50, v52
	v_add_f32_e32 v50, v51, v50
	ds_bpermute_b32 v51, v54, v50
	s_waitcnt lgkmcnt(0)
	v_add_f32_e32 v50, v50, v51
	ds_bpermute_b32 v51, v55, v50
	s_waitcnt lgkmcnt(0)
	v_add_f32_e32 v50, v50, v51
	v_fmamk_f32 v50, v50, 0x3c800000, v203
	v_cmp_gt_f32_e32 vcc, s28, v50
	v_mul_f32_e32 v51, 0x4b800000, v50
	s_nop 0
	v_cndmask_b32_e32 v50, v50, v51, vcc
	v_rsq_f32_e32 v50, v50
	s_nop 0
	v_mul_f32_e32 v51, 0x45800000, v50
	v_cndmask_b32_e32 v52, v50, v51, vcc
	v_cmp_gt_i32_e32 vcc, s37, v167
	v_mul_f32_e32 v40, v40, v52
	v_mul_f32_e32 v38, v38, v52
	v_cndmask_b32_e64 v50, 3, 1, vcc
	v_add_u32_e32 v50, v50, v167
	v_ashrrev_i32_e32 v51, 31, v50
	v_lshlrev_b64 v[50:51], 11, v[50:51]
	v_mul_f32_e32 v40, v14, v40
	v_mul_f32_e32 v41, v41, v52
	v_mul_f32_e32 v38, v16, v38
	v_lshl_add_u64 v[50:51], s[8:9], 0, v[50:51]
	v_mul_f32_e32 v40, v40, v53
	v_mul_f32_e32 v41, v15, v41
	v_mul_f32_e32 v53, v38, v57
	v_mul_f32_e32 v38, v39, v52
	v_lshl_add_u64 v[50:51], v[50:51], 0, v[134:135]
	v_mul_f32_e32 v41, v41, v56
	v_mul_f32_e32 v38, v17, v38
	v_mul_f32_e32 v39, v38, v58
	v_cvt_pk_bf16_f32 v38, v40, v41
	v_lshl_add_u64 v[40:41], v[50:51], 0, v[0:1]
	v_lshl_add_u64 v[50:51], v[40:41], 0, s[54:55]
	v_add_co_u32_e32 v40, vcc, s34, v40
	v_mul_f32_e32 v36, v36, v52
	s_nop 0
	v_addc_co_u32_e32 v41, vcc, 0, v41, vcc
	v_mul_f32_e32 v34, v34, v52
	v_cvt_pk_bf16_f32 v39, v53, v39
	global_store_dwordx2 v[40:41], v[38:39], off offset:1280
	v_lshlrev_b32_e32 v38, 16, v148
	v_lshlrev_b32_e32 v40, 16, v149
	v_mul_f32_e32 v36, v10, v36
	v_mul_f32_e32 v34, v12, v34
	v_mul_f32_e32 v36, v36, v38
	v_mul_f32_e32 v38, v34, v40
	v_mul_f32_e32 v34, v35, v52
	v_and_b32_e32 v41, 0xffff0000, v149
	v_mul_f32_e32 v37, v37, v52
	v_mul_f32_e32 v34, v13, v34
	v_and_b32_e32 v39, 0xffff0000, v148
	v_mul_f32_e32 v37, v11, v37
	v_mul_f32_e32 v35, v34, v41
	v_mul_f32_e32 v37, v37, v39
	v_cvt_pk_bf16_f32 v34, v36, v37
	v_cvt_pk_bf16_f32 v35, v38, v35
	v_mul_f32_e32 v38, v48, v52
	global_store_dwordx2 v[50:51], v[34:35], off offset:32
	v_lshlrev_b32_e32 v34, 16, v146
	v_mul_f32_e32 v38, v6, v38
	v_mul_f32_e32 v34, v38, v34
	v_mul_f32_e32 v38, v49, v52
	v_and_b32_e32 v35, 0xffff0000, v146
	v_mul_f32_e32 v38, v7, v38
	v_mul_f32_e32 v35, v38, v35
	v_mul_f32_e32 v38, v46, v52
	v_lshlrev_b32_e32 v36, 16, v147
	v_mul_f32_e32 v38, v8, v38
	v_mul_f32_e32 v36, v38, v36
	v_mul_f32_e32 v38, v47, v52
	v_and_b32_e32 v37, 0xffff0000, v147
	v_mul_f32_e32 v38, v9, v38
	v_mul_f32_e32 v37, v38, v37
	v_cvt_pk_bf16_f32 v34, v34, v35
	v_mul_f32_e32 v38, v44, v52
	v_cvt_pk_bf16_f32 v35, v36, v37
	global_store_dwordx2 v[50:51], v[34:35], off offset:64
	v_lshlrev_b32_e32 v34, 16, v144
	v_mul_f32_e32 v38, v2, v38
	v_mul_f32_e32 v34, v38, v34
	v_mul_f32_e32 v38, v45, v52
	v_and_b32_e32 v35, 0xffff0000, v144
	v_mul_f32_e32 v38, v3, v38
	v_mul_f32_e32 v35, v38, v35
	v_mul_f32_e32 v38, v42, v52
	v_lshlrev_b32_e32 v36, 16, v145
	v_mul_f32_e32 v38, v4, v38
	v_mul_f32_e32 v36, v38, v36
	v_mul_f32_e32 v38, v43, v52
	v_and_b32_e32 v37, 0xffff0000, v145
	v_mul_f32_e32 v38, v5, v38
	v_mul_f32_e32 v37, v38, v37
	v_cvt_pk_bf16_f32 v34, v34, v35
	v_cvt_pk_bf16_f32 v35, v36, v37
	global_store_dwordx2 v[50:51], v[34:35], off offset:96
	v_mov_b32_e32 v34, v24
	v_mov_b32_e32 v35, v20
	v_mov_b32_e32 v36, v25
	v_mov_b32_e32 v37, v21
	v_pk_add_f32 v[34:35], v[34:35], v[36:37]
	v_mov_b32_e32 v36, v22
	v_mov_b32_e32 v37, v18
	v_pk_add_f32 v[34:35], v[36:37], v[34:35]
	v_mov_b32_e32 v36, v23
	v_mov_b32_e32 v37, v19
	v_pk_add_f32 v[34:35], v[36:37], v[34:35]
	v_mov_b32_e32 v36, v33
	v_add_f32_e32 v34, 0, v34
	v_add_f32_e32 v38, v34, v35
	v_mov_b32_e32 v34, v32
	v_mov_b32_e32 v35, v28
	v_mov_b32_e32 v37, v29
	v_pk_add_f32 v[34:35], v[34:35], v[36:37]
	v_mov_b32_e32 v36, v30
	v_mov_b32_e32 v37, v26
	v_pk_add_f32 v[34:35], v[36:37], v[34:35]
	v_mov_b32_e32 v36, v31
	v_mov_b32_e32 v37, v27
	v_pk_add_f32 v[34:35], v[36:37], v[34:35]
	v_lshlrev_b32_e32 v39, 16, v143
	v_add_f32_e32 v34, v38, v34
	v_add_f32_e32 v34, v34, v35
	ds_bpermute_b32 v35, v54, v34
	v_and_b32_e32 v40, 0xffff0000, v143
	s_waitcnt lgkmcnt(0)
	v_add_f32_e32 v34, v34, v35
	ds_bpermute_b32 v35, v55, v34
	s_waitcnt lgkmcnt(0)
	v_add_f32_e32 v35, v34, v35
	v_fmac_f32_e32 v25, 0xbc800000, v35
	v_fmamk_f32 v24, v35, 0xbc800000, v24
	v_mul_f32_e32 v38, v25, v25
	v_fmac_f32_e32 v38, v24, v24
	v_fmamk_f32 v22, v35, 0xbc800000, v22
	v_fmac_f32_e32 v38, v22, v22
	v_fmac_f32_e32 v23, 0xbc800000, v35
	v_fmac_f32_e32 v38, v23, v23
	v_fmamk_f32 v20, v35, 0xbc800000, v20
	v_fmac_f32_e32 v38, v20, v20
	v_fmac_f32_e32 v21, 0xbc800000, v35
	v_mul_f32_e32 v34, 0x3c800000, v35
	v_fmac_f32_e32 v38, v21, v21
	v_fmamk_f32 v18, v35, 0xbc800000, v18
	v_fmac_f32_e32 v38, v18, v18
	v_fmac_f32_e32 v19, 0xbc800000, v35
	v_pk_add_f32 v[32:33], v[32:33], v[34:35] op_sel_hi:[1,0] neg_lo:[0,1] neg_hi:[0,1]
	v_fmac_f32_e32 v38, v19, v19
	v_pk_mul_f32 v[36:37], v[32:33], v[32:33]
	s_nop 0
	v_add_f32_e32 v35, v36, v38
	v_add_f32_e32 v35, v37, v35
	v_pk_add_f32 v[30:31], v[30:31], v[34:35] op_sel_hi:[1,0] neg_lo:[0,1] neg_hi:[0,1]
	v_and_b32_e32 v38, 0xffff0000, v142
	v_pk_mul_f32 v[36:37], v[30:31], v[30:31]
	s_nop 0
	v_add_f32_e32 v35, v36, v35
	v_add_f32_e32 v35, v37, v35
	v_pk_add_f32 v[28:29], v[28:29], v[34:35] op_sel_hi:[1,0] neg_lo:[0,1] neg_hi:[0,1]
	s_nop 0
	v_pk_mul_f32 v[36:37], v[28:29], v[28:29]
	s_nop 0
	v_add_f32_e32 v35, v36, v35
	v_pk_add_f32 v[26:27], v[26:27], v[34:35] op_sel_hi:[1,0] neg_lo:[0,1] neg_hi:[0,1]
	v_add_f32_e32 v36, v37, v35
	v_pk_mul_f32 v[34:35], v[26:27], v[26:27]
	v_lshlrev_b32_e32 v37, 16, v142
	v_add_f32_e32 v34, v34, v36
	v_add_f32_e32 v34, v35, v34
	ds_bpermute_b32 v35, v54, v34
	s_waitcnt lgkmcnt(0)
	v_add_f32_e32 v34, v34, v35
	ds_bpermute_b32 v35, v55, v34
	s_waitcnt lgkmcnt(0)
	v_add_f32_e32 v34, v34, v35
	v_fmamk_f32 v34, v34, 0x3c800000, v203
	v_cmp_gt_f32_e32 vcc, s28, v34
	v_mul_f32_e32 v35, 0x4b800000, v34
	s_nop 0
	v_cndmask_b32_e32 v34, v34, v35, vcc
	v_rsq_f32_e32 v34, v34
	s_nop 0
	v_mul_f32_e32 v35, 0x45800000, v34
	v_cndmask_b32_e32 v36, v34, v35, vcc
	v_cmp_gt_i32_e32 vcc, s37, v166
	v_mul_f32_e32 v24, v24, v36
	v_mul_f32_e32 v22, v22, v36
	v_cndmask_b32_e64 v34, 3, 1, vcc
	v_add_u32_e32 v34, v34, v166
	v_ashrrev_i32_e32 v35, 31, v34
	v_lshlrev_b64 v[34:35], 11, v[34:35]
	v_mul_f32_e32 v14, v14, v24
	v_mul_f32_e32 v24, v25, v36
	v_mul_f32_e32 v16, v16, v22
	v_mul_f32_e32 v22, v23, v36
	v_lshl_add_u64 v[34:35], s[8:9], 0, v[34:35]
	v_mul_f32_e32 v15, v15, v24
	v_mul_f32_e32 v17, v17, v22
	v_lshl_add_u64 v[34:35], v[34:35], 0, v[134:135]
	v_mul_f32_e32 v14, v14, v37
	v_mul_f32_e32 v15, v15, v38
	v_mul_f32_e32 v16, v16, v39
	v_mul_f32_e32 v17, v17, v40
	v_cvt_pk_bf16_f32 v14, v14, v15
	v_cvt_pk_bf16_f32 v15, v16, v17
	v_lshl_add_u64 v[16:17], v[34:35], 0, v[0:1]
	v_lshl_add_u64 v[22:23], v[16:17], 0, s[54:55]
	v_add_co_u32_e32 v16, vcc, s34, v16
	v_lshlrev_b32_e32 v0, 16, v140
	s_nop 0
	v_addc_co_u32_e32 v17, vcc, 0, v17, vcc
	global_store_dwordx2 v[16:17], v[14:15], off offset:1280
	v_mul_f32_e32 v17, v20, v36
	v_mul_f32_e32 v10, v10, v17
	v_mul_f32_e32 v0, v10, v0
	v_mul_f32_e32 v10, v21, v36
	v_mul_f32_e32 v10, v11, v10
	v_mul_f32_e32 v11, v18, v36
	v_and_b32_e32 v14, 0xffff0000, v140
	v_mul_f32_e32 v11, v12, v11
	v_mul_f32_e32 v12, v19, v36
	v_mul_f32_e32 v10, v10, v14
	v_mul_f32_e32 v12, v13, v12
	v_mul_f32_e32 v13, v32, v36
	v_cvt_pk_bf16_f32 v10, v0, v10
	v_lshlrev_b32_e32 v0, 16, v138
	v_mul_f32_e32 v6, v6, v13
	v_lshlrev_b32_e32 v15, 16, v141
	v_mul_f32_e32 v0, v6, v0
	v_mul_f32_e32 v6, v33, v36
	v_and_b32_e32 v16, 0xffff0000, v141
	v_mul_f32_e32 v11, v11, v15
	v_mul_f32_e32 v6, v7, v6
	v_mul_f32_e32 v7, v30, v36
	v_mul_f32_e32 v12, v12, v16
	v_cvt_pk_bf16_f32 v11, v11, v12
	global_store_dwordx2 v[22:23], v[10:11], off offset:32
	v_and_b32_e32 v10, 0xffff0000, v138
	v_mul_f32_e32 v7, v8, v7
	v_mul_f32_e32 v8, v31, v36
	v_mul_f32_e32 v6, v6, v10
	v_mul_f32_e32 v8, v9, v8
	v_mul_f32_e32 v9, v28, v36
	v_lshlrev_b32_e32 v11, 16, v139
	v_cvt_pk_bf16_f32 v6, v0, v6
	v_lshlrev_b32_e32 v0, 16, v136
	v_mul_f32_e32 v2, v2, v9
	v_and_b32_e32 v12, 0xffff0000, v139
	v_mul_f32_e32 v7, v7, v11
	v_mul_f32_e32 v0, v2, v0
	v_mul_f32_e32 v2, v29, v36
	v_mul_f32_e32 v8, v8, v12
	v_cvt_pk_bf16_f32 v7, v7, v8
	v_mul_f32_e32 v2, v3, v2
	v_mul_f32_e32 v3, v26, v36
	global_store_dwordx2 v[22:23], v[6:7], off offset:64
	v_and_b32_e32 v6, 0xffff0000, v136
	v_lshlrev_b32_e32 v7, 16, v137
	v_mul_f32_e32 v3, v4, v3
	v_mul_f32_e32 v4, v27, v36
	v_cmp_le_i32_e32 vcc, s2, v164
	v_and_b32_e32 v8, 0xffff0000, v137
	v_mul_f32_e32 v2, v2, v6
	v_mul_f32_e32 v3, v3, v7
	v_mul_f32_e32 v4, v5, v4
	s_or_b64 s[40:41], vcc, s[40:41]
	v_mul_f32_e32 v4, v4, v8
	v_cvt_pk_bf16_f32 v2, v0, v2
	v_cvt_pk_bf16_f32 v3, v3, v4
	global_store_dwordx2 v[22:23], v[2:3], off offset:96
	s_andn2_b64 exec, exec, s[40:41]
	s_cbranch_execnz .LBB0_149

.LBB0_182:
	s_add_i32 s91, s2, 2
	s_add_u32 s12, s34, 0x80
	s_addc_u32 s3, s35, 0
	s_add_i32 s13, 0, 0x10000
	v_add_u32_e32 v142, s13, v183
	ds_read_b128 v[130:133], v142
	ds_read_b128 v[134:137], v142 offset:1024
	ds_read_b128 v[138:141], v142 offset:2048
	ds_read_b128 v[142:145], v142 offset:3072
	s_cmp_eq_u32 s88, s2
	s_cselect_b32 s2, s0, s12
	s_cselect_b32 s3, s1, s3
	s_cselect_b32 s43, s41, s90
	s_cselect_b32 s42, s40, s89
	v_lshl_add_u64 v[190:191], s[34:35], 0, v[174:175]
	s_add_i32 m0, s55, 0xc000
	ds_read_b128 v[146:149], v184
	ds_read_b128 v[150:153], v184 offset:1024
	ds_read_b128 v[154:157], v184 offset:2048
	ds_read_b128 v[158:161], v184 offset:3072
	ds_read_b128 v[162:165], v184 offset:4096
	ds_read_b128 v[166:169], v184 offset:5120
	ds_read_b128 v[178:181], v184 offset:6144
	ds_read_b128 v[186:189], v184 offset:7168
	global_load_lds_dwordx4 v[190:191], off
	v_lshl_add_u64 v[190:191], s[34:35], 0, v[176:177]
	s_add_i32 m0, s55, 0xe000
	s_nop 0
	global_load_lds_dwordx4 v[190:191], off
	s_waitcnt lgkmcnt(8)
	s_add_i32 s92, 0, 0x14000
	s_add_i32 s12, s13, s54
	v_add_u32_e32 v185, s92, v183
	ds_read_b128 v[190:193], v185
	ds_read_b128 v[194:197], v185 offset:1024
	ds_read_b128 v[198:201], v185 offset:2048
	ds_read_b128 v[226:229], v185 offset:3072
	s_barrier
	s_waitcnt lgkmcnt(0)
	s_waitcnt lgkmcnt(0)
	s_nop 0
	v_mfma_f32_16x16x32_bf16 v[126:129], v[130:133], v[146:149], v[126:129]
	v_mfma_f32_16x16x32_bf16 v[122:125], v[138:141], v[146:149], v[122:125]
	v_mfma_f32_16x16x32_bf16 v[118:121], v[130:133], v[154:157], v[118:121]
	v_mfma_f32_16x16x32_bf16 v[114:117], v[138:141], v[154:157], v[114:117]
	v_mfma_f32_16x16x32_bf16 v[110:113], v[130:133], v[162:165], v[110:113]
	v_mfma_f32_16x16x32_bf16 v[106:109], v[138:141], v[162:165], v[106:109]
	v_mfma_f32_16x16x32_bf16 v[102:105], v[130:133], v[178:181], v[102:105]
	v_mfma_f32_16x16x32_bf16 v[98:101], v[138:141], v[178:181], v[98:101]
	v_mfma_f32_16x16x32_bf16 v[126:129], v[134:137], v[150:153], v[126:129]
	v_mfma_f32_16x16x32_bf16 v[122:125], v[142:145], v[150:153], v[122:125]
	v_mfma_f32_16x16x32_bf16 v[118:121], v[134:137], v[158:161], v[118:121]
	v_mfma_f32_16x16x32_bf16 v[114:117], v[142:145], v[158:161], v[114:117]
	v_mfma_f32_16x16x32_bf16 v[110:113], v[134:137], v[166:169], v[110:113]
	v_mfma_f32_16x16x32_bf16 v[106:109], v[142:145], v[166:169], v[106:109]
	v_mfma_f32_16x16x32_bf16 v[102:105], v[134:137], v[186:189], v[102:105]
	v_mfma_f32_16x16x32_bf16 v[98:101], v[142:145], v[186:189], v[98:101]
	s_waitcnt lgkmcnt(0)
	s_waitcnt lgkmcnt(0)
	v_mfma_f32_16x16x32_bf16 v[62:65], v[190:193], v[146:149], v[62:65]
	v_mfma_f32_16x16x32_bf16 v[58:61], v[198:201], v[146:149], v[58:61]
	v_mfma_f32_16x16x32_bf16 v[54:57], v[190:193], v[154:157], v[54:57]
	v_mfma_f32_16x16x32_bf16 v[50:53], v[198:201], v[154:157], v[50:53]
	v_mfma_f32_16x16x32_bf16 v[46:49], v[190:193], v[162:165], v[46:49]
	v_mfma_f32_16x16x32_bf16 v[42:45], v[198:201], v[162:165], v[42:45]
	v_mfma_f32_16x16x32_bf16 v[38:41], v[190:193], v[178:181], v[38:41]
	v_mfma_f32_16x16x32_bf16 v[34:37], v[198:201], v[178:181], v[34:37]
	v_mfma_f32_16x16x32_bf16 v[62:65], v[194:197], v[150:153], v[62:65]
	v_mfma_f32_16x16x32_bf16 v[58:61], v[226:229], v[150:153], v[58:61]
	v_mfma_f32_16x16x32_bf16 v[54:57], v[194:197], v[158:161], v[54:57]
	v_mfma_f32_16x16x32_bf16 v[50:53], v[226:229], v[158:161], v[50:53]
	v_mfma_f32_16x16x32_bf16 v[46:49], v[194:197], v[166:169], v[46:49]
	v_mfma_f32_16x16x32_bf16 v[42:45], v[226:229], v[166:169], v[42:45]
	v_mfma_f32_16x16x32_bf16 v[38:41], v[194:197], v[186:189], v[38:41]
	v_mfma_f32_16x16x32_bf16 v[34:37], v[226:229], v[186:189], v[34:37]
	s_mov_b32 m0, s55
	v_lshl_add_u64 v[234:235], s[2:3], 0, v[170:171]
	s_barrier
	ds_read_b128 v[146:149], v184 offset:16384
	ds_read_b128 v[150:153], v184 offset:17408
	ds_read_b128 v[154:157], v184 offset:18432
	ds_read_b128 v[158:161], v184 offset:19456
	ds_read_b128 v[162:165], v184 offset:20480
	ds_read_b128 v[166:169], v184 offset:21504
	ds_read_b128 v[178:181], v184 offset:22528
	ds_read_b128 v[186:189], v184 offset:23552
	global_load_lds_dwordx4 v[234:235], off
	v_lshl_add_u64 v[236:237], s[2:3], 0, v[172:173]
	s_mov_b32 m0, s58
	s_nop 0
	global_load_lds_dwordx4 v[236:237], off
	v_lshl_add_u64 v[230:231], s[42:43], 0, v[170:171]
	s_mov_b32 m0, s12
	s_nop 0
	global_load_lds_dwordx4 v[230:231], off
	v_lshl_add_u64 v[232:233], s[42:43], 0, v[172:173]
	s_add_i32 m0, s12, 0x2000
	s_nop 0
	global_load_lds_dwordx4 v[232:233], off
	s_add_u32 s12, s42, s18
	s_addc_u32 s13, s43, 0
	s_add_i32 s42, s92, s54
	v_lshl_add_u64 v[242:243], s[12:13], 0, v[170:171]
	s_mov_b32 m0, s42
	v_lshl_add_u64 v[244:245], s[12:13], 0, v[172:173]
	global_load_lds_dwordx4 v[242:243], off
	s_add_i32 m0, s42, 0x2000
	s_nop 0
	global_load_lds_dwordx4 v[244:245], off
	s_waitcnt vmcnt(6)
	s_barrier
	s_waitcnt lgkmcnt(0)
	s_waitcnt lgkmcnt(0)
	v_mfma_f32_16x16x32_bf16 v[94:97], v[130:133], v[146:149], v[94:97]
	v_mfma_f32_16x16x32_bf16 v[90:93], v[138:141], v[146:149], v[90:93]
	v_mfma_f32_16x16x32_bf16 v[86:89], v[130:133], v[154:157], v[86:89]
	v_mfma_f32_16x16x32_bf16 v[82:85], v[138:141], v[154:157], v[82:85]
	v_mfma_f32_16x16x32_bf16 v[78:81], v[130:133], v[162:165], v[78:81]
	v_mfma_f32_16x16x32_bf16 v[74:77], v[138:141], v[162:165], v[74:77]
	v_mfma_f32_16x16x32_bf16 v[70:73], v[130:133], v[178:181], v[70:73]
	v_mfma_f32_16x16x32_bf16 v[66:69], v[138:141], v[178:181], v[66:69]
	v_mfma_f32_16x16x32_bf16 v[94:97], v[134:137], v[150:153], v[94:97]
	v_mfma_f32_16x16x32_bf16 v[90:93], v[142:145], v[150:153], v[90:93]
	v_mfma_f32_16x16x32_bf16 v[86:89], v[134:137], v[158:161], v[86:89]
	v_mfma_f32_16x16x32_bf16 v[82:85], v[142:145], v[158:161], v[82:85]
	v_mfma_f32_16x16x32_bf16 v[78:81], v[134:137], v[166:169], v[78:81]
	v_mfma_f32_16x16x32_bf16 v[74:77], v[142:145], v[166:169], v[74:77]
	v_mfma_f32_16x16x32_bf16 v[70:73], v[134:137], v[186:189], v[70:73]
	v_mfma_f32_16x16x32_bf16 v[66:69], v[142:145], v[186:189], v[66:69]
	v_mfma_f32_16x16x32_bf16 v[30:33], v[190:193], v[146:149], v[30:33]
	v_mfma_f32_16x16x32_bf16 v[26:29], v[198:201], v[146:149], v[26:29]
	v_mfma_f32_16x16x32_bf16 v[22:25], v[190:193], v[154:157], v[22:25]
	v_mfma_f32_16x16x32_bf16 v[18:21], v[198:201], v[154:157], v[18:21]
	v_mfma_f32_16x16x32_bf16 v[14:17], v[190:193], v[162:165], v[14:17]
	v_mfma_f32_16x16x32_bf16 v[10:13], v[198:201], v[162:165], v[10:13]
	v_mfma_f32_16x16x32_bf16 v[6:9], v[190:193], v[178:181], v[6:9]
	v_mfma_f32_16x16x32_bf16 v[2:5], v[198:201], v[178:181], v[2:5]
	v_mfma_f32_16x16x32_bf16 v[30:33], v[194:197], v[150:153], v[30:33]
	v_mfma_f32_16x16x32_bf16 v[26:29], v[226:229], v[150:153], v[26:29]
	v_mfma_f32_16x16x32_bf16 v[22:25], v[194:197], v[158:161], v[22:25]
	v_mfma_f32_16x16x32_bf16 v[18:21], v[226:229], v[158:161], v[18:21]
	v_mfma_f32_16x16x32_bf16 v[14:17], v[194:197], v[166:169], v[14:17]
	v_mfma_f32_16x16x32_bf16 v[10:13], v[226:229], v[166:169], v[10:13]
	v_mfma_f32_16x16x32_bf16 v[6:9], v[194:197], v[186:189], v[6:9]
	v_mfma_f32_16x16x32_bf16 v[2:5], v[226:229], v[186:189], v[2:5]
	s_add_i32 s12, 0, 0x18000
	v_add_u32_e32 v142, s12, v183
	s_barrier
	ds_read_b128 v[130:133], v142
	ds_read_b128 v[134:137], v142 offset:1024
	ds_read_b128 v[138:141], v142 offset:2048
	ds_read_b128 v[142:145], v142 offset:3072
	s_add_u32 s2, s2, s18
	s_addc_u32 s3, s3, 0
	s_mov_b32 m0, s59
	v_lshl_add_u64 v[190:191], s[2:3], 0, v[170:171]
	ds_read_b128 v[146:149], v184 offset:32768
	ds_read_b128 v[150:153], v184 offset:33792
	ds_read_b128 v[154:157], v184 offset:34816
	ds_read_b128 v[158:161], v184 offset:35840
	ds_read_b128 v[162:165], v184 offset:36864
	ds_read_b128 v[166:169], v184 offset:37888
	ds_read_b128 v[178:181], v184 offset:38912
	ds_read_b128 v[186:189], v184 offset:39936
	global_load_lds_dwordx4 v[190:191], off
	v_lshl_add_u64 v[190:191], s[2:3], 0, v[172:173]
	s_mov_b32 m0, s77
	s_nop 0
	global_load_lds_dwordx4 v[190:191], off
	s_waitcnt lgkmcnt(8)
	s_add_i32 s2, 0, 0x1c000
	s_add_i32 s3, s12, s54
	v_add_u32_e32 v185, s2, v183
	ds_read_b128 v[190:193], v185
	ds_read_b128 v[194:197], v185 offset:1024
	ds_read_b128 v[198:201], v185 offset:2048
	ds_read_b128 v[226:229], v185 offset:3072
	s_barrier
	s_waitcnt lgkmcnt(0)
	s_waitcnt lgkmcnt(0)
	s_nop 0
	v_mfma_f32_16x16x32_bf16 v[126:129], v[130:133], v[146:149], v[126:129]
	v_mfma_f32_16x16x32_bf16 v[122:125], v[138:141], v[146:149], v[122:125]
	v_mfma_f32_16x16x32_bf16 v[118:121], v[130:133], v[154:157], v[118:121]
	v_mfma_f32_16x16x32_bf16 v[114:117], v[138:141], v[154:157], v[114:117]
	v_mfma_f32_16x16x32_bf16 v[110:113], v[130:133], v[162:165], v[110:113]
	v_mfma_f32_16x16x32_bf16 v[106:109], v[138:141], v[162:165], v[106:109]
	v_mfma_f32_16x16x32_bf16 v[102:105], v[130:133], v[178:181], v[102:105]
	v_mfma_f32_16x16x32_bf16 v[98:101], v[138:141], v[178:181], v[98:101]
	v_mfma_f32_16x16x32_bf16 v[126:129], v[134:137], v[150:153], v[126:129]
	v_mfma_f32_16x16x32_bf16 v[122:125], v[142:145], v[150:153], v[122:125]
	v_mfma_f32_16x16x32_bf16 v[118:121], v[134:137], v[158:161], v[118:121]
	v_mfma_f32_16x16x32_bf16 v[114:117], v[142:145], v[158:161], v[114:117]
	v_mfma_f32_16x16x32_bf16 v[110:113], v[134:137], v[166:169], v[110:113]
	v_mfma_f32_16x16x32_bf16 v[106:109], v[142:145], v[166:169], v[106:109]
	v_mfma_f32_16x16x32_bf16 v[102:105], v[134:137], v[186:189], v[102:105]
	v_mfma_f32_16x16x32_bf16 v[98:101], v[142:145], v[186:189], v[98:101]
	s_waitcnt lgkmcnt(0)
	s_waitcnt lgkmcnt(0)
	v_mfma_f32_16x16x32_bf16 v[62:65], v[190:193], v[146:149], v[62:65]
	v_mfma_f32_16x16x32_bf16 v[58:61], v[198:201], v[146:149], v[58:61]
	v_mfma_f32_16x16x32_bf16 v[54:57], v[190:193], v[154:157], v[54:57]
	v_mfma_f32_16x16x32_bf16 v[50:53], v[198:201], v[154:157], v[50:53]
	v_mfma_f32_16x16x32_bf16 v[46:49], v[190:193], v[162:165], v[46:49]
	v_mfma_f32_16x16x32_bf16 v[42:45], v[198:201], v[162:165], v[42:45]
	v_mfma_f32_16x16x32_bf16 v[38:41], v[190:193], v[178:181], v[38:41]
	v_mfma_f32_16x16x32_bf16 v[34:37], v[198:201], v[178:181], v[34:37]
	v_mfma_f32_16x16x32_bf16 v[62:65], v[194:197], v[150:153], v[62:65]
	v_mfma_f32_16x16x32_bf16 v[58:61], v[226:229], v[150:153], v[58:61]
	v_mfma_f32_16x16x32_bf16 v[54:57], v[194:197], v[158:161], v[54:57]
	v_mfma_f32_16x16x32_bf16 v[50:53], v[226:229], v[158:161], v[50:53]
	v_mfma_f32_16x16x32_bf16 v[46:49], v[194:197], v[166:169], v[46:49]
	v_mfma_f32_16x16x32_bf16 v[42:45], v[226:229], v[166:169], v[42:45]
	v_mfma_f32_16x16x32_bf16 v[38:41], v[194:197], v[186:189], v[38:41]
	v_mfma_f32_16x16x32_bf16 v[34:37], v[226:229], v[186:189], v[34:37]
	s_mov_b32 m0, s80
	v_lshl_add_u64 v[234:235], v[234:235], 0, s[20:21]
	s_barrier
	ds_read_b128 v[146:149], v184 offset:49152
	ds_read_b128 v[150:153], v184 offset:50176
	ds_read_b128 v[154:157], v184 offset:51200
	ds_read_b128 v[158:161], v184 offset:52224
	ds_read_b128 v[162:165], v184 offset:53248
	ds_read_b128 v[166:169], v184 offset:54272
	ds_read_b128 v[178:181], v184 offset:55296
	ds_read_b128 v[186:189], v184 offset:56320
	global_load_lds_dwordx4 v[234:235], off
	v_lshl_add_u64 v[236:237], v[236:237], 0, s[20:21]
	s_mov_b32 m0, s81
	s_nop 0
	global_load_lds_dwordx4 v[236:237], off
	v_lshl_add_u64 v[230:231], v[230:231], 0, s[20:21]
	s_mov_b32 m0, s3
	s_nop 0
	global_load_lds_dwordx4 v[230:231], off
	v_lshl_add_u64 v[230:231], v[232:233], 0, s[20:21]
	s_add_i32 m0, s3, 0x2000
	s_nop 0
	global_load_lds_dwordx4 v[230:231], off
	s_add_i32 s2, s2, s54
	v_lshl_add_u64 v[242:243], v[242:243], 0, s[20:21]
	s_mov_b32 m0, s2
	s_nop 0
	global_load_lds_dwordx4 v[242:243], off
	v_lshl_add_u64 v[244:245], v[244:245], 0, s[20:21]
	s_add_i32 m0, s2, 0x2000
	s_nop 0
	global_load_lds_dwordx4 v[244:245], off
	s_waitcnt vmcnt(6)
	s_barrier
	s_waitcnt lgkmcnt(0)
	s_waitcnt lgkmcnt(0)
	s_nop 0
	v_mfma_f32_16x16x32_bf16 v[94:97], v[130:133], v[146:149], v[94:97]
	v_mfma_f32_16x16x32_bf16 v[90:93], v[138:141], v[146:149], v[90:93]
	v_mfma_f32_16x16x32_bf16 v[86:89], v[130:133], v[154:157], v[86:89]
	v_mfma_f32_16x16x32_bf16 v[82:85], v[138:141], v[154:157], v[82:85]
	v_mfma_f32_16x16x32_bf16 v[78:81], v[130:133], v[162:165], v[78:81]
	v_mfma_f32_16x16x32_bf16 v[74:77], v[138:141], v[162:165], v[74:77]
	v_mfma_f32_16x16x32_bf16 v[70:73], v[130:133], v[178:181], v[70:73]
	v_mfma_f32_16x16x32_bf16 v[66:69], v[138:141], v[178:181], v[66:69]
	v_mfma_f32_16x16x32_bf16 v[94:97], v[134:137], v[150:153], v[94:97]
	v_mfma_f32_16x16x32_bf16 v[90:93], v[142:145], v[150:153], v[90:93]
	v_mfma_f32_16x16x32_bf16 v[86:89], v[134:137], v[158:161], v[86:89]
	v_mfma_f32_16x16x32_bf16 v[82:85], v[142:145], v[158:161], v[82:85]
	v_mfma_f32_16x16x32_bf16 v[78:81], v[134:137], v[166:169], v[78:81]
	v_mfma_f32_16x16x32_bf16 v[74:77], v[142:145], v[166:169], v[74:77]
	v_mfma_f32_16x16x32_bf16 v[70:73], v[134:137], v[186:189], v[70:73]
	v_mfma_f32_16x16x32_bf16 v[66:69], v[142:145], v[186:189], v[66:69]
	v_mfma_f32_16x16x32_bf16 v[30:33], v[190:193], v[146:149], v[30:33]
	v_mfma_f32_16x16x32_bf16 v[26:29], v[198:201], v[146:149], v[26:29]
	v_mfma_f32_16x16x32_bf16 v[22:25], v[190:193], v[154:157], v[22:25]
	v_mfma_f32_16x16x32_bf16 v[18:21], v[198:201], v[154:157], v[18:21]
	v_mfma_f32_16x16x32_bf16 v[14:17], v[190:193], v[162:165], v[14:17]
	v_mfma_f32_16x16x32_bf16 v[10:13], v[198:201], v[162:165], v[10:13]
	v_mfma_f32_16x16x32_bf16 v[6:9], v[190:193], v[178:181], v[6:9]
	v_mfma_f32_16x16x32_bf16 v[2:5], v[198:201], v[178:181], v[2:5]
	v_mfma_f32_16x16x32_bf16 v[30:33], v[194:197], v[150:153], v[30:33]
	v_mfma_f32_16x16x32_bf16 v[26:29], v[226:229], v[150:153], v[26:29]
	v_mfma_f32_16x16x32_bf16 v[22:25], v[194:197], v[158:161], v[22:25]
	v_mfma_f32_16x16x32_bf16 v[18:21], v[226:229], v[158:161], v[18:21]
	v_mfma_f32_16x16x32_bf16 v[14:17], v[194:197], v[166:169], v[14:17]
	v_mfma_f32_16x16x32_bf16 v[10:13], v[226:229], v[166:169], v[10:13]
	v_mfma_f32_16x16x32_bf16 v[6:9], v[194:197], v[186:189], v[6:9]
	v_mfma_f32_16x16x32_bf16 v[2:5], v[226:229], v[186:189], v[2:5]
	s_add_u32 s34, s34, 0x100
	s_addc_u32 s35, s35, 0
	s_add_u32 s89, s89, 0x100
	s_addc_u32 s90, s90, 0
	s_cmp_ge_i32 s91, s44
	s_mov_b32 s2, s91
	s_barrier
	s_cbranch_scc0 .LBB0_182
	s_cmp_lt_i32 s86, 64
	s_cselect_b64 s[34:35], -1, 0
	s_ashr_i32 s2, s45, 8
	s_ashr_i32 s3, s2, 31
	s_lshl_b64 s[2:3], s[2:3], 18
	s_add_u32 s2, s2, 0x3232000
	s_addc_u32 s3, s3, 0
	s_cmp_gt_i32 s86, 63
	s_cselect_b32 s12, 0x6000, 0
	s_cselect_b32 s45, s3, 0
	s_cselect_b32 s44, s2, 0
	s_add_u32 s12, s78, s12
	s_addc_u32 s13, s79, 0
	s_lshl_b32 s2, s87, 8
	s_ashr_i32 s3, s2, 31
	s_lshl_b64 s[2:3], s[2:3], 2
	s_add_u32 s12, s12, s2
	s_addc_u32 s13, s13, s3
	v_readlane_b32 s88, v254, 38
	s_add_u32 s42, s12, s88
	s_addc_u32 s43, s13, 0
	global_load_dwordx4 v[134:137], v0, s[42:43]
	global_load_dwordx4 v[130:133], v0, s[42:43] offset:64
	v_lshl_add_u32 v138, s86, 8, v182
	v_ashrrev_i32_e32 v139, 31, v138
	v_readlane_b32 s12, v252, 5
	v_lshlrev_b64 v[138:139], 12, v[138:139]
	v_readlane_b32 s13, v252, 6
	v_readlane_b32 s89, v254, 39
	s_and_b64 vcc, exec, s[34:35]
	v_lshl_add_u64 v[138:139], s[12:13], 0, v[138:139]
	v_lshl_add_u64 v[138:139], v[138:139], 0, s[2:3]
	v_lshl_add_u64 v[138:139], v[138:139], 0, s[88:89]
	v_lshl_add_u64 v[178:179], v[138:139], 0, v[0:1]
	v_lshl_add_u64 v[180:181], v[178:179], 0, s[22:23]
	v_readfirstlane_b32 s88, v178
	v_readfirstlane_b32 s89, v179
	v_and_b32_e32 v178, 15, v202
	v_bfe_u32 v179, v202, 4, 2
	v_lshlrev_b32_e32 v178, 12, v178
	v_lshl_or_b32 v178, v179, 4, v178
	s_mov_b32 s13, 0
	s_and_b64 vcc, exec, s[34:35]
	s_cbranch_vccz .Lre_nf
	v_readlane_b32 s2, v252, 2
	v_readlane_b32 s3, v255, 14
	v_readlane_b32 s12, v255, 12
	s_cmp_eq_u32 s2, 0x100
	s_cbranch_scc0 .Lre_nf
	s_cmp_eq_u32 s3, 5
	s_cbranch_scc1 .Lre_f
	s_cmp_eq_u32 s3, 8
	s_cbranch_scc0 .Lre_nf

.LBB0_366:
	s_add_u32 s2, s0, 0xfffc0080
	s_addc_u32 s3, s1, -1
	s_add_i32 s12, 0, 0x10000
	v_add_u32_e32 v142, s12, v227
	ds_read_b128 v[130:133], v142
	ds_read_b128 v[134:137], v142 offset:1024
	ds_read_b128 v[138:141], v142 offset:2048
	ds_read_b128 v[142:145], v142 offset:3072
	s_cmp_eq_u32 s47, 12
	s_cselect_b32 s17, s15, s3
	s_cselect_b32 s16, s19, s2
	s_cselect_b32 s3, s43, s46
	s_cselect_b32 s2, s44, s45
	v_lshl_add_u64 v[190:191], s[0:1], 0, v[162:163]
	s_add_i32 m0, s54, 0xc000
	ds_read_b128 v[146:149], v233
	ds_read_b128 v[150:153], v233 offset:1024
	ds_read_b128 v[166:169], v233 offset:2048
	ds_read_b128 v[170:173], v233 offset:3072
	ds_read_b128 v[174:177], v233 offset:4096
	ds_read_b128 v[178:181], v233 offset:5120
	ds_read_b128 v[182:185], v233 offset:6144
	ds_read_b128 v[186:189], v233 offset:7168
	global_load_lds_dwordx4 v[190:191], off
	v_lshl_add_u64 v[190:191], s[0:1], 0, v[164:165]
	s_add_i32 m0, s54, 0xe000
	s_nop 0
	global_load_lds_dwordx4 v[190:191], off
	s_waitcnt lgkmcnt(8)
	s_barrier
	s_waitcnt lgkmcnt(0)
	s_waitcnt lgkmcnt(0)
	s_nop 0
	v_mfma_f32_16x16x32_bf16 v[126:129], v[130:133], v[146:149], v[126:129]
	v_mfma_f32_16x16x32_bf16 v[122:125], v[138:141], v[146:149], v[122:125]
	v_mfma_f32_16x16x32_bf16 v[118:121], v[130:133], v[166:169], v[118:121]
	v_mfma_f32_16x16x32_bf16 v[114:117], v[138:141], v[166:169], v[114:117]
	v_mfma_f32_16x16x32_bf16 v[110:113], v[130:133], v[174:177], v[110:113]
	v_mfma_f32_16x16x32_bf16 v[106:109], v[138:141], v[174:177], v[106:109]
	v_mfma_f32_16x16x32_bf16 v[102:105], v[130:133], v[182:185], v[102:105]
	v_mfma_f32_16x16x32_bf16 v[98:101], v[138:141], v[182:185], v[98:101]
	v_mfma_f32_16x16x32_bf16 v[126:129], v[134:137], v[150:153], v[126:129]
	v_mfma_f32_16x16x32_bf16 v[122:125], v[142:145], v[150:153], v[122:125]
	v_mfma_f32_16x16x32_bf16 v[118:121], v[134:137], v[170:173], v[118:121]
	v_mfma_f32_16x16x32_bf16 v[114:117], v[142:145], v[170:173], v[114:117]
	v_mfma_f32_16x16x32_bf16 v[110:113], v[134:137], v[178:181], v[110:113]
	v_mfma_f32_16x16x32_bf16 v[106:109], v[142:145], v[178:181], v[106:109]
	v_mfma_f32_16x16x32_bf16 v[102:105], v[134:137], v[186:189], v[102:105]
	v_mfma_f32_16x16x32_bf16 v[98:101], v[142:145], v[186:189], v[98:101]
	s_barrier
	s_add_i32 s13, 0, 0x14000
	s_add_i32 s12, s12, s35
	v_add_u32_e32 v234, s13, v227
	v_lshl_add_u64 v[242:243], s[2:3], 0, v[0:1]
	s_mov_b32 m0, s12
	ds_read_b128 v[190:193], v234
	ds_read_b128 v[194:197], v234 offset:1024
	ds_read_b128 v[198:201], v234 offset:2048
	ds_read_b128 v[234:237], v234 offset:3072
	global_load_lds_dwordx4 v[242:243], off
	v_lshl_add_u64 v[244:245], s[2:3], 0, v[154:155]
	s_add_i32 m0, s12, 0x2000
	s_nop 0
	global_load_lds_dwordx4 v[244:245], off
	s_barrier
	s_waitcnt lgkmcnt(0)
	s_waitcnt lgkmcnt(0)
	v_mfma_f32_16x16x32_bf16 v[62:65], v[190:193], v[146:149], v[62:65]
	v_mfma_f32_16x16x32_bf16 v[58:61], v[198:201], v[146:149], v[58:61]
	v_mfma_f32_16x16x32_bf16 v[54:57], v[190:193], v[166:169], v[54:57]
	v_mfma_f32_16x16x32_bf16 v[50:53], v[198:201], v[166:169], v[50:53]
	v_mfma_f32_16x16x32_bf16 v[46:49], v[190:193], v[174:177], v[46:49]
	v_mfma_f32_16x16x32_bf16 v[42:45], v[198:201], v[174:177], v[42:45]
	v_mfma_f32_16x16x32_bf16 v[38:41], v[190:193], v[182:185], v[38:41]
	v_mfma_f32_16x16x32_bf16 v[34:37], v[198:201], v[182:185], v[34:37]
	v_mfma_f32_16x16x32_bf16 v[62:65], v[194:197], v[150:153], v[62:65]
	v_mfma_f32_16x16x32_bf16 v[58:61], v[234:237], v[150:153], v[58:61]
	v_mfma_f32_16x16x32_bf16 v[54:57], v[194:197], v[170:173], v[54:57]
	v_mfma_f32_16x16x32_bf16 v[50:53], v[234:237], v[170:173], v[50:53]
	v_mfma_f32_16x16x32_bf16 v[46:49], v[194:197], v[178:181], v[46:49]
	v_mfma_f32_16x16x32_bf16 v[42:45], v[234:237], v[178:181], v[42:45]
	v_mfma_f32_16x16x32_bf16 v[38:41], v[194:197], v[186:189], v[38:41]
	v_mfma_f32_16x16x32_bf16 v[34:37], v[234:237], v[186:189], v[34:37]
	s_mov_b32 m0, s54
	s_nop 0
	s_barrier
	ds_read_b128 v[146:149], v233 offset:16384
	ds_read_b128 v[150:153], v233 offset:17408
	ds_read_b128 v[166:169], v233 offset:18432
	ds_read_b128 v[170:173], v233 offset:19456
	ds_read_b128 v[174:177], v233 offset:20480
	ds_read_b128 v[178:181], v233 offset:21504
	ds_read_b128 v[182:185], v233 offset:22528
	ds_read_b128 v[186:189], v233 offset:23552
	global_load_lds_dwordx4 v250, s[16:17]
	s_nop 0
	s_mov_b32 m0, s55
	s_nop 0
	global_load_lds_dwordx4 v251, s[16:17]
	s_barrier
	s_waitcnt lgkmcnt(0)
	s_waitcnt lgkmcnt(0)
	s_nop 0
	v_mfma_f32_16x16x32_bf16 v[94:97], v[130:133], v[146:149], v[94:97]
	v_mfma_f32_16x16x32_bf16 v[90:93], v[138:141], v[146:149], v[90:93]
	v_mfma_f32_16x16x32_bf16 v[86:89], v[130:133], v[166:169], v[86:89]
	v_mfma_f32_16x16x32_bf16 v[82:85], v[138:141], v[166:169], v[82:85]
	v_mfma_f32_16x16x32_bf16 v[78:81], v[130:133], v[174:177], v[78:81]
	v_mfma_f32_16x16x32_bf16 v[74:77], v[138:141], v[174:177], v[74:77]
	v_mfma_f32_16x16x32_bf16 v[70:73], v[130:133], v[182:185], v[70:73]
	v_mfma_f32_16x16x32_bf16 v[66:69], v[138:141], v[182:185], v[66:69]
	v_mfma_f32_16x16x32_bf16 v[94:97], v[134:137], v[150:153], v[94:97]
	v_mfma_f32_16x16x32_bf16 v[90:93], v[142:145], v[150:153], v[90:93]
	v_mfma_f32_16x16x32_bf16 v[86:89], v[134:137], v[170:173], v[86:89]
	v_mfma_f32_16x16x32_bf16 v[82:85], v[142:145], v[170:173], v[82:85]
	v_mfma_f32_16x16x32_bf16 v[78:81], v[134:137], v[178:181], v[78:81]
	v_mfma_f32_16x16x32_bf16 v[74:77], v[142:145], v[178:181], v[74:77]
	v_mfma_f32_16x16x32_bf16 v[70:73], v[134:137], v[186:189], v[70:73]
	v_mfma_f32_16x16x32_bf16 v[66:69], v[142:145], v[186:189], v[66:69]
	s_barrier
	s_add_u32 s78, s2, 0x40000
	s_addc_u32 s79, s3, 0
	s_add_i32 s12, s13, s35
	v_lshl_add_u64 v[130:131], s[78:79], 0, v[0:1]
	s_mov_b32 m0, s12
	s_nop 0
	global_load_lds_dwordx4 v[130:131], off
	v_lshl_add_u64 v[130:131], s[78:79], 0, v[154:155]
	s_add_i32 m0, s12, 0x2000
	s_nop 0
	global_load_lds_dwordx4 v[130:131], off
	s_waitcnt vmcnt(6)
	s_barrier
	v_mfma_f32_16x16x32_bf16 v[30:33], v[190:193], v[146:149], v[30:33]
	v_mfma_f32_16x16x32_bf16 v[26:29], v[198:201], v[146:149], v[26:29]
	v_mfma_f32_16x16x32_bf16 v[22:25], v[190:193], v[166:169], v[22:25]
	v_mfma_f32_16x16x32_bf16 v[18:21], v[198:201], v[166:169], v[18:21]
	v_mfma_f32_16x16x32_bf16 v[14:17], v[190:193], v[174:177], v[14:17]
	v_mfma_f32_16x16x32_bf16 v[10:13], v[198:201], v[174:177], v[10:13]
	v_mfma_f32_16x16x32_bf16 v[6:9], v[190:193], v[182:185], v[6:9]
	v_mfma_f32_16x16x32_bf16 v[2:5], v[198:201], v[182:185], v[2:5]
	v_mfma_f32_16x16x32_bf16 v[30:33], v[194:197], v[150:153], v[30:33]
	v_mfma_f32_16x16x32_bf16 v[26:29], v[234:237], v[150:153], v[26:29]
	v_mfma_f32_16x16x32_bf16 v[22:25], v[194:197], v[170:173], v[22:25]
	v_mfma_f32_16x16x32_bf16 v[18:21], v[234:237], v[170:173], v[18:21]
	v_mfma_f32_16x16x32_bf16 v[14:17], v[194:197], v[178:181], v[14:17]
	v_mfma_f32_16x16x32_bf16 v[10:13], v[234:237], v[178:181], v[10:13]
	v_mfma_f32_16x16x32_bf16 v[6:9], v[194:197], v[186:189], v[6:9]
	v_mfma_f32_16x16x32_bf16 v[2:5], v[234:237], v[186:189], v[2:5]
	s_add_i32 s12, 0, 0x18000
	v_add_u32_e32 v142, s12, v227
	s_barrier
	ds_read_b128 v[130:133], v142
	ds_read_b128 v[134:137], v142 offset:1024
	ds_read_b128 v[138:141], v142 offset:2048
	ds_read_b128 v[142:145], v142 offset:3072
	s_add_u32 s16, s16, 0x40000
	s_addc_u32 s17, s17, 0
	s_mov_b32 m0, s58
	s_nop 0
	ds_read_b128 v[146:149], v233 offset:32768
	ds_read_b128 v[150:153], v233 offset:33792
	ds_read_b128 v[166:169], v233 offset:34816
	ds_read_b128 v[170:173], v233 offset:35840
	ds_read_b128 v[174:177], v233 offset:36864
	ds_read_b128 v[178:181], v233 offset:37888
	ds_read_b128 v[182:185], v233 offset:38912
	ds_read_b128 v[186:189], v233 offset:39936
	global_load_lds_dwordx4 v250, s[16:17]
	s_nop 0
	s_mov_b32 m0, s59
	s_nop 0
	global_load_lds_dwordx4 v251, s[16:17]
	s_waitcnt lgkmcnt(8)
	s_barrier
	s_waitcnt lgkmcnt(0)
	s_waitcnt lgkmcnt(0)
	v_mfma_f32_16x16x32_bf16 v[126:129], v[130:133], v[146:149], v[126:129]
	v_mfma_f32_16x16x32_bf16 v[122:125], v[138:141], v[146:149], v[122:125]
	v_mfma_f32_16x16x32_bf16 v[118:121], v[130:133], v[166:169], v[118:121]
	v_mfma_f32_16x16x32_bf16 v[114:117], v[138:141], v[166:169], v[114:117]
	v_mfma_f32_16x16x32_bf16 v[110:113], v[130:133], v[174:177], v[110:113]
	v_mfma_f32_16x16x32_bf16 v[106:109], v[138:141], v[174:177], v[106:109]
	v_mfma_f32_16x16x32_bf16 v[102:105], v[130:133], v[182:185], v[102:105]
	v_mfma_f32_16x16x32_bf16 v[98:101], v[138:141], v[182:185], v[98:101]
	v_mfma_f32_16x16x32_bf16 v[126:129], v[134:137], v[150:153], v[126:129]
	v_mfma_f32_16x16x32_bf16 v[122:125], v[142:145], v[150:153], v[122:125]
	v_mfma_f32_16x16x32_bf16 v[118:121], v[134:137], v[170:173], v[118:121]
	v_mfma_f32_16x16x32_bf16 v[114:117], v[142:145], v[170:173], v[114:117]
	v_mfma_f32_16x16x32_bf16 v[110:113], v[134:137], v[178:181], v[110:113]
	v_mfma_f32_16x16x32_bf16 v[106:109], v[142:145], v[178:181], v[106:109]
	v_mfma_f32_16x16x32_bf16 v[102:105], v[134:137], v[186:189], v[102:105]
	v_mfma_f32_16x16x32_bf16 v[98:101], v[142:145], v[186:189], v[98:101]
	s_barrier
	s_add_i32 s13, 0, 0x1c000
	s_add_i32 s12, s12, s35
	v_add_u32_e32 v234, s13, v227
	v_lshl_add_u64 v[242:243], v[242:243], 0, s[20:21]
	s_mov_b32 m0, s12
	ds_read_b128 v[190:193], v234
	ds_read_b128 v[194:197], v234 offset:1024
	ds_read_b128 v[198:201], v234 offset:2048
	ds_read_b128 v[234:237], v234 offset:3072
	global_load_lds_dwordx4 v[242:243], off
	v_lshl_add_u64 v[242:243], v[244:245], 0, s[20:21]
	s_add_i32 m0, s12, 0x2000
	s_nop 0
	global_load_lds_dwordx4 v[242:243], off
	s_barrier
	s_waitcnt lgkmcnt(0)
	s_waitcnt lgkmcnt(0)
	v_mfma_f32_16x16x32_bf16 v[62:65], v[190:193], v[146:149], v[62:65]
	v_mfma_f32_16x16x32_bf16 v[58:61], v[198:201], v[146:149], v[58:61]
	v_mfma_f32_16x16x32_bf16 v[54:57], v[190:193], v[166:169], v[54:57]
	v_mfma_f32_16x16x32_bf16 v[50:53], v[198:201], v[166:169], v[50:53]
	v_mfma_f32_16x16x32_bf16 v[46:49], v[190:193], v[174:177], v[46:49]
	v_mfma_f32_16x16x32_bf16 v[42:45], v[198:201], v[174:177], v[42:45]
	v_mfma_f32_16x16x32_bf16 v[38:41], v[190:193], v[182:185], v[38:41]
	v_mfma_f32_16x16x32_bf16 v[34:37], v[198:201], v[182:185], v[34:37]
	v_mfma_f32_16x16x32_bf16 v[62:65], v[194:197], v[150:153], v[62:65]
	v_mfma_f32_16x16x32_bf16 v[58:61], v[234:237], v[150:153], v[58:61]
	v_mfma_f32_16x16x32_bf16 v[54:57], v[194:197], v[170:173], v[54:57]
	v_mfma_f32_16x16x32_bf16 v[50:53], v[234:237], v[170:173], v[50:53]
	v_mfma_f32_16x16x32_bf16 v[46:49], v[194:197], v[178:181], v[46:49]
	v_mfma_f32_16x16x32_bf16 v[42:45], v[234:237], v[178:181], v[42:45]
	v_mfma_f32_16x16x32_bf16 v[38:41], v[194:197], v[186:189], v[38:41]
	v_mfma_f32_16x16x32_bf16 v[34:37], v[234:237], v[186:189], v[34:37]
	s_mov_b32 m0, s96
	s_add_u32 s78, s16, 0xfffc0080
	s_addc_u32 s79, s17, -1
	s_barrier
	ds_read_b128 v[146:149], v233 offset:49152
	ds_read_b128 v[150:153], v233 offset:50176
	ds_read_b128 v[166:169], v233 offset:51200
	ds_read_b128 v[170:173], v233 offset:52224
	ds_read_b128 v[174:177], v233 offset:53248
	ds_read_b128 v[178:181], v233 offset:54272
	ds_read_b128 v[182:185], v233 offset:55296
	ds_read_b128 v[186:189], v233 offset:56320
	global_load_lds_dwordx4 v250, s[78:79]
	s_nop 0
	s_mov_b32 m0, s97
	s_nop 0
	global_load_lds_dwordx4 v251, s[78:79]
	s_barrier
	s_waitcnt lgkmcnt(0)
	s_waitcnt lgkmcnt(0)
	s_nop 0
	v_mfma_f32_16x16x32_bf16 v[94:97], v[130:133], v[146:149], v[94:97]
	v_mfma_f32_16x16x32_bf16 v[90:93], v[138:141], v[146:149], v[90:93]
	v_mfma_f32_16x16x32_bf16 v[86:89], v[130:133], v[166:169], v[86:89]
	v_mfma_f32_16x16x32_bf16 v[82:85], v[138:141], v[166:169], v[82:85]
	v_mfma_f32_16x16x32_bf16 v[78:81], v[130:133], v[174:177], v[78:81]
	v_mfma_f32_16x16x32_bf16 v[74:77], v[138:141], v[174:177], v[74:77]
	v_mfma_f32_16x16x32_bf16 v[70:73], v[130:133], v[182:185], v[70:73]
	v_mfma_f32_16x16x32_bf16 v[66:69], v[138:141], v[182:185], v[66:69]
	v_mfma_f32_16x16x32_bf16 v[94:97], v[134:137], v[150:153], v[94:97]
	v_mfma_f32_16x16x32_bf16 v[90:93], v[142:145], v[150:153], v[90:93]
	v_mfma_f32_16x16x32_bf16 v[86:89], v[134:137], v[170:173], v[86:89]
	v_mfma_f32_16x16x32_bf16 v[82:85], v[142:145], v[170:173], v[82:85]
	v_mfma_f32_16x16x32_bf16 v[78:81], v[134:137], v[178:181], v[78:81]
	v_mfma_f32_16x16x32_bf16 v[74:77], v[142:145], v[178:181], v[74:77]
	v_mfma_f32_16x16x32_bf16 v[70:73], v[134:137], v[186:189], v[70:73]
	v_mfma_f32_16x16x32_bf16 v[66:69], v[142:145], v[186:189], v[66:69]
	s_barrier
	s_add_u32 s2, s2, 0x40080
	s_addc_u32 s3, s3, 0
	s_add_i32 s12, s13, s35
	v_lshl_add_u64 v[130:131], s[2:3], 0, v[0:1]
	s_mov_b32 m0, s12
	s_nop 0
	global_load_lds_dwordx4 v[130:131], off
	v_lshl_add_u64 v[130:131], s[2:3], 0, v[154:155]
	s_add_i32 m0, s12, 0x2000
	s_nop 0
	global_load_lds_dwordx4 v[130:131], off
	s_waitcnt vmcnt(6)
	s_barrier
	v_mfma_f32_16x16x32_bf16 v[30:33], v[190:193], v[146:149], v[30:33]
	v_mfma_f32_16x16x32_bf16 v[26:29], v[198:201], v[146:149], v[26:29]
	v_mfma_f32_16x16x32_bf16 v[22:25], v[190:193], v[166:169], v[22:25]
	v_mfma_f32_16x16x32_bf16 v[18:21], v[198:201], v[166:169], v[18:21]
	v_mfma_f32_16x16x32_bf16 v[14:17], v[190:193], v[174:177], v[14:17]
	v_mfma_f32_16x16x32_bf16 v[10:13], v[198:201], v[174:177], v[10:13]
	v_mfma_f32_16x16x32_bf16 v[6:9], v[190:193], v[182:185], v[6:9]
	v_mfma_f32_16x16x32_bf16 v[2:5], v[198:201], v[182:185], v[2:5]
	v_mfma_f32_16x16x32_bf16 v[30:33], v[194:197], v[150:153], v[30:33]
	v_mfma_f32_16x16x32_bf16 v[26:29], v[234:237], v[150:153], v[26:29]
	v_mfma_f32_16x16x32_bf16 v[22:25], v[194:197], v[170:173], v[22:25]
	v_mfma_f32_16x16x32_bf16 v[18:21], v[234:237], v[170:173], v[18:21]
	v_mfma_f32_16x16x32_bf16 v[14:17], v[194:197], v[178:181], v[14:17]
	v_mfma_f32_16x16x32_bf16 v[10:13], v[234:237], v[178:181], v[10:13]
	v_mfma_f32_16x16x32_bf16 v[6:9], v[194:197], v[186:189], v[6:9]
	v_mfma_f32_16x16x32_bf16 v[2:5], v[234:237], v[186:189], v[2:5]
	s_add_i32 s47, s47, 2
	s_add_u32 s0, s0, 0x100
	s_addc_u32 s1, s1, 0
	s_add_u32 s45, s45, 0x100
	s_addc_u32 s46, s46, 0
	s_cmp_gt_u32 s47, 13
	s_barrier
	s_cbranch_scc0 .LBB0_366

.Lq_aligned:
	s_barrier
	s_add_i32 m0, s46, 0x0
	s_nop 0
	global_load_lds_dwordx4 v250, s[0:1]
	s_add_i32 m0, s46, 0x2000
	s_nop 0
	global_load_lds_dwordx4 v251, s[0:1]
	s_add_i32 m0, s47, 0x0
	s_nop 0
	global_load_lds_dwordx4 v0, s[16:17]
	s_add_i32 m0, s47, 0x2000
	s_nop 0
	global_load_lds_dwordx4 v154, s[16:17]
	s_add_u32 s0, s0, 0x80
	s_addc_u32 s1, s1, 0
	s_add_u32 s16, s16, 0x80
	s_addc_u32 s17, s17, 0
	s_add_i32 m0, s46, 0x8000
	s_nop 0
	global_load_lds_dwordx4 v250, s[0:1]
	s_add_i32 m0, s46, 0xa000
	s_nop 0
	global_load_lds_dwordx4 v251, s[0:1]
	s_add_i32 m0, s47, 0x8000
	s_nop 0
	global_load_lds_dwordx4 v0, s[16:17]
	s_add_i32 m0, s47, 0xa000
	s_nop 0
	global_load_lds_dwordx4 v154, s[16:17]
	s_add_u32 s0, s0, 0x80
	s_addc_u32 s1, s1, 0
	s_add_u32 s16, s16, 0x80
	s_addc_u32 s17, s17, 0
	ds_read_b128 v[130:133], v191 offset:0
	ds_read_b128 v[134:137], v191 offset:1024
	ds_read_b128 v[138:141], v191 offset:2048
	ds_read_b128 v[142:145], v191 offset:3072
	ds_read_b128 v[146:149], v190 offset:0
	ds_read_b128 v[150:153], v190 offset:1024
	ds_read_b128 v[166:169], v190 offset:2048
	ds_read_b128 v[170:173], v190 offset:3072
	ds_read_b128 v[174:177], v190 offset:4096
	ds_read_b128 v[178:181], v190 offset:5120
	ds_read_b128 v[182:185], v190 offset:6144
	ds_read_b128 v[186:189], v190 offset:7168
	s_waitcnt lgkmcnt(0)
	s_waitcnt vmcnt(8)
	s_barrier
	s_add_i32 m0, s44, 0x0
	s_nop 0
	global_load_lds_dwordx4 v250, s[0:1]
	s_add_i32 m0, s44, 0x2000
	s_nop 0
	global_load_lds_dwordx4 v251, s[0:1]
	s_add_i32 m0, s45, 0x0
	s_nop 0
	global_load_lds_dwordx4 v0, s[16:17]
	s_add_i32 m0, s45, 0x2000
	s_nop 0
	global_load_lds_dwordx4 v154, s[16:17]
	s_add_u32 s0, s0, 0x80
	s_addc_u32 s1, s1, 0
	s_add_u32 s16, s16, 0x80
	s_addc_u32 s17, s17, 0
	v_mfma_f32_16x16x32_bf16 v[126:129], v[130:133], v[146:149], v[126:129]
	v_mfma_f32_16x16x32_bf16 v[122:125], v[138:141], v[146:149], v[122:125]
	v_mfma_f32_16x16x32_bf16 v[118:121], v[130:133], v[166:169], v[118:121]
	v_mfma_f32_16x16x32_bf16 v[114:117], v[138:141], v[166:169], v[114:117]
	v_mfma_f32_16x16x32_bf16 v[110:113], v[130:133], v[174:177], v[110:113]
	v_mfma_f32_16x16x32_bf16 v[106:109], v[138:141], v[174:177], v[106:109]
	v_mfma_f32_16x16x32_bf16 v[102:105], v[130:133], v[182:185], v[102:105]
	v_mfma_f32_16x16x32_bf16 v[98:101], v[138:141], v[182:185], v[98:101]
	v_mfma_f32_16x16x32_bf16 v[126:129], v[134:137], v[150:153], v[126:129]
	v_mfma_f32_16x16x32_bf16 v[122:125], v[142:145], v[150:153], v[122:125]
	v_mfma_f32_16x16x32_bf16 v[118:121], v[134:137], v[170:173], v[118:121]
	v_mfma_f32_16x16x32_bf16 v[114:117], v[142:145], v[170:173], v[114:117]
	v_mfma_f32_16x16x32_bf16 v[110:113], v[134:137], v[178:181], v[110:113]
	v_mfma_f32_16x16x32_bf16 v[106:109], v[142:145], v[178:181], v[106:109]
	v_mfma_f32_16x16x32_bf16 v[102:105], v[134:137], v[186:189], v[102:105]
	v_mfma_f32_16x16x32_bf16 v[98:101], v[142:145], v[186:189], v[98:101]
	ds_read_b128 v[130:133], v191 offset:32768
	ds_read_b128 v[134:137], v191 offset:33792
	ds_read_b128 v[138:141], v191 offset:34816
	ds_read_b128 v[142:145], v191 offset:35840
	ds_read_b128 v[146:149], v190 offset:32768
	ds_read_b128 v[150:153], v190 offset:33792
	ds_read_b128 v[166:169], v190 offset:34816
	ds_read_b128 v[170:173], v190 offset:35840
	ds_read_b128 v[174:177], v190 offset:36864
	ds_read_b128 v[178:181], v190 offset:37888
	ds_read_b128 v[182:185], v190 offset:38912
	ds_read_b128 v[186:189], v190 offset:39936
	s_waitcnt lgkmcnt(0)
	s_waitcnt vmcnt(8)
	s_barrier
	s_add_i32 m0, s44, 0x8000
	s_nop 0
	global_load_lds_dwordx4 v250, s[0:1]
	s_add_i32 m0, s44, 0xa000
	s_nop 0
	global_load_lds_dwordx4 v251, s[0:1]
	s_add_i32 m0, s45, 0x8000
	s_nop 0
	global_load_lds_dwordx4 v0, s[16:17]
	s_add_i32 m0, s45, 0xa000
	s_nop 0
	global_load_lds_dwordx4 v154, s[16:17]
	s_add_u32 s0, s0, 0x80
	s_addc_u32 s1, s1, 0
	s_add_u32 s16, s16, 0x80
	s_addc_u32 s17, s17, 0
	s_nop 0
	v_mfma_f32_16x16x32_bf16 v[126:129], v[130:133], v[146:149], v[126:129]
	v_mfma_f32_16x16x32_bf16 v[122:125], v[138:141], v[146:149], v[122:125]
	v_mfma_f32_16x16x32_bf16 v[118:121], v[130:133], v[166:169], v[118:121]
	v_mfma_f32_16x16x32_bf16 v[114:117], v[138:141], v[166:169], v[114:117]
	v_mfma_f32_16x16x32_bf16 v[110:113], v[130:133], v[174:177], v[110:113]
	v_mfma_f32_16x16x32_bf16 v[106:109], v[138:141], v[174:177], v[106:109]
	v_mfma_f32_16x16x32_bf16 v[102:105], v[130:133], v[182:185], v[102:105]
	v_mfma_f32_16x16x32_bf16 v[98:101], v[138:141], v[182:185], v[98:101]
	v_mfma_f32_16x16x32_bf16 v[126:129], v[134:137], v[150:153], v[126:129]
	v_mfma_f32_16x16x32_bf16 v[122:125], v[142:145], v[150:153], v[122:125]
	v_mfma_f32_16x16x32_bf16 v[118:121], v[134:137], v[170:173], v[118:121]
	v_mfma_f32_16x16x32_bf16 v[114:117], v[142:145], v[170:173], v[114:117]
	v_mfma_f32_16x16x32_bf16 v[110:113], v[134:137], v[178:181], v[110:113]
	v_mfma_f32_16x16x32_bf16 v[106:109], v[142:145], v[178:181], v[106:109]
	v_mfma_f32_16x16x32_bf16 v[102:105], v[134:137], v[186:189], v[102:105]
	v_mfma_f32_16x16x32_bf16 v[98:101], v[142:145], v[186:189], v[98:101]
	ds_read_b128 v[130:133], v193 offset:0
	ds_read_b128 v[134:137], v193 offset:1024
	ds_read_b128 v[138:141], v193 offset:2048
	ds_read_b128 v[142:145], v193 offset:3072
	ds_read_b128 v[146:149], v192 offset:0
	ds_read_b128 v[150:153], v192 offset:1024
	ds_read_b128 v[166:169], v192 offset:2048
	ds_read_b128 v[170:173], v192 offset:3072
	ds_read_b128 v[174:177], v192 offset:4096
	ds_read_b128 v[178:181], v192 offset:5120
	ds_read_b128 v[182:185], v192 offset:6144
	ds_read_b128 v[186:189], v192 offset:7168
	s_waitcnt lgkmcnt(0)
	s_waitcnt vmcnt(8)
	s_barrier
	s_add_i32 m0, s46, 0x0
	s_nop 0
	global_load_lds_dwordx4 v250, s[0:1]
	s_add_i32 m0, s46, 0x2000
	s_nop 0
	global_load_lds_dwordx4 v251, s[0:1]
	s_add_i32 m0, s47, 0x0
	s_nop 0
	global_load_lds_dwordx4 v0, s[16:17]
	s_add_i32 m0, s47, 0x2000
	s_nop 0
	global_load_lds_dwordx4 v154, s[16:17]
	s_add_u32 s0, s0, 0x80
	s_addc_u32 s1, s1, 0
	s_add_u32 s16, s16, 0x80
	s_addc_u32 s17, s17, 0
	s_nop 0
	v_mfma_f32_16x16x32_bf16 v[126:129], v[130:133], v[146:149], v[126:129]
	v_mfma_f32_16x16x32_bf16 v[122:125], v[138:141], v[146:149], v[122:125]
	v_mfma_f32_16x16x32_bf16 v[118:121], v[130:133], v[166:169], v[118:121]
	v_mfma_f32_16x16x32_bf16 v[114:117], v[138:141], v[166:169], v[114:117]
	v_mfma_f32_16x16x32_bf16 v[110:113], v[130:133], v[174:177], v[110:113]
	v_mfma_f32_16x16x32_bf16 v[106:109], v[138:141], v[174:177], v[106:109]
	v_mfma_f32_16x16x32_bf16 v[102:105], v[130:133], v[182:185], v[102:105]
	v_mfma_f32_16x16x32_bf16 v[98:101], v[138:141], v[182:185], v[98:101]
	v_mfma_f32_16x16x32_bf16 v[126:129], v[134:137], v[150:153], v[126:129]
	v_mfma_f32_16x16x32_bf16 v[122:125], v[142:145], v[150:153], v[122:125]
	v_mfma_f32_16x16x32_bf16 v[118:121], v[134:137], v[170:173], v[118:121]
	v_mfma_f32_16x16x32_bf16 v[114:117], v[142:145], v[170:173], v[114:117]
	v_mfma_f32_16x16x32_bf16 v[110:113], v[134:137], v[178:181], v[110:113]
	v_mfma_f32_16x16x32_bf16 v[106:109], v[142:145], v[178:181], v[106:109]
	v_mfma_f32_16x16x32_bf16 v[102:105], v[134:137], v[186:189], v[102:105]
	v_mfma_f32_16x16x32_bf16 v[98:101], v[142:145], v[186:189], v[98:101]
	ds_read_b128 v[130:133], v193 offset:32768
	ds_read_b128 v[134:137], v193 offset:33792
	ds_read_b128 v[138:141], v193 offset:34816
	ds_read_b128 v[142:145], v193 offset:35840
	ds_read_b128 v[146:149], v192 offset:32768
	ds_read_b128 v[150:153], v192 offset:33792
	ds_read_b128 v[166:169], v192 offset:34816
	ds_read_b128 v[170:173], v192 offset:35840
	ds_read_b128 v[174:177], v192 offset:36864
	ds_read_b128 v[178:181], v192 offset:37888
	ds_read_b128 v[182:185], v192 offset:38912
	ds_read_b128 v[186:189], v192 offset:39936
	s_waitcnt lgkmcnt(0)
	s_waitcnt vmcnt(8)
	s_barrier
	s_add_i32 m0, s46, 0x8000
	s_nop 0
	global_load_lds_dwordx4 v250, s[0:1]
	s_add_i32 m0, s46, 0xa000
	s_nop 0
	global_load_lds_dwordx4 v251, s[0:1]
	s_add_i32 m0, s47, 0x8000
	s_nop 0
	global_load_lds_dwordx4 v0, s[16:17]
	s_add_i32 m0, s47, 0xa000
	s_nop 0
	global_load_lds_dwordx4 v154, s[16:17]
	s_add_u32 s0, s0, 0x80
	s_addc_u32 s1, s1, 0
	s_add_u32 s16, s16, 0x80
	s_addc_u32 s17, s17, 0
	s_nop 0
	v_mfma_f32_16x16x32_bf16 v[126:129], v[130:133], v[146:149], v[126:129]
	v_mfma_f32_16x16x32_bf16 v[122:125], v[138:141], v[146:149], v[122:125]
	v_mfma_f32_16x16x32_bf16 v[118:121], v[130:133], v[166:169], v[118:121]
	v_mfma_f32_16x16x32_bf16 v[114:117], v[138:141], v[166:169], v[114:117]
	v_mfma_f32_16x16x32_bf16 v[110:113], v[130:133], v[174:177], v[110:113]
	v_mfma_f32_16x16x32_bf16 v[106:109], v[138:141], v[174:177], v[106:109]
	v_mfma_f32_16x16x32_bf16 v[102:105], v[130:133], v[182:185], v[102:105]
	v_mfma_f32_16x16x32_bf16 v[98:101], v[138:141], v[182:185], v[98:101]
	v_mfma_f32_16x16x32_bf16 v[126:129], v[134:137], v[150:153], v[126:129]
	v_mfma_f32_16x16x32_bf16 v[122:125], v[142:145], v[150:153], v[122:125]
	v_mfma_f32_16x16x32_bf16 v[118:121], v[134:137], v[170:173], v[118:121]
	v_mfma_f32_16x16x32_bf16 v[114:117], v[142:145], v[170:173], v[114:117]
	v_mfma_f32_16x16x32_bf16 v[110:113], v[134:137], v[178:181], v[110:113]
	v_mfma_f32_16x16x32_bf16 v[106:109], v[142:145], v[178:181], v[106:109]
	v_mfma_f32_16x16x32_bf16 v[102:105], v[134:137], v[186:189], v[102:105]
	v_mfma_f32_16x16x32_bf16 v[98:101], v[142:145], v[186:189], v[98:101]
	ds_read_b128 v[130:133], v191 offset:0
	ds_read_b128 v[134:137], v191 offset:1024
	ds_read_b128 v[138:141], v191 offset:2048
	ds_read_b128 v[142:145], v191 offset:3072
	ds_read_b128 v[146:149], v190 offset:0
	ds_read_b128 v[150:153], v190 offset:1024
	ds_read_b128 v[166:169], v190 offset:2048
	ds_read_b128 v[170:173], v190 offset:3072
	ds_read_b128 v[174:177], v190 offset:4096
	ds_read_b128 v[178:181], v190 offset:5120
	ds_read_b128 v[182:185], v190 offset:6144
	ds_read_b128 v[186:189], v190 offset:7168
	s_waitcnt lgkmcnt(0)
	s_waitcnt vmcnt(8)
	s_barrier
	s_add_i32 m0, s44, 0x0
	s_nop 0
	global_load_lds_dwordx4 v250, s[0:1]
	s_add_i32 m0, s44, 0x2000
	s_nop 0
	global_load_lds_dwordx4 v251, s[0:1]
	s_add_i32 m0, s45, 0x0
	s_nop 0
	global_load_lds_dwordx4 v0, s[16:17]
	s_add_i32 m0, s45, 0x2000
	s_nop 0
	global_load_lds_dwordx4 v154, s[16:17]
	s_add_u32 s0, s0, 0x80
	s_addc_u32 s1, s1, 0
	s_add_u32 s16, s16, 0x80
	s_addc_u32 s17, s17, 0
	s_nop 0
	v_mfma_f32_16x16x32_bf16 v[126:129], v[130:133], v[146:149], v[126:129]
	v_mfma_f32_16x16x32_bf16 v[122:125], v[138:141], v[146:149], v[122:125]
	v_mfma_f32_16x16x32_bf16 v[118:121], v[130:133], v[166:169], v[118:121]
	v_mfma_f32_16x16x32_bf16 v[114:117], v[138:141], v[166:169], v[114:117]
	v_mfma_f32_16x16x32_bf16 v[110:113], v[130:133], v[174:177], v[110:113]
	v_mfma_f32_16x16x32_bf16 v[106:109], v[138:141], v[174:177], v[106:109]
	v_mfma_f32_16x16x32_bf16 v[102:105], v[130:133], v[182:185], v[102:105]
	v_mfma_f32_16x16x32_bf16 v[98:101], v[138:141], v[182:185], v[98:101]
	v_mfma_f32_16x16x32_bf16 v[126:129], v[134:137], v[150:153], v[126:129]
	v_mfma_f32_16x16x32_bf16 v[122:125], v[142:145], v[150:153], v[122:125]
	v_mfma_f32_16x16x32_bf16 v[118:121], v[134:137], v[170:173], v[118:121]
	v_mfma_f32_16x16x32_bf16 v[114:117], v[142:145], v[170:173], v[114:117]
	v_mfma_f32_16x16x32_bf16 v[110:113], v[134:137], v[178:181], v[110:113]
	v_mfma_f32_16x16x32_bf16 v[106:109], v[142:145], v[178:181], v[106:109]
	v_mfma_f32_16x16x32_bf16 v[102:105], v[134:137], v[186:189], v[102:105]
	v_mfma_f32_16x16x32_bf16 v[98:101], v[142:145], v[186:189], v[98:101]
	ds_read_b128 v[130:133], v191 offset:32768
	ds_read_b128 v[134:137], v191 offset:33792
	ds_read_b128 v[138:141], v191 offset:34816
	ds_read_b128 v[142:145], v191 offset:35840
	ds_read_b128 v[146:149], v190 offset:32768
	ds_read_b128 v[150:153], v190 offset:33792
	ds_read_b128 v[166:169], v190 offset:34816
	ds_read_b128 v[170:173], v190 offset:35840
	ds_read_b128 v[174:177], v190 offset:36864
	ds_read_b128 v[178:181], v190 offset:37888
	ds_read_b128 v[182:185], v190 offset:38912
	ds_read_b128 v[186:189], v190 offset:39936
	s_waitcnt lgkmcnt(0)
	s_waitcnt vmcnt(8)
	s_barrier
	s_add_i32 m0, s44, 0x8000
	s_nop 0
	global_load_lds_dwordx4 v250, s[0:1]
	s_add_i32 m0, s44, 0xa000
	s_nop 0
	global_load_lds_dwordx4 v251, s[0:1]
	s_add_i32 m0, s45, 0x8000
	s_nop 0
	global_load_lds_dwordx4 v0, s[16:17]
	s_add_i32 m0, s45, 0xa000
	s_nop 0
	global_load_lds_dwordx4 v154, s[16:17]
	s_add_u32 s0, s0, 0x80
	s_addc_u32 s1, s1, 0
	s_add_u32 s16, s16, 0x80
	s_addc_u32 s17, s17, 0
	s_nop 0
	v_mfma_f32_16x16x32_bf16 v[126:129], v[130:133], v[146:149], v[126:129]
	v_mfma_f32_16x16x32_bf16 v[122:125], v[138:141], v[146:149], v[122:125]
	v_mfma_f32_16x16x32_bf16 v[118:121], v[130:133], v[166:169], v[118:121]
	v_mfma_f32_16x16x32_bf16 v[114:117], v[138:141], v[166:169], v[114:117]
	v_mfma_f32_16x16x32_bf16 v[110:113], v[130:133], v[174:177], v[110:113]
	v_mfma_f32_16x16x32_bf16 v[106:109], v[138:141], v[174:177], v[106:109]
	v_mfma_f32_16x16x32_bf16 v[102:105], v[130:133], v[182:185], v[102:105]
	v_mfma_f32_16x16x32_bf16 v[98:101], v[138:141], v[182:185], v[98:101]
	v_mfma_f32_16x16x32_bf16 v[126:129], v[134:137], v[150:153], v[126:129]
	v_mfma_f32_16x16x32_bf16 v[122:125], v[142:145], v[150:153], v[122:125]
	v_mfma_f32_16x16x32_bf16 v[118:121], v[134:137], v[170:173], v[118:121]
	v_mfma_f32_16x16x32_bf16 v[114:117], v[142:145], v[170:173], v[114:117]
	v_mfma_f32_16x16x32_bf16 v[110:113], v[134:137], v[178:181], v[110:113]
	v_mfma_f32_16x16x32_bf16 v[106:109], v[142:145], v[178:181], v[106:109]
	v_mfma_f32_16x16x32_bf16 v[102:105], v[134:137], v[186:189], v[102:105]
	v_mfma_f32_16x16x32_bf16 v[98:101], v[142:145], v[186:189], v[98:101]
	ds_read_b128 v[130:133], v193 offset:0
	ds_read_b128 v[134:137], v193 offset:1024
	ds_read_b128 v[138:141], v193 offset:2048
	ds_read_b128 v[142:145], v193 offset:3072
	ds_read_b128 v[146:149], v192 offset:0
	ds_read_b128 v[150:153], v192 offset:1024
	ds_read_b128 v[166:169], v192 offset:2048
	ds_read_b128 v[170:173], v192 offset:3072
	ds_read_b128 v[174:177], v192 offset:4096
	ds_read_b128 v[178:181], v192 offset:5120
	ds_read_b128 v[182:185], v192 offset:6144
	ds_read_b128 v[186:189], v192 offset:7168
	s_waitcnt lgkmcnt(0)
	s_waitcnt vmcnt(8)
	s_barrier
	s_add_i32 m0, s46, 0x0
	s_nop 0
	global_load_lds_dwordx4 v250, s[0:1]
	s_add_i32 m0, s46, 0x2000
	s_nop 0
	global_load_lds_dwordx4 v251, s[0:1]
	s_add_i32 m0, s47, 0x0
	s_nop 0
	global_load_lds_dwordx4 v0, s[16:17]
	s_add_i32 m0, s47, 0x2000
	s_nop 0
	global_load_lds_dwordx4 v154, s[16:17]
	s_add_u32 s0, s0, 0x80
	s_addc_u32 s1, s1, 0
	s_add_u32 s16, s16, 0x80
	s_addc_u32 s17, s17, 0
	s_nop 0
	v_mfma_f32_16x16x32_bf16 v[126:129], v[130:133], v[146:149], v[126:129]
	v_mfma_f32_16x16x32_bf16 v[122:125], v[138:141], v[146:149], v[122:125]
	v_mfma_f32_16x16x32_bf16 v[118:121], v[130:133], v[166:169], v[118:121]
	v_mfma_f32_16x16x32_bf16 v[114:117], v[138:141], v[166:169], v[114:117]
	v_mfma_f32_16x16x32_bf16 v[110:113], v[130:133], v[174:177], v[110:113]
	v_mfma_f32_16x16x32_bf16 v[106:109], v[138:141], v[174:177], v[106:109]
	v_mfma_f32_16x16x32_bf16 v[102:105], v[130:133], v[182:185], v[102:105]
	v_mfma_f32_16x16x32_bf16 v[98:101], v[138:141], v[182:185], v[98:101]
	v_mfma_f32_16x16x32_bf16 v[126:129], v[134:137], v[150:153], v[126:129]
	v_mfma_f32_16x16x32_bf16 v[122:125], v[142:145], v[150:153], v[122:125]
	v_mfma_f32_16x16x32_bf16 v[118:121], v[134:137], v[170:173], v[118:121]
	v_mfma_f32_16x16x32_bf16 v[114:117], v[142:145], v[170:173], v[114:117]
	v_mfma_f32_16x16x32_bf16 v[110:113], v[134:137], v[178:181], v[110:113]
	v_mfma_f32_16x16x32_bf16 v[106:109], v[142:145], v[178:181], v[106:109]
	v_mfma_f32_16x16x32_bf16 v[102:105], v[134:137], v[186:189], v[102:105]
	v_mfma_f32_16x16x32_bf16 v[98:101], v[142:145], v[186:189], v[98:101]
	ds_read_b128 v[130:133], v193 offset:32768
	ds_read_b128 v[134:137], v193 offset:33792
	ds_read_b128 v[138:141], v193 offset:34816
	ds_read_b128 v[142:145], v193 offset:35840
	ds_read_b128 v[146:149], v192 offset:32768
	ds_read_b128 v[150:153], v192 offset:33792
	ds_read_b128 v[166:169], v192 offset:34816
	ds_read_b128 v[170:173], v192 offset:35840
	ds_read_b128 v[174:177], v192 offset:36864
	ds_read_b128 v[178:181], v192 offset:37888
	ds_read_b128 v[182:185], v192 offset:38912
	ds_read_b128 v[186:189], v192 offset:39936
	s_waitcnt lgkmcnt(0)
	s_waitcnt vmcnt(8)
	s_barrier
	s_add_i32 m0, s46, 0x8000
	s_nop 0
	global_load_lds_dwordx4 v250, s[0:1]
	s_add_i32 m0, s46, 0xa000
	s_nop 0
	global_load_lds_dwordx4 v251, s[0:1]
	s_add_i32 m0, s47, 0x8000
	s_nop 0
	global_load_lds_dwordx4 v0, s[16:17]
	s_add_i32 m0, s47, 0xa000
	s_nop 0
	global_load_lds_dwordx4 v154, s[16:17]
	s_add_u32 s0, s0, 0x80
	s_addc_u32 s1, s1, 0
	s_add_u32 s16, s16, 0x80
	s_addc_u32 s17, s17, 0
	s_nop 0
	v_mfma_f32_16x16x32_bf16 v[126:129], v[130:133], v[146:149], v[126:129]
	v_mfma_f32_16x16x32_bf16 v[122:125], v[138:141], v[146:149], v[122:125]
	v_mfma_f32_16x16x32_bf16 v[118:121], v[130:133], v[166:169], v[118:121]
	v_mfma_f32_16x16x32_bf16 v[114:117], v[138:141], v[166:169], v[114:117]
	v_mfma_f32_16x16x32_bf16 v[110:113], v[130:133], v[174:177], v[110:113]
	v_mfma_f32_16x16x32_bf16 v[106:109], v[138:141], v[174:177], v[106:109]
	v_mfma_f32_16x16x32_bf16 v[102:105], v[130:133], v[182:185], v[102:105]
	v_mfma_f32_16x16x32_bf16 v[98:101], v[138:141], v[182:185], v[98:101]
	v_mfma_f32_16x16x32_bf16 v[126:129], v[134:137], v[150:153], v[126:129]
	v_mfma_f32_16x16x32_bf16 v[122:125], v[142:145], v[150:153], v[122:125]
	v_mfma_f32_16x16x32_bf16 v[118:121], v[134:137], v[170:173], v[118:121]
	v_mfma_f32_16x16x32_bf16 v[114:117], v[142:145], v[170:173], v[114:117]
	v_mfma_f32_16x16x32_bf16 v[110:113], v[134:137], v[178:181], v[110:113]
	v_mfma_f32_16x16x32_bf16 v[106:109], v[142:145], v[178:181], v[106:109]
	v_mfma_f32_16x16x32_bf16 v[102:105], v[134:137], v[186:189], v[102:105]
	v_mfma_f32_16x16x32_bf16 v[98:101], v[142:145], v[186:189], v[98:101]
	ds_read_b128 v[130:133], v191 offset:0
	ds_read_b128 v[134:137], v191 offset:1024
	ds_read_b128 v[138:141], v191 offset:2048
	ds_read_b128 v[142:145], v191 offset:3072
	ds_read_b128 v[146:149], v190 offset:0
	ds_read_b128 v[150:153], v190 offset:1024
	ds_read_b128 v[166:169], v190 offset:2048
	ds_read_b128 v[170:173], v190 offset:3072
	ds_read_b128 v[174:177], v190 offset:4096
	ds_read_b128 v[178:181], v190 offset:5120
	ds_read_b128 v[182:185], v190 offset:6144
	ds_read_b128 v[186:189], v190 offset:7168
	s_waitcnt lgkmcnt(0)
	s_waitcnt vmcnt(8)
	s_barrier
	s_add_i32 m0, s44, 0x0
	s_nop 0
	global_load_lds_dwordx4 v250, s[0:1]
	s_add_i32 m0, s44, 0x2000
	s_nop 0
	global_load_lds_dwordx4 v251, s[0:1]
	s_add_i32 m0, s45, 0x0
	s_nop 0
	global_load_lds_dwordx4 v0, s[16:17]
	s_add_i32 m0, s45, 0x2000
	s_nop 0
	global_load_lds_dwordx4 v154, s[16:17]
	s_add_u32 s0, s0, 0x80
	s_addc_u32 s1, s1, 0
	s_add_u32 s16, s16, 0x80
	s_addc_u32 s17, s17, 0
	s_nop 0
	v_mfma_f32_16x16x32_bf16 v[126:129], v[130:133], v[146:149], v[126:129]
	v_mfma_f32_16x16x32_bf16 v[122:125], v[138:141], v[146:149], v[122:125]
	v_mfma_f32_16x16x32_bf16 v[118:121], v[130:133], v[166:169], v[118:121]
	v_mfma_f32_16x16x32_bf16 v[114:117], v[138:141], v[166:169], v[114:117]
	v_mfma_f32_16x16x32_bf16 v[110:113], v[130:133], v[174:177], v[110:113]
	v_mfma_f32_16x16x32_bf16 v[106:109], v[138:141], v[174:177], v[106:109]
	v_mfma_f32_16x16x32_bf16 v[102:105], v[130:133], v[182:185], v[102:105]
	v_mfma_f32_16x16x32_bf16 v[98:101], v[138:141], v[182:185], v[98:101]
	v_mfma_f32_16x16x32_bf16 v[126:129], v[134:137], v[150:153], v[126:129]
	v_mfma_f32_16x16x32_bf16 v[122:125], v[142:145], v[150:153], v[122:125]
	v_mfma_f32_16x16x32_bf16 v[118:121], v[134:137], v[170:173], v[118:121]
	v_mfma_f32_16x16x32_bf16 v[114:117], v[142:145], v[170:173], v[114:117]
	v_mfma_f32_16x16x32_bf16 v[110:113], v[134:137], v[178:181], v[110:113]
	v_mfma_f32_16x16x32_bf16 v[106:109], v[142:145], v[178:181], v[106:109]
	v_mfma_f32_16x16x32_bf16 v[102:105], v[134:137], v[186:189], v[102:105]
	v_mfma_f32_16x16x32_bf16 v[98:101], v[142:145], v[186:189], v[98:101]
	ds_read_b128 v[130:133], v191 offset:32768
	ds_read_b128 v[134:137], v191 offset:33792
	ds_read_b128 v[138:141], v191 offset:34816
	ds_read_b128 v[142:145], v191 offset:35840
	ds_read_b128 v[146:149], v190 offset:32768
	ds_read_b128 v[150:153], v190 offset:33792
	ds_read_b128 v[166:169], v190 offset:34816
	ds_read_b128 v[170:173], v190 offset:35840
	ds_read_b128 v[174:177], v190 offset:36864
	ds_read_b128 v[178:181], v190 offset:37888
	ds_read_b128 v[182:185], v190 offset:38912
	ds_read_b128 v[186:189], v190 offset:39936
	s_waitcnt lgkmcnt(0)
	s_waitcnt vmcnt(8)
	s_barrier
	s_add_i32 m0, s44, 0x8000
	s_nop 0
	global_load_lds_dwordx4 v250, s[0:1]
	s_add_i32 m0, s44, 0xa000
	s_nop 0
	global_load_lds_dwordx4 v251, s[0:1]
	s_add_i32 m0, s45, 0x8000
	s_nop 0
	global_load_lds_dwordx4 v0, s[16:17]
	s_add_i32 m0, s45, 0xa000
	s_nop 0
	global_load_lds_dwordx4 v154, s[16:17]
	s_add_u32 s0, s0, 0x80
	s_addc_u32 s1, s1, 0
	s_add_u32 s16, s16, 0x80
	s_addc_u32 s17, s17, 0
	s_nop 0
	v_mfma_f32_16x16x32_bf16 v[126:129], v[130:133], v[146:149], v[126:129]
	v_mfma_f32_16x16x32_bf16 v[122:125], v[138:141], v[146:149], v[122:125]
	v_mfma_f32_16x16x32_bf16 v[118:121], v[130:133], v[166:169], v[118:121]
	v_mfma_f32_16x16x32_bf16 v[114:117], v[138:141], v[166:169], v[114:117]
	v_mfma_f32_16x16x32_bf16 v[110:113], v[130:133], v[174:177], v[110:113]
	v_mfma_f32_16x16x32_bf16 v[106:109], v[138:141], v[174:177], v[106:109]
	v_mfma_f32_16x16x32_bf16 v[102:105], v[130:133], v[182:185], v[102:105]
	v_mfma_f32_16x16x32_bf16 v[98:101], v[138:141], v[182:185], v[98:101]
	v_mfma_f32_16x16x32_bf16 v[126:129], v[134:137], v[150:153], v[126:129]
	v_mfma_f32_16x16x32_bf16 v[122:125], v[142:145], v[150:153], v[122:125]
	v_mfma_f32_16x16x32_bf16 v[118:121], v[134:137], v[170:173], v[118:121]
	v_mfma_f32_16x16x32_bf16 v[114:117], v[142:145], v[170:173], v[114:117]
	v_mfma_f32_16x16x32_bf16 v[110:113], v[134:137], v[178:181], v[110:113]
	v_mfma_f32_16x16x32_bf16 v[106:109], v[142:145], v[178:181], v[106:109]
	v_mfma_f32_16x16x32_bf16 v[102:105], v[134:137], v[186:189], v[102:105]
	v_mfma_f32_16x16x32_bf16 v[98:101], v[142:145], v[186:189], v[98:101]
	ds_read_b128 v[130:133], v193 offset:0
	ds_read_b128 v[134:137], v193 offset:1024
	ds_read_b128 v[138:141], v193 offset:2048
	ds_read_b128 v[142:145], v193 offset:3072
	ds_read_b128 v[146:149], v192 offset:0
	ds_read_b128 v[150:153], v192 offset:1024
	ds_read_b128 v[166:169], v192 offset:2048
	ds_read_b128 v[170:173], v192 offset:3072
	ds_read_b128 v[174:177], v192 offset:4096
	ds_read_b128 v[178:181], v192 offset:5120
	ds_read_b128 v[182:185], v192 offset:6144
	ds_read_b128 v[186:189], v192 offset:7168
	s_waitcnt lgkmcnt(0)
	s_waitcnt vmcnt(8)
	s_barrier
	s_add_i32 m0, s46, 0x0
	s_nop 0
	global_load_lds_dwordx4 v250, s[0:1]
	s_add_i32 m0, s46, 0x2000
	s_nop 0
	global_load_lds_dwordx4 v251, s[0:1]
	s_add_i32 m0, s47, 0x0
	s_nop 0
	global_load_lds_dwordx4 v0, s[16:17]
	s_add_i32 m0, s47, 0x2000
	s_nop 0
	global_load_lds_dwordx4 v154, s[16:17]
	s_add_u32 s0, s0, 0x80
	s_addc_u32 s1, s1, 0
	s_add_u32 s16, s16, 0x80
	s_addc_u32 s17, s17, 0
	s_nop 0
	v_mfma_f32_16x16x32_bf16 v[126:129], v[130:133], v[146:149], v[126:129]
	v_mfma_f32_16x16x32_bf16 v[122:125], v[138:141], v[146:149], v[122:125]
	v_mfma_f32_16x16x32_bf16 v[118:121], v[130:133], v[166:169], v[118:121]
	v_mfma_f32_16x16x32_bf16 v[114:117], v[138:141], v[166:169], v[114:117]
	v_mfma_f32_16x16x32_bf16 v[110:113], v[130:133], v[174:177], v[110:113]
	v_mfma_f32_16x16x32_bf16 v[106:109], v[138:141], v[174:177], v[106:109]
	v_mfma_f32_16x16x32_bf16 v[102:105], v[130:133], v[182:185], v[102:105]
	v_mfma_f32_16x16x32_bf16 v[98:101], v[138:141], v[182:185], v[98:101]
	v_mfma_f32_16x16x32_bf16 v[126:129], v[134:137], v[150:153], v[126:129]
	v_mfma_f32_16x16x32_bf16 v[122:125], v[142:145], v[150:153], v[122:125]
	v_mfma_f32_16x16x32_bf16 v[118:121], v[134:137], v[170:173], v[118:121]
	v_mfma_f32_16x16x32_bf16 v[114:117], v[142:145], v[170:173], v[114:117]
	v_mfma_f32_16x16x32_bf16 v[110:113], v[134:137], v[178:181], v[110:113]
	v_mfma_f32_16x16x32_bf16 v[106:109], v[142:145], v[178:181], v[106:109]
	v_mfma_f32_16x16x32_bf16 v[102:105], v[134:137], v[186:189], v[102:105]
	v_mfma_f32_16x16x32_bf16 v[98:101], v[142:145], v[186:189], v[98:101]
	ds_read_b128 v[130:133], v193 offset:32768
	ds_read_b128 v[134:137], v193 offset:33792
	ds_read_b128 v[138:141], v193 offset:34816
	ds_read_b128 v[142:145], v193 offset:35840
	ds_read_b128 v[146:149], v192 offset:32768
	ds_read_b128 v[150:153], v192 offset:33792
	ds_read_b128 v[166:169], v192 offset:34816
	ds_read_b128 v[170:173], v192 offset:35840
	ds_read_b128 v[174:177], v192 offset:36864
	ds_read_b128 v[178:181], v192 offset:37888
	ds_read_b128 v[182:185], v192 offset:38912
	ds_read_b128 v[186:189], v192 offset:39936
	s_waitcnt lgkmcnt(0)
	s_waitcnt vmcnt(8)
	s_barrier
	s_add_i32 m0, s46, 0x8000
	s_nop 0
	global_load_lds_dwordx4 v250, s[0:1]
	s_add_i32 m0, s46, 0xa000
	s_nop 0
	global_load_lds_dwordx4 v251, s[0:1]
	s_add_i32 m0, s47, 0x8000
	s_nop 0
	global_load_lds_dwordx4 v0, s[16:17]
	s_add_i32 m0, s47, 0xa000
	s_nop 0
	global_load_lds_dwordx4 v154, s[16:17]
	s_add_u32 s0, s0, 0x80
	s_addc_u32 s1, s1, 0
	s_add_u32 s16, s16, 0x80
	s_addc_u32 s17, s17, 0
	s_nop 0
	v_mfma_f32_16x16x32_bf16 v[126:129], v[130:133], v[146:149], v[126:129]
	v_mfma_f32_16x16x32_bf16 v[122:125], v[138:141], v[146:149], v[122:125]
	v_mfma_f32_16x16x32_bf16 v[118:121], v[130:133], v[166:169], v[118:121]
	v_mfma_f32_16x16x32_bf16 v[114:117], v[138:141], v[166:169], v[114:117]
	v_mfma_f32_16x16x32_bf16 v[110:113], v[130:133], v[174:177], v[110:113]
	v_mfma_f32_16x16x32_bf16 v[106:109], v[138:141], v[174:177], v[106:109]
	v_mfma_f32_16x16x32_bf16 v[102:105], v[130:133], v[182:185], v[102:105]
	v_mfma_f32_16x16x32_bf16 v[98:101], v[138:141], v[182:185], v[98:101]
	v_mfma_f32_16x16x32_bf16 v[126:129], v[134:137], v[150:153], v[126:129]
	v_mfma_f32_16x16x32_bf16 v[122:125], v[142:145], v[150:153], v[122:125]
	v_mfma_f32_16x16x32_bf16 v[118:121], v[134:137], v[170:173], v[118:121]
	v_mfma_f32_16x16x32_bf16 v[114:117], v[142:145], v[170:173], v[114:117]
	v_mfma_f32_16x16x32_bf16 v[110:113], v[134:137], v[178:181], v[110:113]
	v_mfma_f32_16x16x32_bf16 v[106:109], v[142:145], v[178:181], v[106:109]
	v_mfma_f32_16x16x32_bf16 v[102:105], v[134:137], v[186:189], v[102:105]
	v_mfma_f32_16x16x32_bf16 v[98:101], v[142:145], v[186:189], v[98:101]
	ds_read_b128 v[130:133], v191 offset:0
	ds_read_b128 v[134:137], v191 offset:1024
	ds_read_b128 v[138:141], v191 offset:2048
	ds_read_b128 v[142:145], v191 offset:3072
	ds_read_b128 v[146:149], v190 offset:0
	ds_read_b128 v[150:153], v190 offset:1024
	ds_read_b128 v[166:169], v190 offset:2048
	ds_read_b128 v[170:173], v190 offset:3072
	ds_read_b128 v[174:177], v190 offset:4096
	ds_read_b128 v[178:181], v190 offset:5120
	ds_read_b128 v[182:185], v190 offset:6144
	ds_read_b128 v[186:189], v190 offset:7168
	s_waitcnt lgkmcnt(0)
	s_waitcnt vmcnt(8)
	s_barrier
	s_nop 0
	v_mfma_f32_16x16x32_bf16 v[126:129], v[130:133], v[146:149], v[126:129]
	v_mfma_f32_16x16x32_bf16 v[122:125], v[138:141], v[146:149], v[122:125]
	v_mfma_f32_16x16x32_bf16 v[118:121], v[130:133], v[166:169], v[118:121]
	v_mfma_f32_16x16x32_bf16 v[114:117], v[138:141], v[166:169], v[114:117]
	v_mfma_f32_16x16x32_bf16 v[110:113], v[130:133], v[174:177], v[110:113]
	v_mfma_f32_16x16x32_bf16 v[106:109], v[138:141], v[174:177], v[106:109]
	v_mfma_f32_16x16x32_bf16 v[102:105], v[130:133], v[182:185], v[102:105]
	v_mfma_f32_16x16x32_bf16 v[98:101], v[138:141], v[182:185], v[98:101]
	v_mfma_f32_16x16x32_bf16 v[126:129], v[134:137], v[150:153], v[126:129]
	v_mfma_f32_16x16x32_bf16 v[122:125], v[142:145], v[150:153], v[122:125]
	v_mfma_f32_16x16x32_bf16 v[118:121], v[134:137], v[170:173], v[118:121]
	v_mfma_f32_16x16x32_bf16 v[114:117], v[142:145], v[170:173], v[114:117]
	v_mfma_f32_16x16x32_bf16 v[110:113], v[134:137], v[178:181], v[110:113]
	v_mfma_f32_16x16x32_bf16 v[106:109], v[142:145], v[178:181], v[106:109]
	v_mfma_f32_16x16x32_bf16 v[102:105], v[134:137], v[186:189], v[102:105]
	v_mfma_f32_16x16x32_bf16 v[98:101], v[142:145], v[186:189], v[98:101]
	ds_read_b128 v[130:133], v191 offset:32768
	ds_read_b128 v[134:137], v191 offset:33792
	ds_read_b128 v[138:141], v191 offset:34816
	ds_read_b128 v[142:145], v191 offset:35840
	ds_read_b128 v[146:149], v190 offset:32768
	ds_read_b128 v[150:153], v190 offset:33792
	ds_read_b128 v[166:169], v190 offset:34816
	ds_read_b128 v[170:173], v190 offset:35840
	ds_read_b128 v[174:177], v190 offset:36864
	ds_read_b128 v[178:181], v190 offset:37888
	ds_read_b128 v[182:185], v190 offset:38912
	ds_read_b128 v[186:189], v190 offset:39936
	s_waitcnt lgkmcnt(0)
	s_waitcnt vmcnt(4)
	s_barrier
	s_nop 0
	v_mfma_f32_16x16x32_bf16 v[126:129], v[130:133], v[146:149], v[126:129]
	v_mfma_f32_16x16x32_bf16 v[122:125], v[138:141], v[146:149], v[122:125]
	v_mfma_f32_16x16x32_bf16 v[118:121], v[130:133], v[166:169], v[118:121]
	v_mfma_f32_16x16x32_bf16 v[114:117], v[138:141], v[166:169], v[114:117]
	v_mfma_f32_16x16x32_bf16 v[110:113], v[130:133], v[174:177], v[110:113]
	v_mfma_f32_16x16x32_bf16 v[106:109], v[138:141], v[174:177], v[106:109]
	v_mfma_f32_16x16x32_bf16 v[102:105], v[130:133], v[182:185], v[102:105]
	v_mfma_f32_16x16x32_bf16 v[98:101], v[138:141], v[182:185], v[98:101]
	v_mfma_f32_16x16x32_bf16 v[126:129], v[134:137], v[150:153], v[126:129]
	v_mfma_f32_16x16x32_bf16 v[122:125], v[142:145], v[150:153], v[122:125]
	v_mfma_f32_16x16x32_bf16 v[118:121], v[134:137], v[170:173], v[118:121]
	v_mfma_f32_16x16x32_bf16 v[114:117], v[142:145], v[170:173], v[114:117]
	v_mfma_f32_16x16x32_bf16 v[110:113], v[134:137], v[178:181], v[110:113]
	v_mfma_f32_16x16x32_bf16 v[106:109], v[142:145], v[178:181], v[106:109]
	v_mfma_f32_16x16x32_bf16 v[102:105], v[134:137], v[186:189], v[102:105]
	v_mfma_f32_16x16x32_bf16 v[98:101], v[142:145], v[186:189], v[98:101]
	ds_read_b128 v[130:133], v193 offset:0
	ds_read_b128 v[134:137], v193 offset:1024
	ds_read_b128 v[138:141], v193 offset:2048
	ds_read_b128 v[142:145], v193 offset:3072
	ds_read_b128 v[146:149], v192 offset:0
	ds_read_b128 v[150:153], v192 offset:1024
	ds_read_b128 v[166:169], v192 offset:2048
	ds_read_b128 v[170:173], v192 offset:3072
	ds_read_b128 v[174:177], v192 offset:4096
	ds_read_b128 v[178:181], v192 offset:5120
	ds_read_b128 v[182:185], v192 offset:6144
	ds_read_b128 v[186:189], v192 offset:7168
	s_waitcnt lgkmcnt(0)
	s_waitcnt vmcnt(0)
	s_barrier
	s_nop 0
	v_mfma_f32_16x16x32_bf16 v[126:129], v[130:133], v[146:149], v[126:129]
	v_mfma_f32_16x16x32_bf16 v[122:125], v[138:141], v[146:149], v[122:125]
	v_mfma_f32_16x16x32_bf16 v[118:121], v[130:133], v[166:169], v[118:121]
	v_mfma_f32_16x16x32_bf16 v[114:117], v[138:141], v[166:169], v[114:117]
	v_mfma_f32_16x16x32_bf16 v[110:113], v[130:133], v[174:177], v[110:113]
	v_mfma_f32_16x16x32_bf16 v[106:109], v[138:141], v[174:177], v[106:109]
	v_mfma_f32_16x16x32_bf16 v[102:105], v[130:133], v[182:185], v[102:105]
	v_mfma_f32_16x16x32_bf16 v[98:101], v[138:141], v[182:185], v[98:101]
	v_mfma_f32_16x16x32_bf16 v[126:129], v[134:137], v[150:153], v[126:129]
	v_mfma_f32_16x16x32_bf16 v[122:125], v[142:145], v[150:153], v[122:125]
	v_mfma_f32_16x16x32_bf16 v[118:121], v[134:137], v[170:173], v[118:121]
	v_mfma_f32_16x16x32_bf16 v[114:117], v[142:145], v[170:173], v[114:117]
	v_mfma_f32_16x16x32_bf16 v[110:113], v[134:137], v[178:181], v[110:113]
	v_mfma_f32_16x16x32_bf16 v[106:109], v[142:145], v[178:181], v[106:109]
	v_mfma_f32_16x16x32_bf16 v[102:105], v[134:137], v[186:189], v[102:105]
	v_mfma_f32_16x16x32_bf16 v[98:101], v[142:145], v[186:189], v[98:101]
	ds_read_b128 v[130:133], v193 offset:32768
	ds_read_b128 v[134:137], v193 offset:33792
	ds_read_b128 v[138:141], v193 offset:34816
	ds_read_b128 v[142:145], v193 offset:35840
	ds_read_b128 v[146:149], v192 offset:32768
	ds_read_b128 v[150:153], v192 offset:33792
	ds_read_b128 v[166:169], v192 offset:34816
	ds_read_b128 v[170:173], v192 offset:35840
	ds_read_b128 v[174:177], v192 offset:36864
	ds_read_b128 v[178:181], v192 offset:37888
	ds_read_b128 v[182:185], v192 offset:38912
	ds_read_b128 v[186:189], v192 offset:39936
	s_waitcnt lgkmcnt(0)
	s_nop 0
	v_mfma_f32_16x16x32_bf16 v[126:129], v[130:133], v[146:149], v[126:129]
	v_mfma_f32_16x16x32_bf16 v[122:125], v[138:141], v[146:149], v[122:125]
	v_mfma_f32_16x16x32_bf16 v[118:121], v[130:133], v[166:169], v[118:121]
	v_mfma_f32_16x16x32_bf16 v[114:117], v[138:141], v[166:169], v[114:117]
	v_mfma_f32_16x16x32_bf16 v[110:113], v[130:133], v[174:177], v[110:113]
	v_mfma_f32_16x16x32_bf16 v[106:109], v[138:141], v[174:177], v[106:109]
	v_mfma_f32_16x16x32_bf16 v[102:105], v[130:133], v[182:185], v[102:105]
	v_mfma_f32_16x16x32_bf16 v[98:101], v[138:141], v[182:185], v[98:101]
	v_mfma_f32_16x16x32_bf16 v[126:129], v[134:137], v[150:153], v[126:129]
	v_mfma_f32_16x16x32_bf16 v[122:125], v[142:145], v[150:153], v[122:125]
	v_mfma_f32_16x16x32_bf16 v[118:121], v[134:137], v[170:173], v[118:121]
	v_mfma_f32_16x16x32_bf16 v[114:117], v[142:145], v[170:173], v[114:117]
	v_mfma_f32_16x16x32_bf16 v[110:113], v[134:137], v[178:181], v[110:113]
	v_mfma_f32_16x16x32_bf16 v[106:109], v[142:145], v[178:181], v[106:109]
	v_mfma_f32_16x16x32_bf16 v[102:105], v[134:137], v[186:189], v[102:105]
	v_mfma_f32_16x16x32_bf16 v[98:101], v[142:145], v[186:189], v[98:101]
	s_nop 7
	s_nop 7
	s_bitcmp1_b32 s98, 0
	s_cbranch_scc1 .Lq_epi
	s_bitcmp1_b32 s98, 1
	s_cbranch_scc0 .Lq_mv1
	v_mov_b32_e32 v34, v98
	v_mov_b32_e32 v35, v99
	v_mov_b32_e32 v36, v100
	v_mov_b32_e32 v37, v101
	v_mov_b32_e32 v38, v102
	v_mov_b32_e32 v39, v103
	v_mov_b32_e32 v40, v104
	v_mov_b32_e32 v41, v105
	v_mov_b32_e32 v42, v106
	v_mov_b32_e32 v43, v107
	v_mov_b32_e32 v44, v108
	v_mov_b32_e32 v45, v109
	v_mov_b32_e32 v46, v110
	v_mov_b32_e32 v47, v111
	v_mov_b32_e32 v48, v112
	v_mov_b32_e32 v49, v113
	v_mov_b32_e32 v50, v114
	v_mov_b32_e32 v51, v115
	v_mov_b32_e32 v52, v116
	v_mov_b32_e32 v53, v117
	v_mov_b32_e32 v54, v118
	v_mov_b32_e32 v55, v119
	v_mov_b32_e32 v56, v120
	v_mov_b32_e32 v57, v121
	v_mov_b32_e32 v58, v122
	v_mov_b32_e32 v59, v123
	v_mov_b32_e32 v60, v124
	v_mov_b32_e32 v61, v125
	v_mov_b32_e32 v62, v126
	v_mov_b32_e32 v63, v127
	v_mov_b32_e32 v64, v128
	v_mov_b32_e32 v65, v129
	v_mov_b32_e32 v98, 0
	v_mov_b32_e32 v99, 0
	v_mov_b32_e32 v100, 0
	v_mov_b32_e32 v101, 0
	v_mov_b32_e32 v102, 0
	v_mov_b32_e32 v103, 0
	v_mov_b32_e32 v104, 0
	v_mov_b32_e32 v105, 0
	v_mov_b32_e32 v106, 0
	v_mov_b32_e32 v107, 0
	v_mov_b32_e32 v108, 0
	v_mov_b32_e32 v109, 0
	v_mov_b32_e32 v110, 0
	v_mov_b32_e32 v111, 0
	v_mov_b32_e32 v112, 0
	v_mov_b32_e32 v113, 0
	v_mov_b32_e32 v114, 0
	v_mov_b32_e32 v115, 0
	v_mov_b32_e32 v116, 0
	v_mov_b32_e32 v117, 0
	v_mov_b32_e32 v118, 0
	v_mov_b32_e32 v119, 0
	v_mov_b32_e32 v120, 0
	v_mov_b32_e32 v121, 0
	v_mov_b32_e32 v122, 0
	v_mov_b32_e32 v123, 0
	v_mov_b32_e32 v124, 0
	v_mov_b32_e32 v125, 0
	v_mov_b32_e32 v126, 0
	v_mov_b32_e32 v127, 0
	v_mov_b32_e32 v128, 0
	v_mov_b32_e32 v129, 0
	s_branch .Lq_epi
